# back-edge rotation on the 16 GEMM K loops: counter/pointer bumps, exit test and back branch moved in front of the loop-back barrier, which becomes the loop head (exit path has its own barrier copy)
# baseline (speedup 1.0000x reference)
.LBB0_288:
	s_ashr_i32 s13, s12, 31
	s_lshl_b64 s[16:17], s[12:13], 19
	s_add_u32 s16, s36, s16
	s_addc_u32 s17, s37, s17
	s_and_b64 s[18:19], s[0:1], exec
	s_cselect_b32 s13, s17, s27
	s_cselect_b32 s50, s16, s26
	s_ashr_i32 s15, s14, 31
	s_lshl_b64 s[18:19], s[14:15], 19
	s_add_u32 s18, s30, s18
	s_addc_u32 s19, s31, s19
	s_and_b64 s[28:29], s[0:1], exec
	s_cselect_b32 s15, s19, s25
	s_cselect_b32 s51, s18, s24
	s_add_u32 s52, s24, 0x10000
	s_addc_u32 s53, s25, 0
	s_add_u32 s24, s26, 0x40080
	v_mov_b32_e32 v0, 0
	s_addc_u32 s25, s27, 0
	s_mov_b32 s54, -2
	v_mov_b32_e32 v1, v0
	v_mov_b32_e32 v2, v0
	v_mov_b32_e32 v3, v0
	v_mov_b32_e32 v8, v0
	v_mov_b32_e32 v9, v0
	v_mov_b32_e32 v10, v0
	v_mov_b32_e32 v11, v0
	v_mov_b32_e32 v16, v0
	v_mov_b32_e32 v17, v0
	v_mov_b32_e32 v18, v0
	v_mov_b32_e32 v19, v0
	v_mov_b32_e32 v24, v0
	v_mov_b32_e32 v25, v0
	v_mov_b32_e32 v26, v0
	v_mov_b32_e32 v27, v0
	v_mov_b32_e32 v32, v0
	v_mov_b32_e32 v33, v0
	v_mov_b32_e32 v34, v0
	v_mov_b32_e32 v35, v0
	v_mov_b32_e32 v40, v0
	v_mov_b32_e32 v41, v0
	v_mov_b32_e32 v42, v0
	v_mov_b32_e32 v43, v0
	v_mov_b32_e32 v48, v0
	v_mov_b32_e32 v49, v0
	v_mov_b32_e32 v50, v0
	v_mov_b32_e32 v51, v0
	v_mov_b32_e32 v56, v0
	v_mov_b32_e32 v57, v0
	v_mov_b32_e32 v58, v0
	v_mov_b32_e32 v59, v0
	v_mov_b32_e32 v4, v0
	v_mov_b32_e32 v5, v0
	v_mov_b32_e32 v6, v0
	v_mov_b32_e32 v7, v0
	v_mov_b32_e32 v12, v0
	v_mov_b32_e32 v13, v0
	v_mov_b32_e32 v14, v0
	v_mov_b32_e32 v15, v0
	v_mov_b32_e32 v20, v0
	v_mov_b32_e32 v21, v0
	v_mov_b32_e32 v22, v0
	v_mov_b32_e32 v23, v0
	v_mov_b32_e32 v28, v0
	v_mov_b32_e32 v29, v0
	v_mov_b32_e32 v30, v0
	v_mov_b32_e32 v31, v0
	v_mov_b32_e32 v36, v0
	v_mov_b32_e32 v37, v0
	v_mov_b32_e32 v38, v0
	v_mov_b32_e32 v39, v0
	v_mov_b32_e32 v44, v0
	v_mov_b32_e32 v45, v0
	v_mov_b32_e32 v46, v0
	v_mov_b32_e32 v47, v0
	v_mov_b32_e32 v52, v0
	v_mov_b32_e32 v53, v0
	v_mov_b32_e32 v54, v0
	v_mov_b32_e32 v55, v0
	v_mov_b32_e32 v60, v0
	v_mov_b32_e32 v61, v0
	v_mov_b32_e32 v62, v0
	v_mov_b32_e32 v63, v0
	v_mov_b32_e32 v64, v0
	v_mov_b32_e32 v65, v0
	v_mov_b32_e32 v66, v0
	v_mov_b32_e32 v67, v0
	v_mov_b32_e32 v72, v0
	v_mov_b32_e32 v73, v0
	v_mov_b32_e32 v74, v0
	v_mov_b32_e32 v75, v0
	v_mov_b32_e32 v80, v0
	v_mov_b32_e32 v81, v0
	v_mov_b32_e32 v82, v0
	v_mov_b32_e32 v83, v0
	v_mov_b32_e32 v88, v0
	v_mov_b32_e32 v89, v0
	v_mov_b32_e32 v90, v0
	v_mov_b32_e32 v91, v0
	v_mov_b32_e32 v96, v0
	v_mov_b32_e32 v97, v0
	v_mov_b32_e32 v98, v0
	v_mov_b32_e32 v99, v0
	v_mov_b32_e32 v104, v0
	v_mov_b32_e32 v105, v0
	v_mov_b32_e32 v106, v0
	v_mov_b32_e32 v107, v0
	v_mov_b32_e32 v112, v0
	v_mov_b32_e32 v113, v0
	v_mov_b32_e32 v114, v0
	v_mov_b32_e32 v115, v0
	v_mov_b32_e32 v120, v0
	v_mov_b32_e32 v121, v0
	v_mov_b32_e32 v122, v0
	v_mov_b32_e32 v123, v0
	v_mov_b32_e32 v68, v0
	v_mov_b32_e32 v69, v0
	v_mov_b32_e32 v70, v0
	v_mov_b32_e32 v71, v0
	v_mov_b32_e32 v76, v0
	v_mov_b32_e32 v77, v0
	v_mov_b32_e32 v78, v0
	v_mov_b32_e32 v79, v0
	v_mov_b32_e32 v84, v0
	v_mov_b32_e32 v85, v0
	v_mov_b32_e32 v86, v0
	v_mov_b32_e32 v87, v0
	v_mov_b32_e32 v92, v0
	v_mov_b32_e32 v93, v0
	v_mov_b32_e32 v94, v0
	v_mov_b32_e32 v95, v0
	v_mov_b32_e32 v100, v0
	v_mov_b32_e32 v101, v0
	v_mov_b32_e32 v102, v0
	v_mov_b32_e32 v103, v0
	v_mov_b32_e32 v108, v0
	v_mov_b32_e32 v109, v0
	v_mov_b32_e32 v110, v0
	v_mov_b32_e32 v111, v0
	v_mov_b32_e32 v116, v0
	v_mov_b32_e32 v117, v0
	v_mov_b32_e32 v118, v0
	v_mov_b32_e32 v119, v0
	v_mov_b32_e32 v124, v0
	v_mov_b32_e32 v125, v0
	v_mov_b32_e32 v126, v0
	v_mov_b32_e32 v127, v0
	s_branch .LBB0_289

.LBB0_289:
	ds_read_b128 v[170:173], v167
	ds_read_b128 v[174:177], v167 offset:1024
	ds_read_b128 v[178:181], v167 offset:2048
	ds_read_b128 v[182:185], v167 offset:3072
	ds_read_b128 v[186:189], v168
	ds_read_b128 v[190:193], v168 offset:1024
	ds_read_b128 v[194:197], v168 offset:2048
	ds_read_b128 v[198:201], v168 offset:3072
	s_add_u32 s26, s24, 0xfffc0080
	s_addc_u32 s27, s25, -1
	s_cmp_eq_u32 s54, 12
	s_cselect_b32 s29, s13, s27
	s_cselect_b32 s28, s50, s26
	s_cselect_b32 s27, s15, s53
	s_cselect_b32 s26, s51, s52
	v_lshl_add_u64 v[164:165], s[24:25], 0, v[158:159]
	s_add_i32 m0, s21, 0xc000
	ds_read_b128 v[210:213], v169
	ds_read_b128 v[214:217], v169 offset:1024
	ds_read_b128 v[218:221], v169 offset:2048
	ds_read_b128 v[222:225], v169 offset:3072
	ds_read_b128 v[226:229], v169 offset:4096
	ds_read_b128 v[230:233], v169 offset:5120
	ds_read_b128 v[234:237], v169 offset:6144
	ds_read_b128 v[238:241], v169 offset:7168
	global_load_lds_dwordx4 v[164:165], off
	v_lshl_add_u64 v[164:165], s[24:25], 0, v[156:157]
	s_add_i32 m0, s21, 0xe000
	s_nop 0
	global_load_lds_dwordx4 v[164:165], off
	s_waitcnt vmcnt(8)
	s_waitcnt lgkmcnt(0)
	s_barrier
	s_setprio 1
	s_waitcnt lgkmcnt(0)
	v_mfma_f32_16x16x32_bf16 v[124:127], v[170:173], v[210:213], v[124:127]
	v_mfma_f32_16x16x32_bf16 v[116:119], v[178:181], v[210:213], v[116:119]
	v_mfma_f32_16x16x32_bf16 v[108:111], v[170:173], v[218:221], v[108:111]
	v_mfma_f32_16x16x32_bf16 v[100:103], v[178:181], v[218:221], v[100:103]
	v_mfma_f32_16x16x32_bf16 v[92:95], v[170:173], v[226:229], v[92:95]
	v_mfma_f32_16x16x32_bf16 v[84:87], v[178:181], v[226:229], v[84:87]
	v_mfma_f32_16x16x32_bf16 v[76:79], v[170:173], v[234:237], v[76:79]
	v_mfma_f32_16x16x32_bf16 v[68:71], v[178:181], v[234:237], v[68:71]
	v_mfma_f32_16x16x32_bf16 v[124:127], v[174:177], v[214:217], v[124:127]
	v_mfma_f32_16x16x32_bf16 v[116:119], v[182:185], v[214:217], v[116:119]
	v_mfma_f32_16x16x32_bf16 v[108:111], v[174:177], v[222:225], v[108:111]
	v_mfma_f32_16x16x32_bf16 v[100:103], v[182:185], v[222:225], v[100:103]
	v_mfma_f32_16x16x32_bf16 v[92:95], v[174:177], v[230:233], v[92:95]
	v_mfma_f32_16x16x32_bf16 v[84:87], v[182:185], v[230:233], v[84:87]
	v_mfma_f32_16x16x32_bf16 v[76:79], v[174:177], v[238:241], v[76:79]
	v_mfma_f32_16x16x32_bf16 v[68:71], v[182:185], v[238:241], v[68:71]
	s_setprio 0
	s_setprio 1
	v_mfma_f32_16x16x32_bf16 v[120:123], v[186:189], v[210:213], v[120:123]
	v_mfma_f32_16x16x32_bf16 v[112:115], v[194:197], v[210:213], v[112:115]
	v_mfma_f32_16x16x32_bf16 v[104:107], v[186:189], v[218:221], v[104:107]
	v_mfma_f32_16x16x32_bf16 v[96:99], v[194:197], v[218:221], v[96:99]
	v_mfma_f32_16x16x32_bf16 v[88:91], v[186:189], v[226:229], v[88:91]
	v_mfma_f32_16x16x32_bf16 v[80:83], v[194:197], v[226:229], v[80:83]
	v_mfma_f32_16x16x32_bf16 v[72:75], v[186:189], v[234:237], v[72:75]
	v_mfma_f32_16x16x32_bf16 v[64:67], v[194:197], v[234:237], v[64:67]
	v_mfma_f32_16x16x32_bf16 v[120:123], v[190:193], v[214:217], v[120:123]
	v_mfma_f32_16x16x32_bf16 v[112:115], v[198:201], v[214:217], v[112:115]
	v_mfma_f32_16x16x32_bf16 v[104:107], v[190:193], v[222:225], v[104:107]
	v_mfma_f32_16x16x32_bf16 v[96:99], v[198:201], v[222:225], v[96:99]
	v_mfma_f32_16x16x32_bf16 v[88:91], v[190:193], v[230:233], v[88:91]
	v_mfma_f32_16x16x32_bf16 v[80:83], v[198:201], v[230:233], v[80:83]
	v_mfma_f32_16x16x32_bf16 v[72:75], v[190:193], v[238:241], v[72:75]
	v_mfma_f32_16x16x32_bf16 v[64:67], v[198:201], v[238:241], v[64:67]
	s_setprio 0
	s_barrier
	s_add_i32 s55, s48, s38
	v_lshl_add_u64 v[164:165], s[26:27], 0, v[134:135]
	s_mov_b32 m0, s55
	ds_read_b128 v[210:213], v169 offset:16384
	ds_read_b128 v[214:217], v169 offset:17408
	ds_read_b128 v[218:221], v169 offset:18432
	ds_read_b128 v[222:225], v169 offset:19456
	ds_read_b128 v[226:229], v169 offset:20480
	ds_read_b128 v[230:233], v169 offset:21504
	ds_read_b128 v[234:237], v169 offset:22528
	ds_read_b128 v[238:241], v169 offset:23552
	global_load_lds_dwordx4 v[164:165], off
	s_add_i32 m0, s55, 0x2000
	s_add_u32 s56, s26, 0x4000
	v_lshl_add_u64 v[164:165], s[26:27], 0, v[130:131]
	s_addc_u32 s57, s27, 0
	s_add_i32 s55, s49, s38
	global_load_lds_dwordx4 v[164:165], off
	v_lshl_add_u64 v[164:165], s[56:57], 0, v[134:135]
	s_mov_b32 m0, s55
	v_lshl_add_u64 v[242:243], s[28:29], 0, v[132:133]
	global_load_lds_dwordx4 v[164:165], off
	v_lshl_add_u64 v[164:165], s[56:57], 0, v[130:131]
	s_add_i32 m0, s55, 0x2000
	s_nop 0
	global_load_lds_dwordx4 v[164:165], off
	v_lshl_add_u64 v[164:165], s[28:29], 0, v[136:137]
	s_mov_b32 m0, s21
	s_nop 0
	global_load_lds_dwordx4 v[164:165], off
	s_mov_b32 m0, s23
	s_nop 0
	global_load_lds_dwordx4 v[242:243], off
	s_waitcnt vmcnt(8)
	s_waitcnt lgkmcnt(0)
	s_barrier
	s_setprio 1
	s_waitcnt lgkmcnt(0)
	v_mfma_f32_16x16x32_bf16 v[60:63], v[170:173], v[210:213], v[60:63]
	v_mfma_f32_16x16x32_bf16 v[52:55], v[178:181], v[210:213], v[52:55]
	v_mfma_f32_16x16x32_bf16 v[44:47], v[170:173], v[218:221], v[44:47]
	v_mfma_f32_16x16x32_bf16 v[36:39], v[178:181], v[218:221], v[36:39]
	v_mfma_f32_16x16x32_bf16 v[28:31], v[170:173], v[226:229], v[28:31]
	v_mfma_f32_16x16x32_bf16 v[20:23], v[178:181], v[226:229], v[20:23]
	v_mfma_f32_16x16x32_bf16 v[12:15], v[170:173], v[234:237], v[12:15]
	v_mfma_f32_16x16x32_bf16 v[4:7], v[178:181], v[234:237], v[4:7]
	v_mfma_f32_16x16x32_bf16 v[60:63], v[174:177], v[214:217], v[60:63]
	v_mfma_f32_16x16x32_bf16 v[52:55], v[182:185], v[214:217], v[52:55]
	v_mfma_f32_16x16x32_bf16 v[44:47], v[174:177], v[222:225], v[44:47]
	v_mfma_f32_16x16x32_bf16 v[36:39], v[182:185], v[222:225], v[36:39]
	v_mfma_f32_16x16x32_bf16 v[28:31], v[174:177], v[230:233], v[28:31]
	v_mfma_f32_16x16x32_bf16 v[20:23], v[182:185], v[230:233], v[20:23]
	v_mfma_f32_16x16x32_bf16 v[12:15], v[174:177], v[238:241], v[12:15]
	v_mfma_f32_16x16x32_bf16 v[4:7], v[182:185], v[238:241], v[4:7]
	s_setprio 0
	s_setprio 1
	v_mfma_f32_16x16x32_bf16 v[56:59], v[186:189], v[210:213], v[56:59]
	v_mfma_f32_16x16x32_bf16 v[48:51], v[194:197], v[210:213], v[48:51]
	v_mfma_f32_16x16x32_bf16 v[40:43], v[186:189], v[218:221], v[40:43]
	v_mfma_f32_16x16x32_bf16 v[32:35], v[194:197], v[218:221], v[32:35]
	v_mfma_f32_16x16x32_bf16 v[24:27], v[186:189], v[226:229], v[24:27]
	v_mfma_f32_16x16x32_bf16 v[16:19], v[194:197], v[226:229], v[16:19]
	v_mfma_f32_16x16x32_bf16 v[8:11], v[186:189], v[234:237], v[8:11]
	v_mfma_f32_16x16x32_bf16 v[0:3], v[194:197], v[234:237], v[0:3]
	v_mfma_f32_16x16x32_bf16 v[56:59], v[190:193], v[214:217], v[56:59]
	v_mfma_f32_16x16x32_bf16 v[48:51], v[198:201], v[214:217], v[48:51]
	v_mfma_f32_16x16x32_bf16 v[40:43], v[190:193], v[222:225], v[40:43]
	v_mfma_f32_16x16x32_bf16 v[32:35], v[198:201], v[222:225], v[32:35]
	v_mfma_f32_16x16x32_bf16 v[24:27], v[190:193], v[230:233], v[24:27]
	v_mfma_f32_16x16x32_bf16 v[16:19], v[198:201], v[230:233], v[16:19]
	v_mfma_f32_16x16x32_bf16 v[8:11], v[190:193], v[238:241], v[8:11]
	v_mfma_f32_16x16x32_bf16 v[0:3], v[198:201], v[238:241], v[0:3]
	s_setprio 0
	s_barrier
	s_add_i32 s55, 0, 0x18000
	s_add_i32 s56, 0, 0x1c000
	v_add_u32_e32 v182, s55, v129
	v_add_u32_e32 v198, s56, v129
	ds_read_b128 v[170:173], v182
	ds_read_b128 v[174:177], v182 offset:1024
	ds_read_b128 v[178:181], v182 offset:2048
	ds_read_b128 v[182:185], v182 offset:3072
	ds_read_b128 v[186:189], v198
	ds_read_b128 v[190:193], v198 offset:1024
	ds_read_b128 v[194:197], v198 offset:2048
	ds_read_b128 v[198:201], v198 offset:3072
	s_add_u32 s28, s28, 0x40000
	s_addc_u32 s29, s29, 0
	s_mov_b32 m0, s41
	v_lshl_add_u64 v[244:245], s[28:29], 0, v[136:137]
	ds_read_b128 v[210:213], v169 offset:32768
	ds_read_b128 v[214:217], v169 offset:33792
	ds_read_b128 v[218:221], v169 offset:34816
	ds_read_b128 v[222:225], v169 offset:35840
	ds_read_b128 v[226:229], v169 offset:36864
	ds_read_b128 v[230:233], v169 offset:37888
	ds_read_b128 v[234:237], v169 offset:38912
	ds_read_b128 v[238:241], v169 offset:39936
	global_load_lds_dwordx4 v[244:245], off
	v_lshl_add_u64 v[244:245], s[28:29], 0, v[132:133]
	s_mov_b32 m0, s42
	s_nop 0
	global_load_lds_dwordx4 v[244:245], off
	s_waitcnt vmcnt(8)
	s_waitcnt lgkmcnt(0)
	s_barrier
	s_setprio 1
	s_waitcnt lgkmcnt(0)
	v_mfma_f32_16x16x32_bf16 v[124:127], v[170:173], v[210:213], v[124:127]
	v_mfma_f32_16x16x32_bf16 v[116:119], v[178:181], v[210:213], v[116:119]
	v_mfma_f32_16x16x32_bf16 v[108:111], v[170:173], v[218:221], v[108:111]
	v_mfma_f32_16x16x32_bf16 v[100:103], v[178:181], v[218:221], v[100:103]
	v_mfma_f32_16x16x32_bf16 v[92:95], v[170:173], v[226:229], v[92:95]
	v_mfma_f32_16x16x32_bf16 v[84:87], v[178:181], v[226:229], v[84:87]
	v_mfma_f32_16x16x32_bf16 v[76:79], v[170:173], v[234:237], v[76:79]
	v_mfma_f32_16x16x32_bf16 v[68:71], v[178:181], v[234:237], v[68:71]
	v_mfma_f32_16x16x32_bf16 v[124:127], v[174:177], v[214:217], v[124:127]
	v_mfma_f32_16x16x32_bf16 v[116:119], v[182:185], v[214:217], v[116:119]
	v_mfma_f32_16x16x32_bf16 v[108:111], v[174:177], v[222:225], v[108:111]
	v_mfma_f32_16x16x32_bf16 v[100:103], v[182:185], v[222:225], v[100:103]
	v_mfma_f32_16x16x32_bf16 v[92:95], v[174:177], v[230:233], v[92:95]
	v_mfma_f32_16x16x32_bf16 v[84:87], v[182:185], v[230:233], v[84:87]
	v_mfma_f32_16x16x32_bf16 v[76:79], v[174:177], v[238:241], v[76:79]
	v_mfma_f32_16x16x32_bf16 v[68:71], v[182:185], v[238:241], v[68:71]
	s_setprio 0
	s_setprio 1
	v_mfma_f32_16x16x32_bf16 v[120:123], v[186:189], v[210:213], v[120:123]
	v_mfma_f32_16x16x32_bf16 v[112:115], v[194:197], v[210:213], v[112:115]
	v_mfma_f32_16x16x32_bf16 v[104:107], v[186:189], v[218:221], v[104:107]
	v_mfma_f32_16x16x32_bf16 v[96:99], v[194:197], v[218:221], v[96:99]
	v_mfma_f32_16x16x32_bf16 v[88:91], v[186:189], v[226:229], v[88:91]
	v_mfma_f32_16x16x32_bf16 v[80:83], v[194:197], v[226:229], v[80:83]
	v_mfma_f32_16x16x32_bf16 v[72:75], v[186:189], v[234:237], v[72:75]
	v_mfma_f32_16x16x32_bf16 v[64:67], v[194:197], v[234:237], v[64:67]
	v_mfma_f32_16x16x32_bf16 v[120:123], v[190:193], v[214:217], v[120:123]
	v_mfma_f32_16x16x32_bf16 v[112:115], v[198:201], v[214:217], v[112:115]
	v_mfma_f32_16x16x32_bf16 v[104:107], v[190:193], v[222:225], v[104:107]
	v_mfma_f32_16x16x32_bf16 v[96:99], v[198:201], v[222:225], v[96:99]
	v_mfma_f32_16x16x32_bf16 v[88:91], v[190:193], v[230:233], v[88:91]
	v_mfma_f32_16x16x32_bf16 v[80:83], v[198:201], v[230:233], v[80:83]
	v_mfma_f32_16x16x32_bf16 v[72:75], v[190:193], v[238:241], v[72:75]
	v_mfma_f32_16x16x32_bf16 v[64:67], v[198:201], v[238:241], v[64:67]
	s_setprio 0
	s_barrier
	s_add_u32 s28, s26, 0x8000
	s_addc_u32 s29, s27, 0
	s_add_i32 s55, s55, s38
	v_lshl_add_u64 v[244:245], s[28:29], 0, v[134:135]
	s_mov_b32 m0, s55
	ds_read_b128 v[210:213], v169 offset:49152
	ds_read_b128 v[214:217], v169 offset:50176
	ds_read_b128 v[218:221], v169 offset:51200
	ds_read_b128 v[222:225], v169 offset:52224
	ds_read_b128 v[226:229], v169 offset:53248
	ds_read_b128 v[230:233], v169 offset:54272
	ds_read_b128 v[234:237], v169 offset:55296
	ds_read_b128 v[238:241], v169 offset:56320
	global_load_lds_dwordx4 v[244:245], off
	s_add_i32 m0, s55, 0x2000
	s_add_u32 s26, s26, 0xc000
	v_lshl_add_u64 v[244:245], s[28:29], 0, v[130:131]
	s_addc_u32 s27, s27, 0
	s_add_i32 s28, s56, s38
	global_load_lds_dwordx4 v[244:245], off
	v_lshl_add_u64 v[244:245], s[26:27], 0, v[134:135]
	s_mov_b32 m0, s28
	v_lshl_add_u64 v[164:165], v[164:165], 0, s[8:9]
	global_load_lds_dwordx4 v[244:245], off
	v_lshl_add_u64 v[244:245], s[26:27], 0, v[130:131]
	s_add_i32 m0, s28, 0x2000
	s_nop 0
	global_load_lds_dwordx4 v[244:245], off
	s_mov_b32 m0, s45
	s_nop 0
	global_load_lds_dwordx4 v[164:165], off
	v_lshl_add_u64 v[164:165], v[242:243], 0, s[8:9]
	s_mov_b32 m0, s46
	s_nop 0
	global_load_lds_dwordx4 v[164:165], off
	s_waitcnt vmcnt(8)
	s_waitcnt lgkmcnt(0)
	s_barrier
	s_setprio 1
	s_waitcnt lgkmcnt(0)
	v_mfma_f32_16x16x32_bf16 v[60:63], v[170:173], v[210:213], v[60:63]
	v_mfma_f32_16x16x32_bf16 v[52:55], v[178:181], v[210:213], v[52:55]
	v_mfma_f32_16x16x32_bf16 v[44:47], v[170:173], v[218:221], v[44:47]
	v_mfma_f32_16x16x32_bf16 v[36:39], v[178:181], v[218:221], v[36:39]
	v_mfma_f32_16x16x32_bf16 v[28:31], v[170:173], v[226:229], v[28:31]
	v_mfma_f32_16x16x32_bf16 v[20:23], v[178:181], v[226:229], v[20:23]
	v_mfma_f32_16x16x32_bf16 v[12:15], v[170:173], v[234:237], v[12:15]
	v_mfma_f32_16x16x32_bf16 v[4:7], v[178:181], v[234:237], v[4:7]
	v_mfma_f32_16x16x32_bf16 v[60:63], v[174:177], v[214:217], v[60:63]
	v_mfma_f32_16x16x32_bf16 v[52:55], v[182:185], v[214:217], v[52:55]
	v_mfma_f32_16x16x32_bf16 v[44:47], v[174:177], v[222:225], v[44:47]
	v_mfma_f32_16x16x32_bf16 v[36:39], v[182:185], v[222:225], v[36:39]
	v_mfma_f32_16x16x32_bf16 v[28:31], v[174:177], v[230:233], v[28:31]
	v_mfma_f32_16x16x32_bf16 v[20:23], v[182:185], v[230:233], v[20:23]
	v_mfma_f32_16x16x32_bf16 v[12:15], v[174:177], v[238:241], v[12:15]
	v_mfma_f32_16x16x32_bf16 v[4:7], v[182:185], v[238:241], v[4:7]
	s_setprio 0
	s_setprio 1
	v_mfma_f32_16x16x32_bf16 v[56:59], v[186:189], v[210:213], v[56:59]
	v_mfma_f32_16x16x32_bf16 v[48:51], v[194:197], v[210:213], v[48:51]
	v_mfma_f32_16x16x32_bf16 v[40:43], v[186:189], v[218:221], v[40:43]
	v_mfma_f32_16x16x32_bf16 v[32:35], v[194:197], v[218:221], v[32:35]
	v_mfma_f32_16x16x32_bf16 v[24:27], v[186:189], v[226:229], v[24:27]
	v_mfma_f32_16x16x32_bf16 v[16:19], v[194:197], v[226:229], v[16:19]
	v_mfma_f32_16x16x32_bf16 v[8:11], v[186:189], v[234:237], v[8:11]
	v_mfma_f32_16x16x32_bf16 v[0:3], v[194:197], v[234:237], v[0:3]
	v_mfma_f32_16x16x32_bf16 v[56:59], v[190:193], v[214:217], v[56:59]
	v_mfma_f32_16x16x32_bf16 v[48:51], v[198:201], v[214:217], v[48:51]
	v_mfma_f32_16x16x32_bf16 v[40:43], v[190:193], v[222:225], v[40:43]
	v_mfma_f32_16x16x32_bf16 v[32:35], v[198:201], v[222:225], v[32:35]
	v_mfma_f32_16x16x32_bf16 v[24:27], v[190:193], v[230:233], v[24:27]
	v_mfma_f32_16x16x32_bf16 v[16:19], v[198:201], v[230:233], v[16:19]
	v_mfma_f32_16x16x32_bf16 v[8:11], v[190:193], v[238:241], v[8:11]
	v_mfma_f32_16x16x32_bf16 v[0:3], v[198:201], v[238:241], v[0:3]
	s_setprio 0
	s_add_i32 s54, s54, 2
	s_add_u32 s52, s52, 0x10000
	s_addc_u32 s53, s53, 0
	s_add_u32 s24, s24, 0x100
	s_addc_u32 s25, s25, 0
	s_cmp_gt_u32 s54, 13
	s_cbranch_scc0 .Lrot0
	s_barrier
	s_and_b64 vcc, exec, s[10:11]
	s_cbranch_vccz .LBB0_292
	s_barrier

.LBB0_407:
	s_add_u32 s47, s38, 0x10000
	s_addc_u32 s48, s39, 0
	s_add_u32 s38, s40, 0xc000
	v_mov_b32_e32 v0, 0
	s_addc_u32 s39, s41, 0
	s_mov_b32 s49, -2
	v_mov_b32_e32 v1, v0
	v_mov_b32_e32 v2, v0
	v_mov_b32_e32 v3, v0
	v_mov_b32_e32 v4, v0
	v_mov_b32_e32 v5, v0
	v_mov_b32_e32 v6, v0
	v_mov_b32_e32 v7, v0
	v_mov_b32_e32 v8, v0
	v_mov_b32_e32 v9, v0
	v_mov_b32_e32 v10, v0
	v_mov_b32_e32 v11, v0
	v_mov_b32_e32 v16, v0
	v_mov_b32_e32 v17, v0
	v_mov_b32_e32 v18, v0
	v_mov_b32_e32 v19, v0
	v_mov_b32_e32 v28, v0
	v_mov_b32_e32 v29, v0
	v_mov_b32_e32 v30, v0
	v_mov_b32_e32 v31, v0
	v_mov_b32_e32 v36, v0
	v_mov_b32_e32 v37, v0
	v_mov_b32_e32 v38, v0
	v_mov_b32_e32 v39, v0
	v_mov_b32_e32 v40, v0
	v_mov_b32_e32 v41, v0
	v_mov_b32_e32 v42, v0
	v_mov_b32_e32 v43, v0
	v_mov_b32_e32 v48, v0
	v_mov_b32_e32 v49, v0
	v_mov_b32_e32 v50, v0
	v_mov_b32_e32 v51, v0
	v_mov_b32_e32 v12, v0
	v_mov_b32_e32 v13, v0
	v_mov_b32_e32 v14, v0
	v_mov_b32_e32 v15, v0
	v_mov_b32_e32 v20, v0
	v_mov_b32_e32 v21, v0
	v_mov_b32_e32 v22, v0
	v_mov_b32_e32 v23, v0
	v_mov_b32_e32 v24, v0
	v_mov_b32_e32 v25, v0
	v_mov_b32_e32 v26, v0
	v_mov_b32_e32 v27, v0
	v_mov_b32_e32 v32, v0
	v_mov_b32_e32 v33, v0
	v_mov_b32_e32 v34, v0
	v_mov_b32_e32 v35, v0
	v_mov_b32_e32 v44, v0
	v_mov_b32_e32 v45, v0
	v_mov_b32_e32 v46, v0
	v_mov_b32_e32 v47, v0
	v_mov_b32_e32 v52, v0
	v_mov_b32_e32 v53, v0
	v_mov_b32_e32 v54, v0
	v_mov_b32_e32 v55, v0
	v_mov_b32_e32 v56, v0
	v_mov_b32_e32 v57, v0
	v_mov_b32_e32 v58, v0
	v_mov_b32_e32 v59, v0
	v_mov_b32_e32 v60, v0
	v_mov_b32_e32 v61, v0
	v_mov_b32_e32 v62, v0
	v_mov_b32_e32 v63, v0
	v_mov_b32_e32 v64, v0
	v_mov_b32_e32 v65, v0
	v_mov_b32_e32 v66, v0
	v_mov_b32_e32 v67, v0
	v_mov_b32_e32 v68, v0
	v_mov_b32_e32 v69, v0
	v_mov_b32_e32 v70, v0
	v_mov_b32_e32 v71, v0
	v_mov_b32_e32 v72, v0
	v_mov_b32_e32 v73, v0
	v_mov_b32_e32 v74, v0
	v_mov_b32_e32 v75, v0
	v_mov_b32_e32 v80, v0
	v_mov_b32_e32 v81, v0
	v_mov_b32_e32 v82, v0
	v_mov_b32_e32 v83, v0
	v_mov_b32_e32 v96, v0
	v_mov_b32_e32 v97, v0
	v_mov_b32_e32 v98, v0
	v_mov_b32_e32 v99, v0
	v_mov_b32_e32 v100, v0
	v_mov_b32_e32 v101, v0
	v_mov_b32_e32 v102, v0
	v_mov_b32_e32 v103, v0
	v_mov_b32_e32 v104, v0
	v_mov_b32_e32 v105, v0
	v_mov_b32_e32 v106, v0
	v_mov_b32_e32 v107, v0
	v_mov_b32_e32 v112, v0
	v_mov_b32_e32 v113, v0
	v_mov_b32_e32 v114, v0
	v_mov_b32_e32 v115, v0
	v_mov_b32_e32 v76, v0
	v_mov_b32_e32 v77, v0
	v_mov_b32_e32 v78, v0
	v_mov_b32_e32 v79, v0
	v_mov_b32_e32 v84, v0
	v_mov_b32_e32 v85, v0
	v_mov_b32_e32 v86, v0
	v_mov_b32_e32 v87, v0
	v_mov_b32_e32 v88, v0
	v_mov_b32_e32 v89, v0
	v_mov_b32_e32 v90, v0
	v_mov_b32_e32 v91, v0
	v_mov_b32_e32 v92, v0
	v_mov_b32_e32 v93, v0
	v_mov_b32_e32 v94, v0
	v_mov_b32_e32 v95, v0
	v_mov_b32_e32 v108, v0
	v_mov_b32_e32 v109, v0
	v_mov_b32_e32 v110, v0
	v_mov_b32_e32 v111, v0
	v_mov_b32_e32 v116, v0
	v_mov_b32_e32 v117, v0
	v_mov_b32_e32 v118, v0
	v_mov_b32_e32 v119, v0
	v_mov_b32_e32 v120, v0
	v_mov_b32_e32 v121, v0
	v_mov_b32_e32 v122, v0
	v_mov_b32_e32 v123, v0
	v_mov_b32_e32 v124, v0
	v_mov_b32_e32 v125, v0
	v_mov_b32_e32 v126, v0
	v_mov_b32_e32 v127, v0
	s_branch .LBB0_408

.LBB0_408:
	v_add_u32_e32 v168, s71, v182
	v_add_u32_e32 v204, s72, v182
	ds_read_b128 v[156:159], v168
	ds_read_b128 v[160:163], v168 offset:1024
	ds_read_b128 v[164:167], v168 offset:2048
	ds_read_b128 v[168:171], v168 offset:3072
	ds_read_b128 v[172:175], v204
	ds_read_b128 v[176:179], v204 offset:1024
	ds_read_b128 v[212:215], v204 offset:2048
	ds_read_b128 v[216:219], v204 offset:3072
	s_add_u32 s40, s38, 0x4000
	s_addc_u32 s41, s39, 0
	s_cmp_eq_u32 s49, 40
	s_cselect_b32 s44, s0, s40
	s_cselect_b32 s45, s1, s41
	s_cselect_b32 s42, s36, s47
	s_cselect_b32 s43, s37, s48
	s_add_u32 s40, s44, 0x8000
	s_addc_u32 s41, s45, 0
	v_lshl_add_u64 v[252:253], s[38:39], 0, v[150:151]
	s_add_i32 m0, s58, 0xc000
	ds_read_b128 v[220:223], v199
	ds_read_b128 v[224:227], v199 offset:1024
	ds_read_b128 v[228:231], v199 offset:2048
	ds_read_b128 v[232:235], v199 offset:3072
	ds_read_b128 v[236:239], v199 offset:4096
	ds_read_b128 v[240:243], v199 offset:5120
	ds_read_b128 v[244:247], v199 offset:6144
	ds_read_b128 v[248:251], v199 offset:7168
	global_load_lds_dwordx4 v[252:253], off
	v_lshl_add_u64 v[252:253], s[38:39], 0, v[148:149]
	s_add_i32 m0, s58, 0xe000
	s_nop 0
	global_load_lds_dwordx4 v[252:253], off
	s_waitcnt vmcnt(8)
	s_waitcnt lgkmcnt(0)
	s_barrier
	s_setprio 1
	s_waitcnt lgkmcnt(0)
	v_mfma_f32_16x16x32_bf16 v[124:127], v[156:159], v[220:223], v[124:127]
	v_mfma_f32_16x16x32_bf16 v[120:123], v[164:167], v[220:223], v[120:123]
	v_mfma_f32_16x16x32_bf16 v[116:119], v[156:159], v[228:231], v[116:119]
	v_mfma_f32_16x16x32_bf16 v[108:111], v[164:167], v[228:231], v[108:111]
	v_mfma_f32_16x16x32_bf16 v[92:95], v[156:159], v[236:239], v[92:95]
	v_mfma_f32_16x16x32_bf16 v[88:91], v[164:167], v[236:239], v[88:91]
	v_mfma_f32_16x16x32_bf16 v[84:87], v[156:159], v[244:247], v[84:87]
	v_mfma_f32_16x16x32_bf16 v[76:79], v[164:167], v[244:247], v[76:79]
	v_mfma_f32_16x16x32_bf16 v[124:127], v[160:163], v[224:227], v[124:127]
	v_mfma_f32_16x16x32_bf16 v[120:123], v[168:171], v[224:227], v[120:123]
	v_mfma_f32_16x16x32_bf16 v[116:119], v[160:163], v[232:235], v[116:119]
	v_mfma_f32_16x16x32_bf16 v[108:111], v[168:171], v[232:235], v[108:111]
	v_mfma_f32_16x16x32_bf16 v[92:95], v[160:163], v[240:243], v[92:95]
	v_mfma_f32_16x16x32_bf16 v[88:91], v[168:171], v[240:243], v[88:91]
	v_mfma_f32_16x16x32_bf16 v[84:87], v[160:163], v[248:251], v[84:87]
	v_mfma_f32_16x16x32_bf16 v[76:79], v[168:171], v[248:251], v[76:79]
	s_setprio 0
	s_setprio 1
	v_mfma_f32_16x16x32_bf16 v[112:115], v[172:175], v[220:223], v[112:115]
	v_mfma_f32_16x16x32_bf16 v[104:107], v[212:215], v[220:223], v[104:107]
	v_mfma_f32_16x16x32_bf16 v[100:103], v[172:175], v[228:231], v[100:103]
	v_mfma_f32_16x16x32_bf16 v[96:99], v[212:215], v[228:231], v[96:99]
	v_mfma_f32_16x16x32_bf16 v[80:83], v[172:175], v[236:239], v[80:83]
	v_mfma_f32_16x16x32_bf16 v[72:75], v[212:215], v[236:239], v[72:75]
	v_mfma_f32_16x16x32_bf16 v[68:71], v[172:175], v[244:247], v[68:71]
	v_mfma_f32_16x16x32_bf16 v[64:67], v[212:215], v[244:247], v[64:67]
	v_mfma_f32_16x16x32_bf16 v[112:115], v[176:179], v[224:227], v[112:115]
	v_mfma_f32_16x16x32_bf16 v[104:107], v[216:219], v[224:227], v[104:107]
	v_mfma_f32_16x16x32_bf16 v[100:103], v[176:179], v[232:235], v[100:103]
	v_mfma_f32_16x16x32_bf16 v[96:99], v[216:219], v[232:235], v[96:99]
	v_mfma_f32_16x16x32_bf16 v[80:83], v[176:179], v[240:243], v[80:83]
	v_mfma_f32_16x16x32_bf16 v[72:75], v[216:219], v[240:243], v[72:75]
	v_mfma_f32_16x16x32_bf16 v[68:71], v[176:179], v[248:251], v[68:71]
	v_mfma_f32_16x16x32_bf16 v[64:67], v[216:219], v[248:251], v[64:67]
	s_setprio 0
	s_barrier
	s_add_i32 s50, s71, s57
	v_lshl_add_u64 v[252:253], s[42:43], 0, v[128:129]
	s_mov_b32 m0, s50
	ds_read_b128 v[220:223], v199 offset:16384
	ds_read_b128 v[224:227], v199 offset:17408
	ds_read_b128 v[228:231], v199 offset:18432
	ds_read_b128 v[232:235], v199 offset:19456
	ds_read_b128 v[236:239], v199 offset:20480
	ds_read_b128 v[240:243], v199 offset:21504
	ds_read_b128 v[244:247], v199 offset:22528
	ds_read_b128 v[248:251], v199 offset:23552
	global_load_lds_dwordx4 v[252:253], off
	s_add_i32 m0, s50, 0x2000
	s_add_u32 s50, s42, 0x4000
	v_lshl_add_u64 v[252:253], s[42:43], 0, v[130:131]
	s_addc_u32 s51, s43, 0
	s_add_i32 s52, s72, s57
	global_load_lds_dwordx4 v[252:253], off
	v_lshl_add_u64 v[252:253], s[50:51], 0, v[128:129]
	s_mov_b32 m0, s52
	s_nop 0
	global_load_lds_dwordx4 v[252:253], off
	v_lshl_add_u64 v[252:253], s[50:51], 0, v[130:131]
	s_add_i32 m0, s52, 0x2000
	s_nop 0
	global_load_lds_dwordx4 v[252:253], off
	v_lshl_add_u64 v[252:253], s[44:45], 0, v[128:129]
	s_mov_b32 m0, s58
	s_nop 0
	global_load_lds_dwordx4 v[252:253], off
	v_lshl_add_u64 v[252:253], s[44:45], 0, v[130:131]
	s_mov_b32 m0, s59
	s_nop 0
	global_load_lds_dwordx4 v[252:253], off
	s_waitcnt vmcnt(8)
	s_waitcnt lgkmcnt(0)
	s_barrier
	s_setprio 1
	s_waitcnt lgkmcnt(0)
	v_mfma_f32_16x16x32_bf16 v[60:63], v[156:159], v[220:223], v[60:63]
	v_mfma_f32_16x16x32_bf16 v[56:59], v[164:167], v[220:223], v[56:59]
	v_mfma_f32_16x16x32_bf16 v[52:55], v[156:159], v[228:231], v[52:55]
	v_mfma_f32_16x16x32_bf16 v[44:47], v[164:167], v[228:231], v[44:47]
	v_mfma_f32_16x16x32_bf16 v[32:35], v[156:159], v[236:239], v[32:35]
	v_mfma_f32_16x16x32_bf16 v[24:27], v[164:167], v[236:239], v[24:27]
	v_mfma_f32_16x16x32_bf16 v[20:23], v[156:159], v[244:247], v[20:23]
	v_mfma_f32_16x16x32_bf16 v[12:15], v[164:167], v[244:247], v[12:15]
	v_mfma_f32_16x16x32_bf16 v[60:63], v[160:163], v[224:227], v[60:63]
	v_mfma_f32_16x16x32_bf16 v[56:59], v[168:171], v[224:227], v[56:59]
	v_mfma_f32_16x16x32_bf16 v[52:55], v[160:163], v[232:235], v[52:55]
	v_mfma_f32_16x16x32_bf16 v[44:47], v[168:171], v[232:235], v[44:47]
	v_mfma_f32_16x16x32_bf16 v[32:35], v[160:163], v[240:243], v[32:35]
	v_mfma_f32_16x16x32_bf16 v[24:27], v[168:171], v[240:243], v[24:27]
	v_mfma_f32_16x16x32_bf16 v[20:23], v[160:163], v[248:251], v[20:23]
	v_mfma_f32_16x16x32_bf16 v[12:15], v[168:171], v[248:251], v[12:15]
	s_setprio 0
	s_setprio 1
	v_mfma_f32_16x16x32_bf16 v[48:51], v[172:175], v[220:223], v[48:51]
	v_mfma_f32_16x16x32_bf16 v[40:43], v[212:215], v[220:223], v[40:43]
	v_mfma_f32_16x16x32_bf16 v[36:39], v[172:175], v[228:231], v[36:39]
	v_mfma_f32_16x16x32_bf16 v[28:31], v[212:215], v[228:231], v[28:31]
	v_mfma_f32_16x16x32_bf16 v[16:19], v[172:175], v[236:239], v[16:19]
	v_mfma_f32_16x16x32_bf16 v[8:11], v[212:215], v[236:239], v[8:11]
	v_mfma_f32_16x16x32_bf16 v[4:7], v[172:175], v[244:247], v[4:7]
	v_mfma_f32_16x16x32_bf16 v[0:3], v[212:215], v[244:247], v[0:3]
	v_mfma_f32_16x16x32_bf16 v[48:51], v[176:179], v[224:227], v[48:51]
	v_mfma_f32_16x16x32_bf16 v[40:43], v[216:219], v[224:227], v[40:43]
	v_mfma_f32_16x16x32_bf16 v[36:39], v[176:179], v[232:235], v[36:39]
	v_mfma_f32_16x16x32_bf16 v[28:31], v[216:219], v[232:235], v[28:31]
	v_mfma_f32_16x16x32_bf16 v[16:19], v[176:179], v[240:243], v[16:19]
	v_mfma_f32_16x16x32_bf16 v[8:11], v[216:219], v[240:243], v[8:11]
	v_mfma_f32_16x16x32_bf16 v[4:7], v[176:179], v[248:251], v[4:7]
	v_mfma_f32_16x16x32_bf16 v[0:3], v[216:219], v[248:251], v[0:3]
	s_setprio 0
	s_barrier
	s_add_i32 s50, 0, 0x18000
	s_add_i32 s51, 0, 0x1c000
	v_add_u32_e32 v168, s50, v182
	v_add_u32_e32 v204, s51, v182
	ds_read_b128 v[156:159], v168
	ds_read_b128 v[160:163], v168 offset:1024
	ds_read_b128 v[164:167], v168 offset:2048
	ds_read_b128 v[168:171], v168 offset:3072
	ds_read_b128 v[172:175], v204
	ds_read_b128 v[176:179], v204 offset:1024
	ds_read_b128 v[212:215], v204 offset:2048
	ds_read_b128 v[216:219], v204 offset:3072
	s_add_u32 s44, s44, 0x4000
	s_addc_u32 s45, s45, 0
	s_mov_b32 m0, s60
	v_lshl_add_u64 v[252:253], s[44:45], 0, v[128:129]
	ds_read_b128 v[220:223], v199 offset:32768
	ds_read_b128 v[224:227], v199 offset:33792
	ds_read_b128 v[228:231], v199 offset:34816
	ds_read_b128 v[232:235], v199 offset:35840
	ds_read_b128 v[236:239], v199 offset:36864
	ds_read_b128 v[240:243], v199 offset:37888
	ds_read_b128 v[244:247], v199 offset:38912
	ds_read_b128 v[248:251], v199 offset:39936
	global_load_lds_dwordx4 v[252:253], off
	v_lshl_add_u64 v[252:253], s[44:45], 0, v[130:131]
	s_mov_b32 m0, s61
	s_nop 0
	global_load_lds_dwordx4 v[252:253], off
	s_waitcnt vmcnt(8)
	s_waitcnt lgkmcnt(0)
	s_barrier
	s_setprio 1
	s_waitcnt lgkmcnt(0)
	v_mfma_f32_16x16x32_bf16 v[124:127], v[156:159], v[220:223], v[124:127]
	v_mfma_f32_16x16x32_bf16 v[120:123], v[164:167], v[220:223], v[120:123]
	v_mfma_f32_16x16x32_bf16 v[116:119], v[156:159], v[228:231], v[116:119]
	v_mfma_f32_16x16x32_bf16 v[108:111], v[164:167], v[228:231], v[108:111]
	v_mfma_f32_16x16x32_bf16 v[92:95], v[156:159], v[236:239], v[92:95]
	v_mfma_f32_16x16x32_bf16 v[88:91], v[164:167], v[236:239], v[88:91]
	v_mfma_f32_16x16x32_bf16 v[84:87], v[156:159], v[244:247], v[84:87]
	v_mfma_f32_16x16x32_bf16 v[76:79], v[164:167], v[244:247], v[76:79]
	v_mfma_f32_16x16x32_bf16 v[124:127], v[160:163], v[224:227], v[124:127]
	v_mfma_f32_16x16x32_bf16 v[120:123], v[168:171], v[224:227], v[120:123]
	v_mfma_f32_16x16x32_bf16 v[116:119], v[160:163], v[232:235], v[116:119]
	v_mfma_f32_16x16x32_bf16 v[108:111], v[168:171], v[232:235], v[108:111]
	v_mfma_f32_16x16x32_bf16 v[92:95], v[160:163], v[240:243], v[92:95]
	v_mfma_f32_16x16x32_bf16 v[88:91], v[168:171], v[240:243], v[88:91]
	v_mfma_f32_16x16x32_bf16 v[84:87], v[160:163], v[248:251], v[84:87]
	v_mfma_f32_16x16x32_bf16 v[76:79], v[168:171], v[248:251], v[76:79]
	s_setprio 0
	s_setprio 1
	v_mfma_f32_16x16x32_bf16 v[112:115], v[172:175], v[220:223], v[112:115]
	v_mfma_f32_16x16x32_bf16 v[104:107], v[212:215], v[220:223], v[104:107]
	v_mfma_f32_16x16x32_bf16 v[100:103], v[172:175], v[228:231], v[100:103]
	v_mfma_f32_16x16x32_bf16 v[96:99], v[212:215], v[228:231], v[96:99]
	v_mfma_f32_16x16x32_bf16 v[80:83], v[172:175], v[236:239], v[80:83]
	v_mfma_f32_16x16x32_bf16 v[72:75], v[212:215], v[236:239], v[72:75]
	v_mfma_f32_16x16x32_bf16 v[68:71], v[172:175], v[244:247], v[68:71]
	v_mfma_f32_16x16x32_bf16 v[64:67], v[212:215], v[244:247], v[64:67]
	v_mfma_f32_16x16x32_bf16 v[112:115], v[176:179], v[224:227], v[112:115]
	v_mfma_f32_16x16x32_bf16 v[104:107], v[216:219], v[224:227], v[104:107]
	v_mfma_f32_16x16x32_bf16 v[100:103], v[176:179], v[232:235], v[100:103]
	v_mfma_f32_16x16x32_bf16 v[96:99], v[216:219], v[232:235], v[96:99]
	v_mfma_f32_16x16x32_bf16 v[80:83], v[176:179], v[240:243], v[80:83]
	v_mfma_f32_16x16x32_bf16 v[72:75], v[216:219], v[240:243], v[72:75]
	v_mfma_f32_16x16x32_bf16 v[68:71], v[176:179], v[248:251], v[68:71]
	v_mfma_f32_16x16x32_bf16 v[64:67], v[216:219], v[248:251], v[64:67]
	s_setprio 0
	s_barrier
	s_add_u32 s44, s42, 0x8000
	s_addc_u32 s45, s43, 0
	s_add_i32 s50, s50, s57
	v_lshl_add_u64 v[252:253], s[44:45], 0, v[128:129]
	s_mov_b32 m0, s50
	ds_read_b128 v[220:223], v199 offset:49152
	ds_read_b128 v[224:227], v199 offset:50176
	ds_read_b128 v[228:231], v199 offset:51200
	ds_read_b128 v[232:235], v199 offset:52224
	ds_read_b128 v[236:239], v199 offset:53248
	ds_read_b128 v[240:243], v199 offset:54272
	ds_read_b128 v[244:247], v199 offset:55296
	ds_read_b128 v[248:251], v199 offset:56320
	global_load_lds_dwordx4 v[252:253], off
	s_add_i32 m0, s50, 0x2000
	s_add_u32 s42, s42, 0xc000
	v_lshl_add_u64 v[252:253], s[44:45], 0, v[130:131]
	s_addc_u32 s43, s43, 0
	s_add_i32 s44, s51, s57
	global_load_lds_dwordx4 v[252:253], off
	v_lshl_add_u64 v[252:253], s[42:43], 0, v[128:129]
	s_mov_b32 m0, s44
	s_nop 0
	global_load_lds_dwordx4 v[252:253], off
	v_lshl_add_u64 v[252:253], s[42:43], 0, v[130:131]
	s_add_i32 m0, s44, 0x2000
	s_nop 0
	global_load_lds_dwordx4 v[252:253], off
	v_lshl_add_u64 v[252:253], s[40:41], 0, v[128:129]
	s_mov_b32 m0, s67
	s_nop 0
	global_load_lds_dwordx4 v[252:253], off
	v_lshl_add_u64 v[252:253], s[40:41], 0, v[130:131]
	s_mov_b32 m0, s68
	s_nop 0
	global_load_lds_dwordx4 v[252:253], off
	s_waitcnt vmcnt(8)
	s_waitcnt lgkmcnt(0)
	s_barrier
	s_setprio 1
	s_waitcnt lgkmcnt(0)
	v_mfma_f32_16x16x32_bf16 v[60:63], v[156:159], v[220:223], v[60:63]
	v_mfma_f32_16x16x32_bf16 v[56:59], v[164:167], v[220:223], v[56:59]
	v_mfma_f32_16x16x32_bf16 v[52:55], v[156:159], v[228:231], v[52:55]
	v_mfma_f32_16x16x32_bf16 v[44:47], v[164:167], v[228:231], v[44:47]
	v_mfma_f32_16x16x32_bf16 v[32:35], v[156:159], v[236:239], v[32:35]
	v_mfma_f32_16x16x32_bf16 v[24:27], v[164:167], v[236:239], v[24:27]
	v_mfma_f32_16x16x32_bf16 v[20:23], v[156:159], v[244:247], v[20:23]
	v_mfma_f32_16x16x32_bf16 v[12:15], v[164:167], v[244:247], v[12:15]
	v_mfma_f32_16x16x32_bf16 v[60:63], v[160:163], v[224:227], v[60:63]
	v_mfma_f32_16x16x32_bf16 v[56:59], v[168:171], v[224:227], v[56:59]
	v_mfma_f32_16x16x32_bf16 v[52:55], v[160:163], v[232:235], v[52:55]
	v_mfma_f32_16x16x32_bf16 v[44:47], v[168:171], v[232:235], v[44:47]
	v_mfma_f32_16x16x32_bf16 v[32:35], v[160:163], v[240:243], v[32:35]
	v_mfma_f32_16x16x32_bf16 v[24:27], v[168:171], v[240:243], v[24:27]
	v_mfma_f32_16x16x32_bf16 v[20:23], v[160:163], v[248:251], v[20:23]
	v_mfma_f32_16x16x32_bf16 v[12:15], v[168:171], v[248:251], v[12:15]
	s_setprio 0
	s_setprio 1
	v_mfma_f32_16x16x32_bf16 v[48:51], v[172:175], v[220:223], v[48:51]
	v_mfma_f32_16x16x32_bf16 v[40:43], v[212:215], v[220:223], v[40:43]
	v_mfma_f32_16x16x32_bf16 v[36:39], v[172:175], v[228:231], v[36:39]
	v_mfma_f32_16x16x32_bf16 v[28:31], v[212:215], v[228:231], v[28:31]
	v_mfma_f32_16x16x32_bf16 v[16:19], v[172:175], v[236:239], v[16:19]
	v_mfma_f32_16x16x32_bf16 v[8:11], v[212:215], v[236:239], v[8:11]
	v_mfma_f32_16x16x32_bf16 v[4:7], v[172:175], v[244:247], v[4:7]
	v_mfma_f32_16x16x32_bf16 v[0:3], v[212:215], v[244:247], v[0:3]
	v_mfma_f32_16x16x32_bf16 v[48:51], v[176:179], v[224:227], v[48:51]
	v_mfma_f32_16x16x32_bf16 v[40:43], v[216:219], v[224:227], v[40:43]
	v_mfma_f32_16x16x32_bf16 v[36:39], v[176:179], v[232:235], v[36:39]
	v_mfma_f32_16x16x32_bf16 v[28:31], v[216:219], v[232:235], v[28:31]
	v_mfma_f32_16x16x32_bf16 v[16:19], v[176:179], v[240:243], v[16:19]
	v_mfma_f32_16x16x32_bf16 v[8:11], v[216:219], v[240:243], v[8:11]
	v_mfma_f32_16x16x32_bf16 v[4:7], v[176:179], v[248:251], v[4:7]
	v_mfma_f32_16x16x32_bf16 v[0:3], v[216:219], v[248:251], v[0:3]
	s_setprio 0
	s_add_i32 s49, s49, 2
	s_add_u32 s47, s47, 0x10000
	s_addc_u32 s48, s48, 0
	s_add_u32 s38, s38, 0x10000
	s_addc_u32 s39, s39, 0
	s_cmp_gt_u32 s49, 41
	s_cbranch_scc0 .Lrot1
	s_barrier
	s_and_b64 vcc, exec, s[14:15]
	s_cbranch_vccz .LBB0_411
	s_barrier

.LBB0_491:
	s_ashr_i32 s23, s22, 31
	s_lshl_b64 s[26:27], s[22:23], 19
	s_add_u32 s26, s42, s26
	s_addc_u32 s27, s43, s27
	s_and_b64 s[28:29], s[4:5], exec
	s_cselect_b32 s1, s27, s35
	s_cselect_b32 s7, s26, s34
	s_ashr_i32 s25, s24, 31
	s_lshl_b64 s[28:29], s[24:25], 19
	s_add_u32 s28, s44, s28
	s_addc_u32 s29, s45, s29
	s_and_b64 s[36:37], s[4:5], exec
	s_cselect_b32 s10, s29, s31
	s_cselect_b32 s23, s28, s30
	s_add_u32 s25, s30, 0x10000
	s_addc_u32 s38, s31, 0
	s_add_u32 s30, s34, 0x40080
	v_mov_b32_e32 v0, 0
	s_addc_u32 s31, s35, 0
	s_mov_b32 s39, -2
	v_mov_b32_e32 v1, v0
	v_mov_b32_e32 v2, v0
	v_mov_b32_e32 v3, v0
	v_mov_b32_e32 v4, v0
	v_mov_b32_e32 v5, v0
	v_mov_b32_e32 v6, v0
	v_mov_b32_e32 v7, v0
	v_mov_b32_e32 v8, v0
	v_mov_b32_e32 v9, v0
	v_mov_b32_e32 v10, v0
	v_mov_b32_e32 v11, v0
	v_mov_b32_e32 v12, v0
	v_mov_b32_e32 v13, v0
	v_mov_b32_e32 v14, v0
	v_mov_b32_e32 v15, v0
	v_mov_b32_e32 v16, v0
	v_mov_b32_e32 v17, v0
	v_mov_b32_e32 v18, v0
	v_mov_b32_e32 v19, v0
	v_mov_b32_e32 v20, v0
	v_mov_b32_e32 v21, v0
	v_mov_b32_e32 v22, v0
	v_mov_b32_e32 v23, v0
	v_mov_b32_e32 v24, v0
	v_mov_b32_e32 v25, v0
	v_mov_b32_e32 v26, v0
	v_mov_b32_e32 v27, v0
	v_mov_b32_e32 v28, v0
	v_mov_b32_e32 v29, v0
	v_mov_b32_e32 v30, v0
	v_mov_b32_e32 v31, v0
	v_mov_b32_e32 v64, v0
	v_mov_b32_e32 v65, v0
	v_mov_b32_e32 v66, v0
	v_mov_b32_e32 v67, v0
	v_mov_b32_e32 v68, v0
	v_mov_b32_e32 v69, v0
	v_mov_b32_e32 v70, v0
	v_mov_b32_e32 v71, v0
	v_mov_b32_e32 v72, v0
	v_mov_b32_e32 v73, v0
	v_mov_b32_e32 v74, v0
	v_mov_b32_e32 v75, v0
	v_mov_b32_e32 v76, v0
	v_mov_b32_e32 v77, v0
	v_mov_b32_e32 v78, v0
	v_mov_b32_e32 v79, v0
	v_mov_b32_e32 v80, v0
	v_mov_b32_e32 v81, v0
	v_mov_b32_e32 v82, v0
	v_mov_b32_e32 v83, v0
	v_mov_b32_e32 v84, v0
	v_mov_b32_e32 v85, v0
	v_mov_b32_e32 v86, v0
	v_mov_b32_e32 v87, v0
	v_mov_b32_e32 v88, v0
	v_mov_b32_e32 v89, v0
	v_mov_b32_e32 v90, v0
	v_mov_b32_e32 v91, v0
	v_mov_b32_e32 v92, v0
	v_mov_b32_e32 v93, v0
	v_mov_b32_e32 v94, v0
	v_mov_b32_e32 v95, v0
	v_mov_b32_e32 v32, v0
	v_mov_b32_e32 v33, v0
	v_mov_b32_e32 v34, v0
	v_mov_b32_e32 v35, v0
	v_mov_b32_e32 v36, v0
	v_mov_b32_e32 v37, v0
	v_mov_b32_e32 v38, v0
	v_mov_b32_e32 v39, v0
	v_mov_b32_e32 v40, v0
	v_mov_b32_e32 v41, v0
	v_mov_b32_e32 v42, v0
	v_mov_b32_e32 v43, v0
	v_mov_b32_e32 v44, v0
	v_mov_b32_e32 v45, v0
	v_mov_b32_e32 v46, v0
	v_mov_b32_e32 v47, v0
	v_mov_b32_e32 v48, v0
	v_mov_b32_e32 v49, v0
	v_mov_b32_e32 v50, v0
	v_mov_b32_e32 v51, v0
	v_mov_b32_e32 v52, v0
	v_mov_b32_e32 v53, v0
	v_mov_b32_e32 v54, v0
	v_mov_b32_e32 v55, v0
	v_mov_b32_e32 v56, v0
	v_mov_b32_e32 v57, v0
	v_mov_b32_e32 v58, v0
	v_mov_b32_e32 v59, v0
	v_mov_b32_e32 v60, v0
	v_mov_b32_e32 v61, v0
	v_mov_b32_e32 v62, v0
	v_mov_b32_e32 v63, v0
	v_mov_b32_e32 v96, v0
	v_mov_b32_e32 v97, v0
	v_mov_b32_e32 v98, v0
	v_mov_b32_e32 v99, v0
	v_mov_b32_e32 v100, v0
	v_mov_b32_e32 v101, v0
	v_mov_b32_e32 v102, v0
	v_mov_b32_e32 v103, v0
	v_mov_b32_e32 v104, v0
	v_mov_b32_e32 v105, v0
	v_mov_b32_e32 v106, v0
	v_mov_b32_e32 v107, v0
	v_mov_b32_e32 v108, v0
	v_mov_b32_e32 v109, v0
	v_mov_b32_e32 v110, v0
	v_mov_b32_e32 v111, v0
	v_mov_b32_e32 v112, v0
	v_mov_b32_e32 v113, v0
	v_mov_b32_e32 v114, v0
	v_mov_b32_e32 v115, v0
	v_mov_b32_e32 v116, v0
	v_mov_b32_e32 v117, v0
	v_mov_b32_e32 v118, v0
	v_mov_b32_e32 v119, v0
	v_mov_b32_e32 v120, v0
	v_mov_b32_e32 v121, v0
	v_mov_b32_e32 v122, v0
	v_mov_b32_e32 v123, v0
	v_mov_b32_e32 v124, v0
	v_mov_b32_e32 v125, v0
	v_mov_b32_e32 v126, v0
	v_mov_b32_e32 v127, v0
	s_branch .LBB0_492

.LBB0_492:
	ds_read_b128 v[128:131], v212
	ds_read_b128 v[132:135], v212 offset:1024
	ds_read_b128 v[136:139], v212 offset:2048
	ds_read_b128 v[140:143], v212 offset:3072
	ds_read_b128 v[144:147], v213
	ds_read_b128 v[148:151], v213 offset:1024
	ds_read_b128 v[152:155], v213 offset:2048
	ds_read_b128 v[156:159], v213 offset:3072
	s_add_u32 s34, s30, 0xfffc0080
	s_addc_u32 s35, s31, -1
	s_cmp_eq_u32 s39, 12
	s_cselect_b32 s37, s1, s35
	s_cselect_b32 s36, s7, s34
	s_cselect_b32 s35, s10, s38
	s_cselect_b32 s34, s23, s25
	v_lshl_add_u64 v[200:201], s[30:31], 0, v[190:191]
	s_add_i32 m0, s47, 0xc000
	ds_read_b128 v[160:163], v214
	ds_read_b128 v[164:167], v214 offset:1024
	ds_read_b128 v[196:199], v214 offset:2048
	ds_read_b128 v[216:219], v214 offset:3072
	ds_read_b128 v[220:223], v214 offset:4096
	ds_read_b128 v[224:227], v214 offset:5120
	ds_read_b128 v[228:231], v214 offset:6144
	ds_read_b128 v[232:235], v214 offset:7168
	global_load_lds_dwordx4 v[200:201], off
	v_lshl_add_u64 v[200:201], s[30:31], 0, v[188:189]
	s_add_i32 m0, s47, 0xe000
	s_nop 0
	global_load_lds_dwordx4 v[200:201], off
	s_waitcnt vmcnt(8)
	s_waitcnt lgkmcnt(0)
	s_barrier
	s_setprio 1
	s_waitcnt lgkmcnt(0)
	v_mfma_f32_16x16x32_bf16 v[124:127], v[128:131], v[160:163], v[124:127]
	v_mfma_f32_16x16x32_bf16 v[120:123], v[136:139], v[160:163], v[120:123]
	v_mfma_f32_16x16x32_bf16 v[116:119], v[128:131], v[196:199], v[116:119]
	v_mfma_f32_16x16x32_bf16 v[112:115], v[136:139], v[196:199], v[112:115]
	v_mfma_f32_16x16x32_bf16 v[108:111], v[128:131], v[220:223], v[108:111]
	v_mfma_f32_16x16x32_bf16 v[104:107], v[136:139], v[220:223], v[104:107]
	v_mfma_f32_16x16x32_bf16 v[100:103], v[128:131], v[228:231], v[100:103]
	v_mfma_f32_16x16x32_bf16 v[96:99], v[136:139], v[228:231], v[96:99]
	v_mfma_f32_16x16x32_bf16 v[124:127], v[132:135], v[164:167], v[124:127]
	v_mfma_f32_16x16x32_bf16 v[120:123], v[140:143], v[164:167], v[120:123]
	v_mfma_f32_16x16x32_bf16 v[116:119], v[132:135], v[216:219], v[116:119]
	v_mfma_f32_16x16x32_bf16 v[112:115], v[140:143], v[216:219], v[112:115]
	v_mfma_f32_16x16x32_bf16 v[108:111], v[132:135], v[224:227], v[108:111]
	v_mfma_f32_16x16x32_bf16 v[104:107], v[140:143], v[224:227], v[104:107]
	v_mfma_f32_16x16x32_bf16 v[100:103], v[132:135], v[232:235], v[100:103]
	v_mfma_f32_16x16x32_bf16 v[96:99], v[140:143], v[232:235], v[96:99]
	s_setprio 0
	s_setprio 1
	v_mfma_f32_16x16x32_bf16 v[60:63], v[144:147], v[160:163], v[60:63]
	v_mfma_f32_16x16x32_bf16 v[56:59], v[152:155], v[160:163], v[56:59]
	v_mfma_f32_16x16x32_bf16 v[52:55], v[144:147], v[196:199], v[52:55]
	v_mfma_f32_16x16x32_bf16 v[48:51], v[152:155], v[196:199], v[48:51]
	v_mfma_f32_16x16x32_bf16 v[44:47], v[144:147], v[220:223], v[44:47]
	v_mfma_f32_16x16x32_bf16 v[40:43], v[152:155], v[220:223], v[40:43]
	v_mfma_f32_16x16x32_bf16 v[36:39], v[144:147], v[228:231], v[36:39]
	v_mfma_f32_16x16x32_bf16 v[32:35], v[152:155], v[228:231], v[32:35]
	v_mfma_f32_16x16x32_bf16 v[60:63], v[148:151], v[164:167], v[60:63]
	v_mfma_f32_16x16x32_bf16 v[56:59], v[156:159], v[164:167], v[56:59]
	v_mfma_f32_16x16x32_bf16 v[52:55], v[148:151], v[216:219], v[52:55]
	v_mfma_f32_16x16x32_bf16 v[48:51], v[156:159], v[216:219], v[48:51]
	v_mfma_f32_16x16x32_bf16 v[44:47], v[148:151], v[224:227], v[44:47]
	v_mfma_f32_16x16x32_bf16 v[40:43], v[156:159], v[224:227], v[40:43]
	v_mfma_f32_16x16x32_bf16 v[36:39], v[148:151], v[232:235], v[36:39]
	v_mfma_f32_16x16x32_bf16 v[32:35], v[156:159], v[232:235], v[32:35]
	s_setprio 0
	s_barrier
	s_add_i32 s66, s61, s46
	v_lshl_add_u64 v[200:201], s[34:35], 0, v[172:173]
	s_mov_b32 m0, s66
	ds_read_b128 v[160:163], v214 offset:16384
	ds_read_b128 v[164:167], v214 offset:17408
	ds_read_b128 v[196:199], v214 offset:18432
	ds_read_b128 v[216:219], v214 offset:19456
	ds_read_b128 v[220:223], v214 offset:20480
	ds_read_b128 v[224:227], v214 offset:21504
	ds_read_b128 v[228:231], v214 offset:22528
	ds_read_b128 v[232:235], v214 offset:23552
	global_load_lds_dwordx4 v[200:201], off
	s_add_i32 m0, s66, 0x2000
	s_add_u32 s66, s34, 0x4000
	v_lshl_add_u64 v[200:201], s[34:35], 0, v[176:177]
	s_addc_u32 s67, s35, 0
	s_add_i32 s68, s62, s46
	global_load_lds_dwordx4 v[200:201], off
	v_lshl_add_u64 v[200:201], s[66:67], 0, v[172:173]
	s_mov_b32 m0, s68
	v_lshl_add_u64 v[236:237], s[36:37], 0, v[174:175]
	global_load_lds_dwordx4 v[200:201], off
	v_lshl_add_u64 v[200:201], s[66:67], 0, v[176:177]
	s_add_i32 m0, s68, 0x2000
	s_nop 0
	global_load_lds_dwordx4 v[200:201], off
	v_lshl_add_u64 v[200:201], s[36:37], 0, v[170:171]
	s_mov_b32 m0, s47
	s_nop 0
	global_load_lds_dwordx4 v[200:201], off
	s_mov_b32 m0, s48
	s_nop 0
	global_load_lds_dwordx4 v[236:237], off
	s_waitcnt vmcnt(8)
	s_waitcnt lgkmcnt(0)
	s_barrier
	s_setprio 1
	s_waitcnt lgkmcnt(0)
	v_mfma_f32_16x16x32_bf16 v[92:95], v[128:131], v[160:163], v[92:95]
	v_mfma_f32_16x16x32_bf16 v[88:91], v[136:139], v[160:163], v[88:91]
	v_mfma_f32_16x16x32_bf16 v[84:87], v[128:131], v[196:199], v[84:87]
	v_mfma_f32_16x16x32_bf16 v[80:83], v[136:139], v[196:199], v[80:83]
	v_mfma_f32_16x16x32_bf16 v[76:79], v[128:131], v[220:223], v[76:79]
	v_mfma_f32_16x16x32_bf16 v[72:75], v[136:139], v[220:223], v[72:75]
	v_mfma_f32_16x16x32_bf16 v[68:71], v[128:131], v[228:231], v[68:71]
	v_mfma_f32_16x16x32_bf16 v[64:67], v[136:139], v[228:231], v[64:67]
	v_mfma_f32_16x16x32_bf16 v[92:95], v[132:135], v[164:167], v[92:95]
	v_mfma_f32_16x16x32_bf16 v[88:91], v[140:143], v[164:167], v[88:91]
	v_mfma_f32_16x16x32_bf16 v[84:87], v[132:135], v[216:219], v[84:87]
	v_mfma_f32_16x16x32_bf16 v[80:83], v[140:143], v[216:219], v[80:83]
	v_mfma_f32_16x16x32_bf16 v[76:79], v[132:135], v[224:227], v[76:79]
	v_mfma_f32_16x16x32_bf16 v[72:75], v[140:143], v[224:227], v[72:75]
	v_mfma_f32_16x16x32_bf16 v[68:71], v[132:135], v[232:235], v[68:71]
	v_mfma_f32_16x16x32_bf16 v[64:67], v[140:143], v[232:235], v[64:67]
	s_setprio 0
	s_setprio 1
	v_mfma_f32_16x16x32_bf16 v[28:31], v[144:147], v[160:163], v[28:31]
	v_mfma_f32_16x16x32_bf16 v[24:27], v[152:155], v[160:163], v[24:27]
	v_mfma_f32_16x16x32_bf16 v[20:23], v[144:147], v[196:199], v[20:23]
	v_mfma_f32_16x16x32_bf16 v[16:19], v[152:155], v[196:199], v[16:19]
	v_mfma_f32_16x16x32_bf16 v[12:15], v[144:147], v[220:223], v[12:15]
	v_mfma_f32_16x16x32_bf16 v[8:11], v[152:155], v[220:223], v[8:11]
	v_mfma_f32_16x16x32_bf16 v[4:7], v[144:147], v[228:231], v[4:7]
	v_mfma_f32_16x16x32_bf16 v[0:3], v[152:155], v[228:231], v[0:3]
	v_mfma_f32_16x16x32_bf16 v[28:31], v[148:151], v[164:167], v[28:31]
	v_mfma_f32_16x16x32_bf16 v[24:27], v[156:159], v[164:167], v[24:27]
	v_mfma_f32_16x16x32_bf16 v[20:23], v[148:151], v[216:219], v[20:23]
	v_mfma_f32_16x16x32_bf16 v[16:19], v[156:159], v[216:219], v[16:19]
	v_mfma_f32_16x16x32_bf16 v[12:15], v[148:151], v[224:227], v[12:15]
	v_mfma_f32_16x16x32_bf16 v[8:11], v[156:159], v[224:227], v[8:11]
	v_mfma_f32_16x16x32_bf16 v[4:7], v[148:151], v[232:235], v[4:7]
	v_mfma_f32_16x16x32_bf16 v[0:3], v[156:159], v[232:235], v[0:3]
	s_setprio 0
	s_barrier
	s_add_i32 s66, 0, 0x18000
	s_add_i32 s67, 0, 0x1c000
	v_add_u32_e32 v140, s66, v210
	v_add_u32_e32 v156, s67, v210
	ds_read_b128 v[128:131], v140
	ds_read_b128 v[132:135], v140 offset:1024
	ds_read_b128 v[136:139], v140 offset:2048
	ds_read_b128 v[140:143], v140 offset:3072
	ds_read_b128 v[144:147], v156
	ds_read_b128 v[148:151], v156 offset:1024
	ds_read_b128 v[152:155], v156 offset:2048
	ds_read_b128 v[156:159], v156 offset:3072
	s_add_u32 s36, s36, 0x40000
	s_addc_u32 s37, s37, 0
	s_mov_b32 m0, s49
	v_lshl_add_u64 v[238:239], s[36:37], 0, v[170:171]
	ds_read_b128 v[160:163], v214 offset:32768
	ds_read_b128 v[164:167], v214 offset:33792
	ds_read_b128 v[196:199], v214 offset:34816
	ds_read_b128 v[216:219], v214 offset:35840
	ds_read_b128 v[220:223], v214 offset:36864
	ds_read_b128 v[224:227], v214 offset:37888
	ds_read_b128 v[228:231], v214 offset:38912
	ds_read_b128 v[232:235], v214 offset:39936
	global_load_lds_dwordx4 v[238:239], off
	v_lshl_add_u64 v[238:239], s[36:37], 0, v[174:175]
	s_mov_b32 m0, s50
	s_nop 0
	global_load_lds_dwordx4 v[238:239], off
	s_waitcnt vmcnt(8)
	s_waitcnt lgkmcnt(0)
	s_barrier
	s_setprio 1
	s_waitcnt lgkmcnt(0)
	v_mfma_f32_16x16x32_bf16 v[124:127], v[128:131], v[160:163], v[124:127]
	v_mfma_f32_16x16x32_bf16 v[120:123], v[136:139], v[160:163], v[120:123]
	v_mfma_f32_16x16x32_bf16 v[116:119], v[128:131], v[196:199], v[116:119]
	v_mfma_f32_16x16x32_bf16 v[112:115], v[136:139], v[196:199], v[112:115]
	v_mfma_f32_16x16x32_bf16 v[108:111], v[128:131], v[220:223], v[108:111]
	v_mfma_f32_16x16x32_bf16 v[104:107], v[136:139], v[220:223], v[104:107]
	v_mfma_f32_16x16x32_bf16 v[100:103], v[128:131], v[228:231], v[100:103]
	v_mfma_f32_16x16x32_bf16 v[96:99], v[136:139], v[228:231], v[96:99]
	v_mfma_f32_16x16x32_bf16 v[124:127], v[132:135], v[164:167], v[124:127]
	v_mfma_f32_16x16x32_bf16 v[120:123], v[140:143], v[164:167], v[120:123]
	v_mfma_f32_16x16x32_bf16 v[116:119], v[132:135], v[216:219], v[116:119]
	v_mfma_f32_16x16x32_bf16 v[112:115], v[140:143], v[216:219], v[112:115]
	v_mfma_f32_16x16x32_bf16 v[108:111], v[132:135], v[224:227], v[108:111]
	v_mfma_f32_16x16x32_bf16 v[104:107], v[140:143], v[224:227], v[104:107]
	v_mfma_f32_16x16x32_bf16 v[100:103], v[132:135], v[232:235], v[100:103]
	v_mfma_f32_16x16x32_bf16 v[96:99], v[140:143], v[232:235], v[96:99]
	s_setprio 0
	s_setprio 1
	v_mfma_f32_16x16x32_bf16 v[60:63], v[144:147], v[160:163], v[60:63]
	v_mfma_f32_16x16x32_bf16 v[56:59], v[152:155], v[160:163], v[56:59]
	v_mfma_f32_16x16x32_bf16 v[52:55], v[144:147], v[196:199], v[52:55]
	v_mfma_f32_16x16x32_bf16 v[48:51], v[152:155], v[196:199], v[48:51]
	v_mfma_f32_16x16x32_bf16 v[44:47], v[144:147], v[220:223], v[44:47]
	v_mfma_f32_16x16x32_bf16 v[40:43], v[152:155], v[220:223], v[40:43]
	v_mfma_f32_16x16x32_bf16 v[36:39], v[144:147], v[228:231], v[36:39]
	v_mfma_f32_16x16x32_bf16 v[32:35], v[152:155], v[228:231], v[32:35]
	v_mfma_f32_16x16x32_bf16 v[60:63], v[148:151], v[164:167], v[60:63]
	v_mfma_f32_16x16x32_bf16 v[56:59], v[156:159], v[164:167], v[56:59]
	v_mfma_f32_16x16x32_bf16 v[52:55], v[148:151], v[216:219], v[52:55]
	v_mfma_f32_16x16x32_bf16 v[48:51], v[156:159], v[216:219], v[48:51]
	v_mfma_f32_16x16x32_bf16 v[44:47], v[148:151], v[224:227], v[44:47]
	v_mfma_f32_16x16x32_bf16 v[40:43], v[156:159], v[224:227], v[40:43]
	v_mfma_f32_16x16x32_bf16 v[36:39], v[148:151], v[232:235], v[36:39]
	v_mfma_f32_16x16x32_bf16 v[32:35], v[156:159], v[232:235], v[32:35]
	s_setprio 0
	s_barrier
	s_add_u32 s36, s34, 0x8000
	s_addc_u32 s37, s35, 0
	s_add_i32 s66, s66, s46
	v_lshl_add_u64 v[238:239], s[36:37], 0, v[172:173]
	s_mov_b32 m0, s66
	ds_read_b128 v[160:163], v214 offset:49152
	ds_read_b128 v[164:167], v214 offset:50176
	ds_read_b128 v[196:199], v214 offset:51200
	ds_read_b128 v[216:219], v214 offset:52224
	ds_read_b128 v[220:223], v214 offset:53248
	ds_read_b128 v[224:227], v214 offset:54272
	ds_read_b128 v[228:231], v214 offset:55296
	ds_read_b128 v[232:235], v214 offset:56320
	global_load_lds_dwordx4 v[238:239], off
	s_add_i32 m0, s66, 0x2000
	s_add_u32 s34, s34, 0xc000
	v_lshl_add_u64 v[238:239], s[36:37], 0, v[176:177]
	s_addc_u32 s35, s35, 0
	s_add_i32 s36, s67, s46
	global_load_lds_dwordx4 v[238:239], off
	v_lshl_add_u64 v[238:239], s[34:35], 0, v[172:173]
	s_mov_b32 m0, s36
	v_lshl_add_u64 v[200:201], v[200:201], 0, s[16:17]
	global_load_lds_dwordx4 v[238:239], off
	v_lshl_add_u64 v[238:239], s[34:35], 0, v[176:177]
	s_add_i32 m0, s36, 0x2000
	s_nop 0
	global_load_lds_dwordx4 v[238:239], off
	s_mov_b32 m0, s55
	s_nop 0
	global_load_lds_dwordx4 v[200:201], off
	v_lshl_add_u64 v[200:201], v[236:237], 0, s[16:17]
	s_mov_b32 m0, s56
	s_nop 0
	global_load_lds_dwordx4 v[200:201], off
	s_waitcnt vmcnt(8)
	s_waitcnt lgkmcnt(0)
	s_barrier
	s_setprio 1
	s_waitcnt lgkmcnt(0)
	v_mfma_f32_16x16x32_bf16 v[92:95], v[128:131], v[160:163], v[92:95]
	v_mfma_f32_16x16x32_bf16 v[88:91], v[136:139], v[160:163], v[88:91]
	v_mfma_f32_16x16x32_bf16 v[84:87], v[128:131], v[196:199], v[84:87]
	v_mfma_f32_16x16x32_bf16 v[80:83], v[136:139], v[196:199], v[80:83]
	v_mfma_f32_16x16x32_bf16 v[76:79], v[128:131], v[220:223], v[76:79]
	v_mfma_f32_16x16x32_bf16 v[72:75], v[136:139], v[220:223], v[72:75]
	v_mfma_f32_16x16x32_bf16 v[68:71], v[128:131], v[228:231], v[68:71]
	v_mfma_f32_16x16x32_bf16 v[64:67], v[136:139], v[228:231], v[64:67]
	v_mfma_f32_16x16x32_bf16 v[92:95], v[132:135], v[164:167], v[92:95]
	v_mfma_f32_16x16x32_bf16 v[88:91], v[140:143], v[164:167], v[88:91]
	v_mfma_f32_16x16x32_bf16 v[84:87], v[132:135], v[216:219], v[84:87]
	v_mfma_f32_16x16x32_bf16 v[80:83], v[140:143], v[216:219], v[80:83]
	v_mfma_f32_16x16x32_bf16 v[76:79], v[132:135], v[224:227], v[76:79]
	v_mfma_f32_16x16x32_bf16 v[72:75], v[140:143], v[224:227], v[72:75]
	v_mfma_f32_16x16x32_bf16 v[68:71], v[132:135], v[232:235], v[68:71]
	v_mfma_f32_16x16x32_bf16 v[64:67], v[140:143], v[232:235], v[64:67]
	s_setprio 0
	s_setprio 1
	v_mfma_f32_16x16x32_bf16 v[28:31], v[144:147], v[160:163], v[28:31]
	v_mfma_f32_16x16x32_bf16 v[24:27], v[152:155], v[160:163], v[24:27]
	v_mfma_f32_16x16x32_bf16 v[20:23], v[144:147], v[196:199], v[20:23]
	v_mfma_f32_16x16x32_bf16 v[16:19], v[152:155], v[196:199], v[16:19]
	v_mfma_f32_16x16x32_bf16 v[12:15], v[144:147], v[220:223], v[12:15]
	v_mfma_f32_16x16x32_bf16 v[8:11], v[152:155], v[220:223], v[8:11]
	v_mfma_f32_16x16x32_bf16 v[4:7], v[144:147], v[228:231], v[4:7]
	v_mfma_f32_16x16x32_bf16 v[0:3], v[152:155], v[228:231], v[0:3]
	v_mfma_f32_16x16x32_bf16 v[28:31], v[148:151], v[164:167], v[28:31]
	v_mfma_f32_16x16x32_bf16 v[24:27], v[156:159], v[164:167], v[24:27]
	v_mfma_f32_16x16x32_bf16 v[20:23], v[148:151], v[216:219], v[20:23]
	v_mfma_f32_16x16x32_bf16 v[16:19], v[156:159], v[216:219], v[16:19]
	v_mfma_f32_16x16x32_bf16 v[12:15], v[148:151], v[224:227], v[12:15]
	v_mfma_f32_16x16x32_bf16 v[8:11], v[156:159], v[224:227], v[8:11]
	v_mfma_f32_16x16x32_bf16 v[4:7], v[148:151], v[232:235], v[4:7]
	v_mfma_f32_16x16x32_bf16 v[0:3], v[156:159], v[232:235], v[0:3]
	s_setprio 0
	s_add_i32 s39, s39, 2
	s_add_u32 s25, s25, 0x10000
	s_addc_u32 s38, s38, 0
	s_add_u32 s30, s30, 0x100
	s_addc_u32 s31, s31, 0
	s_cmp_gt_u32 s39, 13
	s_cbranch_scc0 .Lrot2
	s_barrier
	s_and_b64 vcc, exec, s[18:19]
	s_cbranch_vccz .LBB0_503
	s_barrier
	v_lshl_add_u32 v216, s0, 8, v169
	s_cmp_gt_i32 s6, 4
	s_mov_b64 s[0:1], -1
	s_cbranch_scc1 .LBB0_504

.LBB0_1070:
	s_ashr_i32 s17, s16, 31
	s_lshl_b64 s[20:21], s[16:17], 18
	s_add_u32 s20, s38, s20
	s_addc_u32 s21, s39, s21
	s_and_b64 s[22:23], s[0:1], exec
	s_cselect_b32 s17, s21, s31
	s_cselect_b32 s52, s20, s30
	s_ashr_i32 s19, s18, 31
	s_lshl_b64 s[22:23], s[18:19], 18
	s_add_u32 s22, s40, s22
	s_addc_u32 s23, s41, s23
	s_and_b64 s[34:35], s[0:1], exec
	s_cselect_b32 s19, s23, s29
	s_cselect_b32 s53, s22, s28
	s_add_u32 s54, s28, 0x10000
	s_addc_u32 s55, s29, 0
	s_add_u32 s28, s30, 0x20080
	v_mov_b32_e32 v0, 0
	s_addc_u32 s29, s31, 0
	s_mov_b32 s56, -2
	v_mov_b32_e32 v1, v0
	v_mov_b32_e32 v2, v0
	v_mov_b32_e32 v3, v0
	v_mov_b32_e32 v4, v0
	v_mov_b32_e32 v5, v0
	v_mov_b32_e32 v6, v0
	v_mov_b32_e32 v7, v0
	v_mov_b32_e32 v12, v0
	v_mov_b32_e32 v13, v0
	v_mov_b32_e32 v14, v0
	v_mov_b32_e32 v15, v0
	v_mov_b32_e32 v20, v0
	v_mov_b32_e32 v21, v0
	v_mov_b32_e32 v22, v0
	v_mov_b32_e32 v23, v0
	v_mov_b32_e32 v28, v0
	v_mov_b32_e32 v29, v0
	v_mov_b32_e32 v30, v0
	v_mov_b32_e32 v31, v0
	v_mov_b32_e32 v36, v0
	v_mov_b32_e32 v37, v0
	v_mov_b32_e32 v38, v0
	v_mov_b32_e32 v39, v0
	v_mov_b32_e32 v44, v0
	v_mov_b32_e32 v45, v0
	v_mov_b32_e32 v46, v0
	v_mov_b32_e32 v47, v0
	v_mov_b32_e32 v52, v0
	v_mov_b32_e32 v53, v0
	v_mov_b32_e32 v54, v0
	v_mov_b32_e32 v55, v0
	v_mov_b32_e32 v8, v0
	v_mov_b32_e32 v9, v0
	v_mov_b32_e32 v10, v0
	v_mov_b32_e32 v11, v0
	v_mov_b32_e32 v16, v0
	v_mov_b32_e32 v17, v0
	v_mov_b32_e32 v18, v0
	v_mov_b32_e32 v19, v0
	v_mov_b32_e32 v24, v0
	v_mov_b32_e32 v25, v0
	v_mov_b32_e32 v26, v0
	v_mov_b32_e32 v27, v0
	v_mov_b32_e32 v32, v0
	v_mov_b32_e32 v33, v0
	v_mov_b32_e32 v34, v0
	v_mov_b32_e32 v35, v0
	v_mov_b32_e32 v40, v0
	v_mov_b32_e32 v41, v0
	v_mov_b32_e32 v42, v0
	v_mov_b32_e32 v43, v0
	v_mov_b32_e32 v48, v0
	v_mov_b32_e32 v49, v0
	v_mov_b32_e32 v50, v0
	v_mov_b32_e32 v51, v0
	v_mov_b32_e32 v56, v0
	v_mov_b32_e32 v57, v0
	v_mov_b32_e32 v58, v0
	v_mov_b32_e32 v59, v0
	v_mov_b32_e32 v60, v0
	v_mov_b32_e32 v61, v0
	v_mov_b32_e32 v62, v0
	v_mov_b32_e32 v63, v0
	v_mov_b32_e32 v64, v0
	v_mov_b32_e32 v65, v0
	v_mov_b32_e32 v66, v0
	v_mov_b32_e32 v67, v0
	v_mov_b32_e32 v68, v0
	v_mov_b32_e32 v69, v0
	v_mov_b32_e32 v70, v0
	v_mov_b32_e32 v71, v0
	v_mov_b32_e32 v76, v0
	v_mov_b32_e32 v77, v0
	v_mov_b32_e32 v78, v0
	v_mov_b32_e32 v79, v0
	v_mov_b32_e32 v80, v0
	v_mov_b32_e32 v81, v0
	v_mov_b32_e32 v82, v0
	v_mov_b32_e32 v83, v0
	v_mov_b32_e32 v96, v0
	v_mov_b32_e32 v97, v0
	v_mov_b32_e32 v98, v0
	v_mov_b32_e32 v99, v0
	v_mov_b32_e32 v100, v0
	v_mov_b32_e32 v101, v0
	v_mov_b32_e32 v102, v0
	v_mov_b32_e32 v103, v0
	v_mov_b32_e32 v104, v0
	v_mov_b32_e32 v105, v0
	v_mov_b32_e32 v106, v0
	v_mov_b32_e32 v107, v0
	v_mov_b32_e32 v108, v0
	v_mov_b32_e32 v109, v0
	v_mov_b32_e32 v110, v0
	v_mov_b32_e32 v111, v0
	v_mov_b32_e32 v72, v0
	v_mov_b32_e32 v73, v0
	v_mov_b32_e32 v74, v0
	v_mov_b32_e32 v75, v0
	v_mov_b32_e32 v84, v0
	v_mov_b32_e32 v85, v0
	v_mov_b32_e32 v86, v0
	v_mov_b32_e32 v87, v0
	v_mov_b32_e32 v88, v0
	v_mov_b32_e32 v89, v0
	v_mov_b32_e32 v90, v0
	v_mov_b32_e32 v91, v0
	v_mov_b32_e32 v92, v0
	v_mov_b32_e32 v93, v0
	v_mov_b32_e32 v94, v0
	v_mov_b32_e32 v95, v0
	v_mov_b32_e32 v112, v0
	v_mov_b32_e32 v113, v0
	v_mov_b32_e32 v114, v0
	v_mov_b32_e32 v115, v0
	v_mov_b32_e32 v116, v0
	v_mov_b32_e32 v117, v0
	v_mov_b32_e32 v118, v0
	v_mov_b32_e32 v119, v0
	v_mov_b32_e32 v120, v0
	v_mov_b32_e32 v121, v0
	v_mov_b32_e32 v122, v0
	v_mov_b32_e32 v123, v0
	v_mov_b32_e32 v124, v0
	v_mov_b32_e32 v125, v0
	v_mov_b32_e32 v126, v0
	v_mov_b32_e32 v127, v0
	s_branch .LBB0_1071

.LBB0_1071:
	ds_read_b128 v[128:131], v170
	ds_read_b128 v[148:151], v170 offset:1024
	ds_read_b128 v[152:155], v170 offset:2048
	ds_read_b128 v[174:177], v170 offset:3072
	ds_read_b128 v[178:181], v171
	ds_read_b128 v[182:185], v171 offset:1024
	ds_read_b128 v[186:189], v171 offset:2048
	ds_read_b128 v[190:193], v171 offset:3072
	s_add_u32 s30, s28, 0xfffe0080
	s_addc_u32 s31, s29, -1
	s_cmp_eq_u32 s56, 4
	s_cselect_b32 s35, s17, s31
	s_cselect_b32 s34, s52, s30
	s_cselect_b32 s31, s19, s55
	s_cselect_b32 s30, s53, s54
	v_lshl_add_u64 v[234:235], s[28:29], 0, v[142:143]
	s_add_i32 m0, s25, 0xc000
	ds_read_b128 v[194:197], v172
	ds_read_b128 v[198:201], v172 offset:1024
	ds_read_b128 v[210:213], v172 offset:2048
	ds_read_b128 v[214:217], v172 offset:3072
	ds_read_b128 v[218:221], v172 offset:4096
	ds_read_b128 v[222:225], v172 offset:5120
	ds_read_b128 v[226:229], v172 offset:6144
	ds_read_b128 v[230:233], v172 offset:7168
	global_load_lds_dwordx4 v[234:235], off
	v_lshl_add_u64 v[234:235], s[28:29], 0, v[140:141]
	s_add_i32 m0, s25, 0xe000
	s_nop 0
	global_load_lds_dwordx4 v[234:235], off
	s_waitcnt vmcnt(8)
	s_waitcnt lgkmcnt(0)
	s_barrier
	s_setprio 1
	s_waitcnt lgkmcnt(0)
	v_mfma_f32_16x16x32_bf16 v[124:127], v[128:131], v[194:197], v[124:127]
	v_mfma_f32_16x16x32_bf16 v[120:123], v[152:155], v[194:197], v[120:123]
	v_mfma_f32_16x16x32_bf16 v[116:119], v[128:131], v[210:213], v[116:119]
	v_mfma_f32_16x16x32_bf16 v[112:115], v[152:155], v[210:213], v[112:115]
	v_mfma_f32_16x16x32_bf16 v[92:95], v[128:131], v[218:221], v[92:95]
	v_mfma_f32_16x16x32_bf16 v[88:91], v[152:155], v[218:221], v[88:91]
	v_mfma_f32_16x16x32_bf16 v[84:87], v[128:131], v[226:229], v[84:87]
	v_mfma_f32_16x16x32_bf16 v[72:75], v[152:155], v[226:229], v[72:75]
	v_mfma_f32_16x16x32_bf16 v[124:127], v[148:151], v[198:201], v[124:127]
	v_mfma_f32_16x16x32_bf16 v[120:123], v[174:177], v[198:201], v[120:123]
	v_mfma_f32_16x16x32_bf16 v[116:119], v[148:151], v[214:217], v[116:119]
	v_mfma_f32_16x16x32_bf16 v[112:115], v[174:177], v[214:217], v[112:115]
	v_mfma_f32_16x16x32_bf16 v[92:95], v[148:151], v[222:225], v[92:95]
	v_mfma_f32_16x16x32_bf16 v[88:91], v[174:177], v[222:225], v[88:91]
	v_mfma_f32_16x16x32_bf16 v[84:87], v[148:151], v[230:233], v[84:87]
	v_mfma_f32_16x16x32_bf16 v[72:75], v[174:177], v[230:233], v[72:75]
	s_setprio 0
	s_setprio 1
	v_mfma_f32_16x16x32_bf16 v[108:111], v[178:181], v[194:197], v[108:111]
	v_mfma_f32_16x16x32_bf16 v[104:107], v[186:189], v[194:197], v[104:107]
	v_mfma_f32_16x16x32_bf16 v[100:103], v[178:181], v[210:213], v[100:103]
	v_mfma_f32_16x16x32_bf16 v[96:99], v[186:189], v[210:213], v[96:99]
	v_mfma_f32_16x16x32_bf16 v[80:83], v[178:181], v[218:221], v[80:83]
	v_mfma_f32_16x16x32_bf16 v[76:79], v[186:189], v[218:221], v[76:79]
	v_mfma_f32_16x16x32_bf16 v[68:71], v[178:181], v[226:229], v[68:71]
	v_mfma_f32_16x16x32_bf16 v[64:67], v[186:189], v[226:229], v[64:67]
	v_mfma_f32_16x16x32_bf16 v[108:111], v[182:185], v[198:201], v[108:111]
	v_mfma_f32_16x16x32_bf16 v[104:107], v[190:193], v[198:201], v[104:107]
	v_mfma_f32_16x16x32_bf16 v[100:103], v[182:185], v[214:217], v[100:103]
	v_mfma_f32_16x16x32_bf16 v[96:99], v[190:193], v[214:217], v[96:99]
	v_mfma_f32_16x16x32_bf16 v[80:83], v[182:185], v[222:225], v[80:83]
	v_mfma_f32_16x16x32_bf16 v[76:79], v[190:193], v[222:225], v[76:79]
	v_mfma_f32_16x16x32_bf16 v[68:71], v[182:185], v[230:233], v[68:71]
	v_mfma_f32_16x16x32_bf16 v[64:67], v[190:193], v[230:233], v[64:67]
	s_setprio 0
	s_barrier
	s_add_i32 s57, s49, s42
	v_lshl_add_u64 v[234:235], s[30:31], 0, v[134:135]
	s_mov_b32 m0, s57
	ds_read_b128 v[194:197], v172 offset:16384
	ds_read_b128 v[198:201], v172 offset:17408
	ds_read_b128 v[210:213], v172 offset:18432
	ds_read_b128 v[214:217], v172 offset:19456
	ds_read_b128 v[218:221], v172 offset:20480
	ds_read_b128 v[222:225], v172 offset:21504
	ds_read_b128 v[226:229], v172 offset:22528
	ds_read_b128 v[230:233], v172 offset:23552
	global_load_lds_dwordx4 v[234:235], off
	s_add_i32 m0, s57, 0x2000
	s_add_u32 s58, s30, 0x4000
	v_lshl_add_u64 v[234:235], s[30:31], 0, v[138:139]
	s_addc_u32 s59, s31, 0
	s_add_i32 s57, s50, s42
	global_load_lds_dwordx4 v[234:235], off
	v_lshl_add_u64 v[234:235], s[58:59], 0, v[134:135]
	s_mov_b32 m0, s57
	v_lshl_add_u64 v[236:237], s[34:35], 0, v[136:137]
	global_load_lds_dwordx4 v[234:235], off
	v_lshl_add_u64 v[234:235], s[58:59], 0, v[138:139]
	s_add_i32 m0, s57, 0x2000
	s_nop 0
	global_load_lds_dwordx4 v[234:235], off
	v_lshl_add_u64 v[234:235], s[34:35], 0, v[132:133]
	s_mov_b32 m0, s25
	s_nop 0
	global_load_lds_dwordx4 v[234:235], off
	s_mov_b32 m0, s27
	s_nop 0
	global_load_lds_dwordx4 v[236:237], off
	s_waitcnt vmcnt(8)
	s_waitcnt lgkmcnt(0)
	s_barrier
	s_setprio 1
	s_waitcnt lgkmcnt(0)
	v_mfma_f32_16x16x32_bf16 v[60:63], v[128:131], v[194:197], v[60:63]
	v_mfma_f32_16x16x32_bf16 v[56:59], v[152:155], v[194:197], v[56:59]
	v_mfma_f32_16x16x32_bf16 v[48:51], v[128:131], v[210:213], v[48:51]
	v_mfma_f32_16x16x32_bf16 v[40:43], v[152:155], v[210:213], v[40:43]
	v_mfma_f32_16x16x32_bf16 v[32:35], v[128:131], v[218:221], v[32:35]
	v_mfma_f32_16x16x32_bf16 v[24:27], v[152:155], v[218:221], v[24:27]
	v_mfma_f32_16x16x32_bf16 v[16:19], v[128:131], v[226:229], v[16:19]
	v_mfma_f32_16x16x32_bf16 v[8:11], v[152:155], v[226:229], v[8:11]
	v_mfma_f32_16x16x32_bf16 v[60:63], v[148:151], v[198:201], v[60:63]
	v_mfma_f32_16x16x32_bf16 v[56:59], v[174:177], v[198:201], v[56:59]
	v_mfma_f32_16x16x32_bf16 v[48:51], v[148:151], v[214:217], v[48:51]
	v_mfma_f32_16x16x32_bf16 v[40:43], v[174:177], v[214:217], v[40:43]
	v_mfma_f32_16x16x32_bf16 v[32:35], v[148:151], v[222:225], v[32:35]
	v_mfma_f32_16x16x32_bf16 v[24:27], v[174:177], v[222:225], v[24:27]
	v_mfma_f32_16x16x32_bf16 v[16:19], v[148:151], v[230:233], v[16:19]
	v_mfma_f32_16x16x32_bf16 v[8:11], v[174:177], v[230:233], v[8:11]
	s_setprio 0
	s_setprio 1
	v_mfma_f32_16x16x32_bf16 v[52:55], v[178:181], v[194:197], v[52:55]
	v_mfma_f32_16x16x32_bf16 v[44:47], v[186:189], v[194:197], v[44:47]
	v_mfma_f32_16x16x32_bf16 v[36:39], v[178:181], v[210:213], v[36:39]
	v_mfma_f32_16x16x32_bf16 v[28:31], v[186:189], v[210:213], v[28:31]
	v_mfma_f32_16x16x32_bf16 v[20:23], v[178:181], v[218:221], v[20:23]
	v_mfma_f32_16x16x32_bf16 v[12:15], v[186:189], v[218:221], v[12:15]
	v_mfma_f32_16x16x32_bf16 v[4:7], v[178:181], v[226:229], v[4:7]
	v_mfma_f32_16x16x32_bf16 v[0:3], v[186:189], v[226:229], v[0:3]
	v_mfma_f32_16x16x32_bf16 v[52:55], v[182:185], v[198:201], v[52:55]
	v_mfma_f32_16x16x32_bf16 v[44:47], v[190:193], v[198:201], v[44:47]
	v_mfma_f32_16x16x32_bf16 v[36:39], v[182:185], v[214:217], v[36:39]
	v_mfma_f32_16x16x32_bf16 v[28:31], v[190:193], v[214:217], v[28:31]
	v_mfma_f32_16x16x32_bf16 v[20:23], v[182:185], v[222:225], v[20:23]
	v_mfma_f32_16x16x32_bf16 v[12:15], v[190:193], v[222:225], v[12:15]
	v_mfma_f32_16x16x32_bf16 v[4:7], v[182:185], v[230:233], v[4:7]
	v_mfma_f32_16x16x32_bf16 v[0:3], v[190:193], v[230:233], v[0:3]
	s_setprio 0
	s_barrier
	s_add_i32 s57, 0, 0x18000
	v_add_u32_e32 v173, s57, v168
	s_add_i32 s58, 0, 0x1c000
	ds_read_b128 v[128:131], v173
	ds_read_b128 v[148:151], v173 offset:1024
	ds_read_b128 v[152:155], v173 offset:2048
	ds_read_b128 v[174:177], v173 offset:3072
	v_add_u32_e32 v173, s58, v168
	ds_read_b128 v[178:181], v173
	ds_read_b128 v[182:185], v173 offset:1024
	ds_read_b128 v[186:189], v173 offset:2048
	ds_read_b128 v[190:193], v173 offset:3072
	s_add_u32 s34, s34, 0x20000
	s_addc_u32 s35, s35, 0
	s_mov_b32 m0, s43
	v_lshl_add_u64 v[238:239], s[34:35], 0, v[132:133]
	ds_read_b128 v[194:197], v172 offset:32768
	ds_read_b128 v[198:201], v172 offset:33792
	ds_read_b128 v[210:213], v172 offset:34816
	ds_read_b128 v[214:217], v172 offset:35840
	ds_read_b128 v[218:221], v172 offset:36864
	ds_read_b128 v[222:225], v172 offset:37888
	ds_read_b128 v[226:229], v172 offset:38912
	ds_read_b128 v[230:233], v172 offset:39936
	global_load_lds_dwordx4 v[238:239], off
	v_lshl_add_u64 v[238:239], s[34:35], 0, v[136:137]
	s_mov_b32 m0, s44
	s_nop 0
	global_load_lds_dwordx4 v[238:239], off
	s_waitcnt vmcnt(8)
	s_waitcnt lgkmcnt(0)
	s_barrier
	s_setprio 1
	s_waitcnt lgkmcnt(0)
	v_mfma_f32_16x16x32_bf16 v[124:127], v[128:131], v[194:197], v[124:127]
	v_mfma_f32_16x16x32_bf16 v[120:123], v[152:155], v[194:197], v[120:123]
	v_mfma_f32_16x16x32_bf16 v[116:119], v[128:131], v[210:213], v[116:119]
	v_mfma_f32_16x16x32_bf16 v[112:115], v[152:155], v[210:213], v[112:115]
	v_mfma_f32_16x16x32_bf16 v[92:95], v[128:131], v[218:221], v[92:95]
	v_mfma_f32_16x16x32_bf16 v[88:91], v[152:155], v[218:221], v[88:91]
	v_mfma_f32_16x16x32_bf16 v[84:87], v[128:131], v[226:229], v[84:87]
	v_mfma_f32_16x16x32_bf16 v[72:75], v[152:155], v[226:229], v[72:75]
	v_mfma_f32_16x16x32_bf16 v[124:127], v[148:151], v[198:201], v[124:127]
	v_mfma_f32_16x16x32_bf16 v[120:123], v[174:177], v[198:201], v[120:123]
	v_mfma_f32_16x16x32_bf16 v[116:119], v[148:151], v[214:217], v[116:119]
	v_mfma_f32_16x16x32_bf16 v[112:115], v[174:177], v[214:217], v[112:115]
	v_mfma_f32_16x16x32_bf16 v[92:95], v[148:151], v[222:225], v[92:95]
	v_mfma_f32_16x16x32_bf16 v[88:91], v[174:177], v[222:225], v[88:91]
	v_mfma_f32_16x16x32_bf16 v[84:87], v[148:151], v[230:233], v[84:87]
	v_mfma_f32_16x16x32_bf16 v[72:75], v[174:177], v[230:233], v[72:75]
	s_setprio 0
	s_setprio 1
	v_mfma_f32_16x16x32_bf16 v[108:111], v[178:181], v[194:197], v[108:111]
	v_mfma_f32_16x16x32_bf16 v[104:107], v[186:189], v[194:197], v[104:107]
	v_mfma_f32_16x16x32_bf16 v[100:103], v[178:181], v[210:213], v[100:103]
	v_mfma_f32_16x16x32_bf16 v[96:99], v[186:189], v[210:213], v[96:99]
	v_mfma_f32_16x16x32_bf16 v[80:83], v[178:181], v[218:221], v[80:83]
	v_mfma_f32_16x16x32_bf16 v[76:79], v[186:189], v[218:221], v[76:79]
	v_mfma_f32_16x16x32_bf16 v[68:71], v[178:181], v[226:229], v[68:71]
	v_mfma_f32_16x16x32_bf16 v[64:67], v[186:189], v[226:229], v[64:67]
	v_mfma_f32_16x16x32_bf16 v[108:111], v[182:185], v[198:201], v[108:111]
	v_mfma_f32_16x16x32_bf16 v[104:107], v[190:193], v[198:201], v[104:107]
	v_mfma_f32_16x16x32_bf16 v[100:103], v[182:185], v[214:217], v[100:103]
	v_mfma_f32_16x16x32_bf16 v[96:99], v[190:193], v[214:217], v[96:99]
	v_mfma_f32_16x16x32_bf16 v[80:83], v[182:185], v[222:225], v[80:83]
	v_mfma_f32_16x16x32_bf16 v[76:79], v[190:193], v[222:225], v[76:79]
	v_mfma_f32_16x16x32_bf16 v[68:71], v[182:185], v[230:233], v[68:71]
	v_mfma_f32_16x16x32_bf16 v[64:67], v[190:193], v[230:233], v[64:67]
	s_setprio 0
	s_barrier
	s_add_u32 s34, s30, 0x8000
	s_addc_u32 s35, s31, 0
	s_add_i32 s57, s57, s42
	v_lshl_add_u64 v[238:239], s[34:35], 0, v[134:135]
	s_mov_b32 m0, s57
	ds_read_b128 v[194:197], v172 offset:49152
	ds_read_b128 v[198:201], v172 offset:50176
	ds_read_b128 v[210:213], v172 offset:51200
	ds_read_b128 v[214:217], v172 offset:52224
	ds_read_b128 v[218:221], v172 offset:53248
	ds_read_b128 v[222:225], v172 offset:54272
	ds_read_b128 v[226:229], v172 offset:55296
	ds_read_b128 v[230:233], v172 offset:56320
	global_load_lds_dwordx4 v[238:239], off
	s_add_i32 m0, s57, 0x2000
	s_add_u32 s30, s30, 0xc000
	v_lshl_add_u64 v[238:239], s[34:35], 0, v[138:139]
	s_addc_u32 s31, s31, 0
	s_add_i32 s34, s58, s42
	global_load_lds_dwordx4 v[238:239], off
	v_lshl_add_u64 v[238:239], s[30:31], 0, v[134:135]
	s_mov_b32 m0, s34
	v_lshl_add_u64 v[234:235], v[234:235], 0, s[12:13]
	global_load_lds_dwordx4 v[238:239], off
	v_lshl_add_u64 v[238:239], s[30:31], 0, v[138:139]
	s_add_i32 m0, s34, 0x2000
	s_nop 0
	global_load_lds_dwordx4 v[238:239], off
	s_mov_b32 m0, s46
	s_nop 0
	global_load_lds_dwordx4 v[234:235], off
	v_lshl_add_u64 v[234:235], v[236:237], 0, s[12:13]
	s_mov_b32 m0, s47
	s_nop 0
	global_load_lds_dwordx4 v[234:235], off
	s_waitcnt vmcnt(8)
	s_waitcnt lgkmcnt(0)
	s_barrier
	s_setprio 1
	s_waitcnt lgkmcnt(0)
	v_mfma_f32_16x16x32_bf16 v[60:63], v[128:131], v[194:197], v[60:63]
	v_mfma_f32_16x16x32_bf16 v[56:59], v[152:155], v[194:197], v[56:59]
	v_mfma_f32_16x16x32_bf16 v[48:51], v[128:131], v[210:213], v[48:51]
	v_mfma_f32_16x16x32_bf16 v[40:43], v[152:155], v[210:213], v[40:43]
	v_mfma_f32_16x16x32_bf16 v[32:35], v[128:131], v[218:221], v[32:35]
	v_mfma_f32_16x16x32_bf16 v[24:27], v[152:155], v[218:221], v[24:27]
	v_mfma_f32_16x16x32_bf16 v[16:19], v[128:131], v[226:229], v[16:19]
	v_mfma_f32_16x16x32_bf16 v[8:11], v[152:155], v[226:229], v[8:11]
	v_mfma_f32_16x16x32_bf16 v[60:63], v[148:151], v[198:201], v[60:63]
	v_mfma_f32_16x16x32_bf16 v[56:59], v[174:177], v[198:201], v[56:59]
	v_mfma_f32_16x16x32_bf16 v[48:51], v[148:151], v[214:217], v[48:51]
	v_mfma_f32_16x16x32_bf16 v[40:43], v[174:177], v[214:217], v[40:43]
	v_mfma_f32_16x16x32_bf16 v[32:35], v[148:151], v[222:225], v[32:35]
	v_mfma_f32_16x16x32_bf16 v[24:27], v[174:177], v[222:225], v[24:27]
	v_mfma_f32_16x16x32_bf16 v[16:19], v[148:151], v[230:233], v[16:19]
	v_mfma_f32_16x16x32_bf16 v[8:11], v[174:177], v[230:233], v[8:11]
	s_setprio 0
	s_setprio 1
	v_mfma_f32_16x16x32_bf16 v[52:55], v[178:181], v[194:197], v[52:55]
	v_mfma_f32_16x16x32_bf16 v[44:47], v[186:189], v[194:197], v[44:47]
	v_mfma_f32_16x16x32_bf16 v[36:39], v[178:181], v[210:213], v[36:39]
	v_mfma_f32_16x16x32_bf16 v[28:31], v[186:189], v[210:213], v[28:31]
	v_mfma_f32_16x16x32_bf16 v[20:23], v[178:181], v[218:221], v[20:23]
	v_mfma_f32_16x16x32_bf16 v[12:15], v[186:189], v[218:221], v[12:15]
	v_mfma_f32_16x16x32_bf16 v[4:7], v[178:181], v[226:229], v[4:7]
	v_mfma_f32_16x16x32_bf16 v[0:3], v[186:189], v[226:229], v[0:3]
	v_mfma_f32_16x16x32_bf16 v[52:55], v[182:185], v[198:201], v[52:55]
	v_mfma_f32_16x16x32_bf16 v[44:47], v[190:193], v[198:201], v[44:47]
	v_mfma_f32_16x16x32_bf16 v[36:39], v[182:185], v[214:217], v[36:39]
	v_mfma_f32_16x16x32_bf16 v[28:31], v[190:193], v[214:217], v[28:31]
	v_mfma_f32_16x16x32_bf16 v[20:23], v[182:185], v[222:225], v[20:23]
	v_mfma_f32_16x16x32_bf16 v[12:15], v[190:193], v[222:225], v[12:15]
	v_mfma_f32_16x16x32_bf16 v[4:7], v[182:185], v[230:233], v[4:7]
	v_mfma_f32_16x16x32_bf16 v[0:3], v[190:193], v[230:233], v[0:3]
	s_setprio 0
	s_add_i32 s56, s56, 2
	s_add_u32 s54, s54, 0x10000
	s_addc_u32 s55, s55, 0
	s_add_u32 s28, s28, 0x100
	s_addc_u32 s29, s29, 0
	s_cmp_gt_u32 s56, 5
	s_cbranch_scc0 .Lrot3
	s_barrier
	s_and_b64 vcc, exec, s[14:15]
	s_cbranch_vccz .LBB0_1074
	s_barrier

.LBB0_1094:
	s_ashr_i32 s15, s14, 31
	s_lshl_b64 s[18:19], s[14:15], 18
	s_add_u32 s18, s35, s18
	s_addc_u32 s19, s37, s19
	s_and_b64 s[20:21], s[0:1], exec
	s_cselect_b32 s15, s19, s29
	s_cselect_b32 s50, s18, s28
	s_ashr_i32 s17, s16, 31
	s_lshl_b64 s[20:21], s[16:17], 18
	s_add_u32 s20, s38, s20
	s_addc_u32 s21, s39, s21
	s_and_b64 s[30:31], s[0:1], exec
	s_cselect_b32 s17, s21, s27
	s_cselect_b32 s51, s20, s26
	s_add_u32 s52, s26, 0x10000
	s_addc_u32 s53, s27, 0
	s_add_u32 s26, s28, 0x20080
	v_mov_b32_e32 v0, 0
	s_addc_u32 s27, s29, 0
	s_mov_b32 s54, -2
	v_mov_b32_e32 v1, v0
	v_mov_b32_e32 v2, v0
	v_mov_b32_e32 v3, v0
	v_mov_b32_e32 v4, v0
	v_mov_b32_e32 v5, v0
	v_mov_b32_e32 v6, v0
	v_mov_b32_e32 v7, v0
	v_mov_b32_e32 v12, v0
	v_mov_b32_e32 v13, v0
	v_mov_b32_e32 v14, v0
	v_mov_b32_e32 v15, v0
	v_mov_b32_e32 v20, v0
	v_mov_b32_e32 v21, v0
	v_mov_b32_e32 v22, v0
	v_mov_b32_e32 v23, v0
	v_mov_b32_e32 v32, v0
	v_mov_b32_e32 v33, v0
	v_mov_b32_e32 v34, v0
	v_mov_b32_e32 v35, v0
	v_mov_b32_e32 v36, v0
	v_mov_b32_e32 v37, v0
	v_mov_b32_e32 v38, v0
	v_mov_b32_e32 v39, v0
	v_mov_b32_e32 v44, v0
	v_mov_b32_e32 v45, v0
	v_mov_b32_e32 v46, v0
	v_mov_b32_e32 v47, v0
	v_mov_b32_e32 v52, v0
	v_mov_b32_e32 v53, v0
	v_mov_b32_e32 v54, v0
	v_mov_b32_e32 v55, v0
	v_mov_b32_e32 v8, v0
	v_mov_b32_e32 v9, v0
	v_mov_b32_e32 v10, v0
	v_mov_b32_e32 v11, v0
	v_mov_b32_e32 v16, v0
	v_mov_b32_e32 v17, v0
	v_mov_b32_e32 v18, v0
	v_mov_b32_e32 v19, v0
	v_mov_b32_e32 v24, v0
	v_mov_b32_e32 v25, v0
	v_mov_b32_e32 v26, v0
	v_mov_b32_e32 v27, v0
	v_mov_b32_e32 v28, v0
	v_mov_b32_e32 v29, v0
	v_mov_b32_e32 v30, v0
	v_mov_b32_e32 v31, v0
	v_mov_b32_e32 v40, v0
	v_mov_b32_e32 v41, v0
	v_mov_b32_e32 v42, v0
	v_mov_b32_e32 v43, v0
	v_mov_b32_e32 v48, v0
	v_mov_b32_e32 v49, v0
	v_mov_b32_e32 v50, v0
	v_mov_b32_e32 v51, v0
	v_mov_b32_e32 v56, v0
	v_mov_b32_e32 v57, v0
	v_mov_b32_e32 v58, v0
	v_mov_b32_e32 v59, v0
	v_mov_b32_e32 v60, v0
	v_mov_b32_e32 v61, v0
	v_mov_b32_e32 v62, v0
	v_mov_b32_e32 v63, v0
	v_mov_b32_e32 v64, v0
	v_mov_b32_e32 v65, v0
	v_mov_b32_e32 v66, v0
	v_mov_b32_e32 v67, v0
	v_mov_b32_e32 v68, v0
	v_mov_b32_e32 v69, v0
	v_mov_b32_e32 v70, v0
	v_mov_b32_e32 v71, v0
	v_mov_b32_e32 v76, v0
	v_mov_b32_e32 v77, v0
	v_mov_b32_e32 v78, v0
	v_mov_b32_e32 v79, v0
	v_mov_b32_e32 v84, v0
	v_mov_b32_e32 v85, v0
	v_mov_b32_e32 v86, v0
	v_mov_b32_e32 v87, v0
	v_mov_b32_e32 v96, v0
	v_mov_b32_e32 v97, v0
	v_mov_b32_e32 v98, v0
	v_mov_b32_e32 v99, v0
	v_mov_b32_e32 v100, v0
	v_mov_b32_e32 v101, v0
	v_mov_b32_e32 v102, v0
	v_mov_b32_e32 v103, v0
	v_mov_b32_e32 v108, v0
	v_mov_b32_e32 v109, v0
	v_mov_b32_e32 v110, v0
	v_mov_b32_e32 v111, v0
	v_mov_b32_e32 v116, v0
	v_mov_b32_e32 v117, v0
	v_mov_b32_e32 v118, v0
	v_mov_b32_e32 v119, v0
	v_mov_b32_e32 v72, v0
	v_mov_b32_e32 v73, v0
	v_mov_b32_e32 v74, v0
	v_mov_b32_e32 v75, v0
	v_mov_b32_e32 v80, v0
	v_mov_b32_e32 v81, v0
	v_mov_b32_e32 v82, v0
	v_mov_b32_e32 v83, v0
	v_mov_b32_e32 v88, v0
	v_mov_b32_e32 v89, v0
	v_mov_b32_e32 v90, v0
	v_mov_b32_e32 v91, v0
	v_mov_b32_e32 v92, v0
	v_mov_b32_e32 v93, v0
	v_mov_b32_e32 v94, v0
	v_mov_b32_e32 v95, v0
	v_mov_b32_e32 v104, v0
	v_mov_b32_e32 v105, v0
	v_mov_b32_e32 v106, v0
	v_mov_b32_e32 v107, v0
	v_mov_b32_e32 v112, v0
	v_mov_b32_e32 v113, v0
	v_mov_b32_e32 v114, v0
	v_mov_b32_e32 v115, v0
	v_mov_b32_e32 v120, v0
	v_mov_b32_e32 v121, v0
	v_mov_b32_e32 v122, v0
	v_mov_b32_e32 v123, v0
	v_mov_b32_e32 v124, v0
	v_mov_b32_e32 v125, v0
	v_mov_b32_e32 v126, v0
	v_mov_b32_e32 v127, v0
	s_branch .LBB0_1095

.LBB0_1095:
	ds_read_b128 v[144:147], v155
	ds_read_b128 v[148:151], v155 offset:1024
	ds_read_b128 v[158:161], v155 offset:2048
	ds_read_b128 v[162:165], v155 offset:3072
	ds_read_b128 v[166:169], v156
	ds_read_b128 v[170:173], v156 offset:1024
	ds_read_b128 v[174:177], v156 offset:2048
	ds_read_b128 v[178:181], v156 offset:3072
	s_add_u32 s28, s26, 0xfffe0080
	s_addc_u32 s29, s27, -1
	s_cmp_eq_u32 s54, 4
	s_cselect_b32 s31, s15, s29
	s_cselect_b32 s30, s50, s28
	s_cselect_b32 s29, s17, s53
	s_cselect_b32 s28, s51, s52
	v_lshl_add_u64 v[222:223], s[26:27], 0, v[130:131]
	s_add_i32 m0, s23, 0xc000
	ds_read_b128 v[182:185], v157
	ds_read_b128 v[186:189], v157 offset:1024
	ds_read_b128 v[190:193], v157 offset:2048
	ds_read_b128 v[194:197], v157 offset:3072
	ds_read_b128 v[198:201], v157 offset:4096
	ds_read_b128 v[210:213], v157 offset:5120
	ds_read_b128 v[214:217], v157 offset:6144
	ds_read_b128 v[218:221], v157 offset:7168
	global_load_lds_dwordx4 v[222:223], off
	v_lshl_add_u64 v[222:223], s[26:27], 0, v[128:129]
	s_add_i32 m0, s23, 0xe000
	s_nop 0
	global_load_lds_dwordx4 v[222:223], off
	s_waitcnt vmcnt(8)
	s_waitcnt lgkmcnt(0)
	s_barrier
	s_setprio 1
	s_waitcnt lgkmcnt(0)
	v_mfma_f32_16x16x32_bf16 v[124:127], v[144:147], v[182:185], v[124:127]
	v_mfma_f32_16x16x32_bf16 v[120:123], v[158:161], v[182:185], v[120:123]
	v_mfma_f32_16x16x32_bf16 v[112:115], v[144:147], v[190:193], v[112:115]
	v_mfma_f32_16x16x32_bf16 v[104:107], v[158:161], v[190:193], v[104:107]
	v_mfma_f32_16x16x32_bf16 v[92:95], v[144:147], v[198:201], v[92:95]
	v_mfma_f32_16x16x32_bf16 v[88:91], v[158:161], v[198:201], v[88:91]
	v_mfma_f32_16x16x32_bf16 v[80:83], v[144:147], v[214:217], v[80:83]
	v_mfma_f32_16x16x32_bf16 v[72:75], v[158:161], v[214:217], v[72:75]
	v_mfma_f32_16x16x32_bf16 v[124:127], v[148:151], v[186:189], v[124:127]
	v_mfma_f32_16x16x32_bf16 v[120:123], v[162:165], v[186:189], v[120:123]
	v_mfma_f32_16x16x32_bf16 v[112:115], v[148:151], v[194:197], v[112:115]
	v_mfma_f32_16x16x32_bf16 v[104:107], v[162:165], v[194:197], v[104:107]
	v_mfma_f32_16x16x32_bf16 v[92:95], v[148:151], v[210:213], v[92:95]
	v_mfma_f32_16x16x32_bf16 v[88:91], v[162:165], v[210:213], v[88:91]
	v_mfma_f32_16x16x32_bf16 v[80:83], v[148:151], v[218:221], v[80:83]
	v_mfma_f32_16x16x32_bf16 v[72:75], v[162:165], v[218:221], v[72:75]
	s_setprio 0
	s_setprio 1
	v_mfma_f32_16x16x32_bf16 v[116:119], v[166:169], v[182:185], v[116:119]
	v_mfma_f32_16x16x32_bf16 v[108:111], v[174:177], v[182:185], v[108:111]
	v_mfma_f32_16x16x32_bf16 v[100:103], v[166:169], v[190:193], v[100:103]
	v_mfma_f32_16x16x32_bf16 v[96:99], v[174:177], v[190:193], v[96:99]
	v_mfma_f32_16x16x32_bf16 v[84:87], v[166:169], v[198:201], v[84:87]
	v_mfma_f32_16x16x32_bf16 v[76:79], v[174:177], v[198:201], v[76:79]
	v_mfma_f32_16x16x32_bf16 v[68:71], v[166:169], v[214:217], v[68:71]
	v_mfma_f32_16x16x32_bf16 v[64:67], v[174:177], v[214:217], v[64:67]
	v_mfma_f32_16x16x32_bf16 v[116:119], v[170:173], v[186:189], v[116:119]
	v_mfma_f32_16x16x32_bf16 v[108:111], v[178:181], v[186:189], v[108:111]
	v_mfma_f32_16x16x32_bf16 v[100:103], v[170:173], v[194:197], v[100:103]
	v_mfma_f32_16x16x32_bf16 v[96:99], v[178:181], v[194:197], v[96:99]
	v_mfma_f32_16x16x32_bf16 v[84:87], v[170:173], v[210:213], v[84:87]
	v_mfma_f32_16x16x32_bf16 v[76:79], v[178:181], v[210:213], v[76:79]
	v_mfma_f32_16x16x32_bf16 v[68:71], v[170:173], v[218:221], v[68:71]
	v_mfma_f32_16x16x32_bf16 v[64:67], v[178:181], v[218:221], v[64:67]
	s_setprio 0
	s_barrier
	s_add_i32 s55, s47, s40
	v_lshl_add_u64 v[222:223], s[28:29], 0, v[134:135]
	s_mov_b32 m0, s55
	ds_read_b128 v[182:185], v157 offset:16384
	ds_read_b128 v[186:189], v157 offset:17408
	ds_read_b128 v[190:193], v157 offset:18432
	ds_read_b128 v[194:197], v157 offset:19456
	ds_read_b128 v[198:201], v157 offset:20480
	ds_read_b128 v[210:213], v157 offset:21504
	ds_read_b128 v[214:217], v157 offset:22528
	ds_read_b128 v[218:221], v157 offset:23552
	global_load_lds_dwordx4 v[222:223], off
	s_add_i32 m0, s55, 0x2000
	s_add_u32 s56, s28, 0x4000
	v_lshl_add_u64 v[222:223], s[28:29], 0, v[138:139]
	s_addc_u32 s57, s29, 0
	s_add_i32 s55, s48, s40
	global_load_lds_dwordx4 v[222:223], off
	v_lshl_add_u64 v[222:223], s[56:57], 0, v[134:135]
	s_mov_b32 m0, s55
	v_lshl_add_u64 v[224:225], s[30:31], 0, v[136:137]
	global_load_lds_dwordx4 v[222:223], off
	v_lshl_add_u64 v[222:223], s[56:57], 0, v[138:139]
	s_add_i32 m0, s55, 0x2000
	s_nop 0
	global_load_lds_dwordx4 v[222:223], off
	v_lshl_add_u64 v[222:223], s[30:31], 0, v[132:133]
	s_mov_b32 m0, s23
	s_nop 0
	global_load_lds_dwordx4 v[222:223], off
	s_mov_b32 m0, s25
	s_nop 0
	global_load_lds_dwordx4 v[224:225], off
	s_waitcnt vmcnt(8)
	s_waitcnt lgkmcnt(0)
	s_barrier
	s_setprio 1
	s_waitcnt lgkmcnt(0)
	v_mfma_f32_16x16x32_bf16 v[60:63], v[144:147], v[182:185], v[60:63]
	v_mfma_f32_16x16x32_bf16 v[56:59], v[158:161], v[182:185], v[56:59]
	v_mfma_f32_16x16x32_bf16 v[48:51], v[144:147], v[190:193], v[48:51]
	v_mfma_f32_16x16x32_bf16 v[40:43], v[158:161], v[190:193], v[40:43]
	v_mfma_f32_16x16x32_bf16 v[28:31], v[144:147], v[198:201], v[28:31]
	v_mfma_f32_16x16x32_bf16 v[24:27], v[158:161], v[198:201], v[24:27]
	v_mfma_f32_16x16x32_bf16 v[16:19], v[144:147], v[214:217], v[16:19]
	v_mfma_f32_16x16x32_bf16 v[8:11], v[158:161], v[214:217], v[8:11]
	v_mfma_f32_16x16x32_bf16 v[60:63], v[148:151], v[186:189], v[60:63]
	v_mfma_f32_16x16x32_bf16 v[56:59], v[162:165], v[186:189], v[56:59]
	v_mfma_f32_16x16x32_bf16 v[48:51], v[148:151], v[194:197], v[48:51]
	v_mfma_f32_16x16x32_bf16 v[40:43], v[162:165], v[194:197], v[40:43]
	v_mfma_f32_16x16x32_bf16 v[28:31], v[148:151], v[210:213], v[28:31]
	v_mfma_f32_16x16x32_bf16 v[24:27], v[162:165], v[210:213], v[24:27]
	v_mfma_f32_16x16x32_bf16 v[16:19], v[148:151], v[218:221], v[16:19]
	v_mfma_f32_16x16x32_bf16 v[8:11], v[162:165], v[218:221], v[8:11]
	s_setprio 0
	s_setprio 1
	v_mfma_f32_16x16x32_bf16 v[52:55], v[166:169], v[182:185], v[52:55]
	v_mfma_f32_16x16x32_bf16 v[44:47], v[174:177], v[182:185], v[44:47]
	v_mfma_f32_16x16x32_bf16 v[36:39], v[166:169], v[190:193], v[36:39]
	v_mfma_f32_16x16x32_bf16 v[32:35], v[174:177], v[190:193], v[32:35]
	v_mfma_f32_16x16x32_bf16 v[20:23], v[166:169], v[198:201], v[20:23]
	v_mfma_f32_16x16x32_bf16 v[12:15], v[174:177], v[198:201], v[12:15]
	v_mfma_f32_16x16x32_bf16 v[4:7], v[166:169], v[214:217], v[4:7]
	v_mfma_f32_16x16x32_bf16 v[0:3], v[174:177], v[214:217], v[0:3]
	v_mfma_f32_16x16x32_bf16 v[52:55], v[170:173], v[186:189], v[52:55]
	v_mfma_f32_16x16x32_bf16 v[44:47], v[178:181], v[186:189], v[44:47]
	v_mfma_f32_16x16x32_bf16 v[36:39], v[170:173], v[194:197], v[36:39]
	v_mfma_f32_16x16x32_bf16 v[32:35], v[178:181], v[194:197], v[32:35]
	v_mfma_f32_16x16x32_bf16 v[20:23], v[170:173], v[210:213], v[20:23]
	v_mfma_f32_16x16x32_bf16 v[12:15], v[178:181], v[210:213], v[12:15]
	v_mfma_f32_16x16x32_bf16 v[4:7], v[170:173], v[218:221], v[4:7]
	v_mfma_f32_16x16x32_bf16 v[0:3], v[178:181], v[218:221], v[0:3]
	s_setprio 0
	s_barrier
	s_add_i32 s55, 0, 0x18000
	s_add_i32 s56, 0, 0x1c000
	v_add_u32_e32 v162, s55, v153
	v_add_u32_e32 v178, s56, v153
	ds_read_b128 v[144:147], v162
	ds_read_b128 v[148:151], v162 offset:1024
	ds_read_b128 v[158:161], v162 offset:2048
	ds_read_b128 v[162:165], v162 offset:3072
	ds_read_b128 v[166:169], v178
	ds_read_b128 v[170:173], v178 offset:1024
	ds_read_b128 v[174:177], v178 offset:2048
	ds_read_b128 v[178:181], v178 offset:3072
	s_add_u32 s30, s30, 0x20000
	s_addc_u32 s31, s31, 0
	s_mov_b32 m0, s41
	v_lshl_add_u64 v[226:227], s[30:31], 0, v[132:133]
	ds_read_b128 v[182:185], v157 offset:32768
	ds_read_b128 v[186:189], v157 offset:33792
	ds_read_b128 v[190:193], v157 offset:34816
	ds_read_b128 v[194:197], v157 offset:35840
	ds_read_b128 v[198:201], v157 offset:36864
	ds_read_b128 v[210:213], v157 offset:37888
	ds_read_b128 v[214:217], v157 offset:38912
	ds_read_b128 v[218:221], v157 offset:39936
	global_load_lds_dwordx4 v[226:227], off
	v_lshl_add_u64 v[226:227], s[30:31], 0, v[136:137]
	s_mov_b32 m0, s42
	s_nop 0
	global_load_lds_dwordx4 v[226:227], off
	s_waitcnt vmcnt(8)
	s_waitcnt lgkmcnt(0)
	s_barrier
	s_setprio 1
	s_waitcnt lgkmcnt(0)
	v_mfma_f32_16x16x32_bf16 v[124:127], v[144:147], v[182:185], v[124:127]
	v_mfma_f32_16x16x32_bf16 v[120:123], v[158:161], v[182:185], v[120:123]
	v_mfma_f32_16x16x32_bf16 v[112:115], v[144:147], v[190:193], v[112:115]
	v_mfma_f32_16x16x32_bf16 v[104:107], v[158:161], v[190:193], v[104:107]
	v_mfma_f32_16x16x32_bf16 v[92:95], v[144:147], v[198:201], v[92:95]
	v_mfma_f32_16x16x32_bf16 v[88:91], v[158:161], v[198:201], v[88:91]
	v_mfma_f32_16x16x32_bf16 v[80:83], v[144:147], v[214:217], v[80:83]
	v_mfma_f32_16x16x32_bf16 v[72:75], v[158:161], v[214:217], v[72:75]
	v_mfma_f32_16x16x32_bf16 v[124:127], v[148:151], v[186:189], v[124:127]
	v_mfma_f32_16x16x32_bf16 v[120:123], v[162:165], v[186:189], v[120:123]
	v_mfma_f32_16x16x32_bf16 v[112:115], v[148:151], v[194:197], v[112:115]
	v_mfma_f32_16x16x32_bf16 v[104:107], v[162:165], v[194:197], v[104:107]
	v_mfma_f32_16x16x32_bf16 v[92:95], v[148:151], v[210:213], v[92:95]
	v_mfma_f32_16x16x32_bf16 v[88:91], v[162:165], v[210:213], v[88:91]
	v_mfma_f32_16x16x32_bf16 v[80:83], v[148:151], v[218:221], v[80:83]
	v_mfma_f32_16x16x32_bf16 v[72:75], v[162:165], v[218:221], v[72:75]
	s_setprio 0
	s_setprio 1
	v_mfma_f32_16x16x32_bf16 v[116:119], v[166:169], v[182:185], v[116:119]
	v_mfma_f32_16x16x32_bf16 v[108:111], v[174:177], v[182:185], v[108:111]
	v_mfma_f32_16x16x32_bf16 v[100:103], v[166:169], v[190:193], v[100:103]
	v_mfma_f32_16x16x32_bf16 v[96:99], v[174:177], v[190:193], v[96:99]
	v_mfma_f32_16x16x32_bf16 v[84:87], v[166:169], v[198:201], v[84:87]
	v_mfma_f32_16x16x32_bf16 v[76:79], v[174:177], v[198:201], v[76:79]
	v_mfma_f32_16x16x32_bf16 v[68:71], v[166:169], v[214:217], v[68:71]
	v_mfma_f32_16x16x32_bf16 v[64:67], v[174:177], v[214:217], v[64:67]
	v_mfma_f32_16x16x32_bf16 v[116:119], v[170:173], v[186:189], v[116:119]
	v_mfma_f32_16x16x32_bf16 v[108:111], v[178:181], v[186:189], v[108:111]
	v_mfma_f32_16x16x32_bf16 v[100:103], v[170:173], v[194:197], v[100:103]
	v_mfma_f32_16x16x32_bf16 v[96:99], v[178:181], v[194:197], v[96:99]
	v_mfma_f32_16x16x32_bf16 v[84:87], v[170:173], v[210:213], v[84:87]
	v_mfma_f32_16x16x32_bf16 v[76:79], v[178:181], v[210:213], v[76:79]
	v_mfma_f32_16x16x32_bf16 v[68:71], v[170:173], v[218:221], v[68:71]
	v_mfma_f32_16x16x32_bf16 v[64:67], v[178:181], v[218:221], v[64:67]
	s_setprio 0
	s_barrier
	s_add_u32 s30, s28, 0x8000
	s_addc_u32 s31, s29, 0
	s_add_i32 s55, s55, s40
	v_lshl_add_u64 v[226:227], s[30:31], 0, v[134:135]
	s_mov_b32 m0, s55
	ds_read_b128 v[182:185], v157 offset:49152
	ds_read_b128 v[186:189], v157 offset:50176
	ds_read_b128 v[190:193], v157 offset:51200
	ds_read_b128 v[194:197], v157 offset:52224
	ds_read_b128 v[198:201], v157 offset:53248
	ds_read_b128 v[210:213], v157 offset:54272
	ds_read_b128 v[214:217], v157 offset:55296
	ds_read_b128 v[218:221], v157 offset:56320
	global_load_lds_dwordx4 v[226:227], off
	s_add_i32 m0, s55, 0x2000
	s_add_u32 s28, s28, 0xc000
	v_lshl_add_u64 v[226:227], s[30:31], 0, v[138:139]
	s_addc_u32 s29, s29, 0
	s_add_i32 s30, s56, s40
	global_load_lds_dwordx4 v[226:227], off
	v_lshl_add_u64 v[226:227], s[28:29], 0, v[134:135]
	s_mov_b32 m0, s30
	v_lshl_add_u64 v[222:223], v[222:223], 0, s[8:9]
	global_load_lds_dwordx4 v[226:227], off
	v_lshl_add_u64 v[226:227], s[28:29], 0, v[138:139]
	s_add_i32 m0, s30, 0x2000
	s_nop 0
	global_load_lds_dwordx4 v[226:227], off
	s_mov_b32 m0, s44
	s_nop 0
	global_load_lds_dwordx4 v[222:223], off
	v_lshl_add_u64 v[222:223], v[224:225], 0, s[8:9]
	s_mov_b32 m0, s45
	s_nop 0
	global_load_lds_dwordx4 v[222:223], off
	s_waitcnt vmcnt(8)
	s_waitcnt lgkmcnt(0)
	s_barrier
	s_setprio 1
	s_waitcnt lgkmcnt(0)
	v_mfma_f32_16x16x32_bf16 v[60:63], v[144:147], v[182:185], v[60:63]
	v_mfma_f32_16x16x32_bf16 v[56:59], v[158:161], v[182:185], v[56:59]
	v_mfma_f32_16x16x32_bf16 v[48:51], v[144:147], v[190:193], v[48:51]
	v_mfma_f32_16x16x32_bf16 v[40:43], v[158:161], v[190:193], v[40:43]
	v_mfma_f32_16x16x32_bf16 v[28:31], v[144:147], v[198:201], v[28:31]
	v_mfma_f32_16x16x32_bf16 v[24:27], v[158:161], v[198:201], v[24:27]
	v_mfma_f32_16x16x32_bf16 v[16:19], v[144:147], v[214:217], v[16:19]
	v_mfma_f32_16x16x32_bf16 v[8:11], v[158:161], v[214:217], v[8:11]
	v_mfma_f32_16x16x32_bf16 v[60:63], v[148:151], v[186:189], v[60:63]
	v_mfma_f32_16x16x32_bf16 v[56:59], v[162:165], v[186:189], v[56:59]
	v_mfma_f32_16x16x32_bf16 v[48:51], v[148:151], v[194:197], v[48:51]
	v_mfma_f32_16x16x32_bf16 v[40:43], v[162:165], v[194:197], v[40:43]
	v_mfma_f32_16x16x32_bf16 v[28:31], v[148:151], v[210:213], v[28:31]
	v_mfma_f32_16x16x32_bf16 v[24:27], v[162:165], v[210:213], v[24:27]
	v_mfma_f32_16x16x32_bf16 v[16:19], v[148:151], v[218:221], v[16:19]
	v_mfma_f32_16x16x32_bf16 v[8:11], v[162:165], v[218:221], v[8:11]
	s_setprio 0
	s_setprio 1
	v_mfma_f32_16x16x32_bf16 v[52:55], v[166:169], v[182:185], v[52:55]
	v_mfma_f32_16x16x32_bf16 v[44:47], v[174:177], v[182:185], v[44:47]
	v_mfma_f32_16x16x32_bf16 v[36:39], v[166:169], v[190:193], v[36:39]
	v_mfma_f32_16x16x32_bf16 v[32:35], v[174:177], v[190:193], v[32:35]
	v_mfma_f32_16x16x32_bf16 v[20:23], v[166:169], v[198:201], v[20:23]
	v_mfma_f32_16x16x32_bf16 v[12:15], v[174:177], v[198:201], v[12:15]
	v_mfma_f32_16x16x32_bf16 v[4:7], v[166:169], v[214:217], v[4:7]
	v_mfma_f32_16x16x32_bf16 v[0:3], v[174:177], v[214:217], v[0:3]
	v_mfma_f32_16x16x32_bf16 v[52:55], v[170:173], v[186:189], v[52:55]
	v_mfma_f32_16x16x32_bf16 v[44:47], v[178:181], v[186:189], v[44:47]
	v_mfma_f32_16x16x32_bf16 v[36:39], v[170:173], v[194:197], v[36:39]
	v_mfma_f32_16x16x32_bf16 v[32:35], v[178:181], v[194:197], v[32:35]
	v_mfma_f32_16x16x32_bf16 v[20:23], v[170:173], v[210:213], v[20:23]
	v_mfma_f32_16x16x32_bf16 v[12:15], v[178:181], v[210:213], v[12:15]
	v_mfma_f32_16x16x32_bf16 v[4:7], v[170:173], v[218:221], v[4:7]
	v_mfma_f32_16x16x32_bf16 v[0:3], v[178:181], v[218:221], v[0:3]
	s_setprio 0
	s_add_i32 s54, s54, 2
	s_add_u32 s52, s52, 0x10000
	s_addc_u32 s53, s53, 0
	s_add_u32 s26, s26, 0x100
	s_addc_u32 s27, s27, 0
	s_cmp_gt_u32 s54, 5
	s_cbranch_scc0 .Lrot4
	s_barrier
	s_and_b64 vcc, exec, s[10:11]
	s_cbranch_vccz .LBB0_1098
	s_barrier

.LBB0_1170:
	s_ashr_i32 s35, s34, 31
	s_lshl_b64 s[38:39], s[34:35], 19
	s_add_u32 s38, s60, s38
	s_addc_u32 s39, s61, s39
	s_and_b64 s[40:41], s[8:9], exec
	s_cselect_b32 s35, s39, s49
	s_cselect_b32 s43, s38, s48
	s_ashr_i32 s37, s36, 31
	s_lshl_b64 s[40:41], s[36:37], 19
	s_add_u32 s40, s62, s40
	s_addc_u32 s41, s63, s41
	s_and_b64 s[50:51], s[8:9], exec
	s_cselect_b32 s37, s41, s47
	s_cselect_b32 s45, s40, s46
	s_add_u32 s52, s46, 0x10000
	s_addc_u32 s53, s47, 0
	s_add_u32 s46, s48, 0x40080
	v_mov_b32_e32 v0, 0
	s_addc_u32 s47, s49, 0
	s_mov_b32 s54, -2
	v_mov_b32_e32 v1, v0
	v_mov_b32_e32 v2, v0
	v_mov_b32_e32 v3, v0
	v_mov_b32_e32 v4, v0
	v_mov_b32_e32 v5, v0
	v_mov_b32_e32 v6, v0
	v_mov_b32_e32 v7, v0
	v_mov_b32_e32 v8, v0
	v_mov_b32_e32 v9, v0
	v_mov_b32_e32 v10, v0
	v_mov_b32_e32 v11, v0
	v_mov_b32_e32 v16, v0
	v_mov_b32_e32 v17, v0
	v_mov_b32_e32 v18, v0
	v_mov_b32_e32 v19, v0
	v_mov_b32_e32 v32, v0
	v_mov_b32_e32 v33, v0
	v_mov_b32_e32 v34, v0
	v_mov_b32_e32 v35, v0
	v_mov_b32_e32 v36, v0
	v_mov_b32_e32 v37, v0
	v_mov_b32_e32 v38, v0
	v_mov_b32_e32 v39, v0
	v_mov_b32_e32 v40, v0
	v_mov_b32_e32 v41, v0
	v_mov_b32_e32 v42, v0
	v_mov_b32_e32 v43, v0
	v_mov_b32_e32 v44, v0
	v_mov_b32_e32 v45, v0
	v_mov_b32_e32 v46, v0
	v_mov_b32_e32 v47, v0
	v_mov_b32_e32 v12, v0
	v_mov_b32_e32 v13, v0
	v_mov_b32_e32 v14, v0
	v_mov_b32_e32 v15, v0
	v_mov_b32_e32 v20, v0
	v_mov_b32_e32 v21, v0
	v_mov_b32_e32 v22, v0
	v_mov_b32_e32 v23, v0
	v_mov_b32_e32 v24, v0
	v_mov_b32_e32 v25, v0
	v_mov_b32_e32 v26, v0
	v_mov_b32_e32 v27, v0
	v_mov_b32_e32 v28, v0
	v_mov_b32_e32 v29, v0
	v_mov_b32_e32 v30, v0
	v_mov_b32_e32 v31, v0
	v_mov_b32_e32 v48, v0
	v_mov_b32_e32 v49, v0
	v_mov_b32_e32 v50, v0
	v_mov_b32_e32 v51, v0
	v_mov_b32_e32 v52, v0
	v_mov_b32_e32 v53, v0
	v_mov_b32_e32 v54, v0
	v_mov_b32_e32 v55, v0
	v_mov_b32_e32 v56, v0
	v_mov_b32_e32 v57, v0
	v_mov_b32_e32 v58, v0
	v_mov_b32_e32 v59, v0
	v_mov_b32_e32 v60, v0
	v_mov_b32_e32 v61, v0
	v_mov_b32_e32 v62, v0
	v_mov_b32_e32 v63, v0
	v_mov_b32_e32 v64, v0
	v_mov_b32_e32 v65, v0
	v_mov_b32_e32 v66, v0
	v_mov_b32_e32 v67, v0
	v_mov_b32_e32 v68, v0
	v_mov_b32_e32 v69, v0
	v_mov_b32_e32 v70, v0
	v_mov_b32_e32 v71, v0
	v_mov_b32_e32 v72, v0
	v_mov_b32_e32 v73, v0
	v_mov_b32_e32 v74, v0
	v_mov_b32_e32 v75, v0
	v_mov_b32_e32 v76, v0
	v_mov_b32_e32 v77, v0
	v_mov_b32_e32 v78, v0
	v_mov_b32_e32 v79, v0
	v_mov_b32_e32 v96, v0
	v_mov_b32_e32 v97, v0
	v_mov_b32_e32 v98, v0
	v_mov_b32_e32 v99, v0
	v_mov_b32_e32 v100, v0
	v_mov_b32_e32 v101, v0
	v_mov_b32_e32 v102, v0
	v_mov_b32_e32 v103, v0
	v_mov_b32_e32 v104, v0
	v_mov_b32_e32 v105, v0
	v_mov_b32_e32 v106, v0
	v_mov_b32_e32 v107, v0
	v_mov_b32_e32 v108, v0
	v_mov_b32_e32 v109, v0
	v_mov_b32_e32 v110, v0
	v_mov_b32_e32 v111, v0
	v_mov_b32_e32 v80, v0
	v_mov_b32_e32 v81, v0
	v_mov_b32_e32 v82, v0
	v_mov_b32_e32 v83, v0
	v_mov_b32_e32 v84, v0
	v_mov_b32_e32 v85, v0
	v_mov_b32_e32 v86, v0
	v_mov_b32_e32 v87, v0
	v_mov_b32_e32 v88, v0
	v_mov_b32_e32 v89, v0
	v_mov_b32_e32 v90, v0
	v_mov_b32_e32 v91, v0
	v_mov_b32_e32 v92, v0
	v_mov_b32_e32 v93, v0
	v_mov_b32_e32 v94, v0
	v_mov_b32_e32 v95, v0
	v_mov_b32_e32 v112, v0
	v_mov_b32_e32 v113, v0
	v_mov_b32_e32 v114, v0
	v_mov_b32_e32 v115, v0
	v_mov_b32_e32 v116, v0
	v_mov_b32_e32 v117, v0
	v_mov_b32_e32 v118, v0
	v_mov_b32_e32 v119, v0
	v_mov_b32_e32 v120, v0
	v_mov_b32_e32 v121, v0
	v_mov_b32_e32 v122, v0
	v_mov_b32_e32 v123, v0
	v_mov_b32_e32 v124, v0
	v_mov_b32_e32 v125, v0
	v_mov_b32_e32 v126, v0
	v_mov_b32_e32 v127, v0
	s_branch .LBB0_1171

.LBB0_1171:
	v_add_u32_e32 v168, s77, v182
	v_add_u32_e32 v204, s78, v182
	ds_read_b128 v[156:159], v168
	ds_read_b128 v[160:163], v168 offset:1024
	ds_read_b128 v[164:167], v168 offset:2048
	ds_read_b128 v[168:171], v168 offset:3072
	ds_read_b128 v[172:175], v204
	ds_read_b128 v[176:179], v204 offset:1024
	ds_read_b128 v[212:215], v204 offset:2048
	ds_read_b128 v[216:219], v204 offset:3072
	s_add_u32 s48, s46, 0xfffc0080
	s_addc_u32 s49, s47, -1
	s_cmp_eq_u32 s54, 12
	s_cselect_b32 s51, s35, s49
	s_cselect_b32 s50, s43, s48
	s_cselect_b32 s49, s37, s53
	s_cselect_b32 s48, s45, s52
	v_lshl_add_u64 v[252:253], s[46:47], 0, v[154:155]
	s_add_i32 m0, s65, 0xc000
	ds_read_b128 v[220:223], v199
	ds_read_b128 v[224:227], v199 offset:1024
	ds_read_b128 v[228:231], v199 offset:2048
	ds_read_b128 v[232:235], v199 offset:3072
	ds_read_b128 v[236:239], v199 offset:4096
	ds_read_b128 v[240:243], v199 offset:5120
	ds_read_b128 v[244:247], v199 offset:6144
	ds_read_b128 v[248:251], v199 offset:7168
	global_load_lds_dwordx4 v[252:253], off
	v_lshl_add_u64 v[252:253], s[46:47], 0, v[152:153]
	s_add_i32 m0, s65, 0xe000
	s_nop 0
	global_load_lds_dwordx4 v[252:253], off
	s_waitcnt vmcnt(8)
	s_waitcnt lgkmcnt(0)
	s_barrier
	s_setprio 1
	s_waitcnt lgkmcnt(0)
	v_mfma_f32_16x16x32_bf16 v[124:127], v[156:159], v[220:223], v[124:127]
	v_mfma_f32_16x16x32_bf16 v[120:123], v[164:167], v[220:223], v[120:123]
	v_mfma_f32_16x16x32_bf16 v[116:119], v[156:159], v[228:231], v[116:119]
	v_mfma_f32_16x16x32_bf16 v[112:115], v[164:167], v[228:231], v[112:115]
	v_mfma_f32_16x16x32_bf16 v[92:95], v[156:159], v[236:239], v[92:95]
	v_mfma_f32_16x16x32_bf16 v[88:91], v[164:167], v[236:239], v[88:91]
	v_mfma_f32_16x16x32_bf16 v[84:87], v[156:159], v[244:247], v[84:87]
	v_mfma_f32_16x16x32_bf16 v[80:83], v[164:167], v[244:247], v[80:83]
	v_mfma_f32_16x16x32_bf16 v[124:127], v[160:163], v[224:227], v[124:127]
	v_mfma_f32_16x16x32_bf16 v[120:123], v[168:171], v[224:227], v[120:123]
	v_mfma_f32_16x16x32_bf16 v[116:119], v[160:163], v[232:235], v[116:119]
	v_mfma_f32_16x16x32_bf16 v[112:115], v[168:171], v[232:235], v[112:115]
	v_mfma_f32_16x16x32_bf16 v[92:95], v[160:163], v[240:243], v[92:95]
	v_mfma_f32_16x16x32_bf16 v[88:91], v[168:171], v[240:243], v[88:91]
	v_mfma_f32_16x16x32_bf16 v[84:87], v[160:163], v[248:251], v[84:87]
	v_mfma_f32_16x16x32_bf16 v[80:83], v[168:171], v[248:251], v[80:83]
	s_setprio 0
	s_setprio 1
	v_mfma_f32_16x16x32_bf16 v[108:111], v[172:175], v[220:223], v[108:111]
	v_mfma_f32_16x16x32_bf16 v[104:107], v[212:215], v[220:223], v[104:107]
	v_mfma_f32_16x16x32_bf16 v[100:103], v[172:175], v[228:231], v[100:103]
	v_mfma_f32_16x16x32_bf16 v[96:99], v[212:215], v[228:231], v[96:99]
	v_mfma_f32_16x16x32_bf16 v[76:79], v[172:175], v[236:239], v[76:79]
	v_mfma_f32_16x16x32_bf16 v[72:75], v[212:215], v[236:239], v[72:75]
	v_mfma_f32_16x16x32_bf16 v[68:71], v[172:175], v[244:247], v[68:71]
	v_mfma_f32_16x16x32_bf16 v[64:67], v[212:215], v[244:247], v[64:67]
	v_mfma_f32_16x16x32_bf16 v[108:111], v[176:179], v[224:227], v[108:111]
	v_mfma_f32_16x16x32_bf16 v[104:107], v[216:219], v[224:227], v[104:107]
	v_mfma_f32_16x16x32_bf16 v[100:103], v[176:179], v[232:235], v[100:103]
	v_mfma_f32_16x16x32_bf16 v[96:99], v[216:219], v[232:235], v[96:99]
	v_mfma_f32_16x16x32_bf16 v[76:79], v[176:179], v[240:243], v[76:79]
	v_mfma_f32_16x16x32_bf16 v[72:75], v[216:219], v[240:243], v[72:75]
	v_mfma_f32_16x16x32_bf16 v[68:71], v[176:179], v[248:251], v[68:71]
	v_mfma_f32_16x16x32_bf16 v[64:67], v[216:219], v[248:251], v[64:67]
	s_setprio 0
	s_barrier
	s_add_i32 s55, s77, s64
	v_lshl_add_u64 v[252:253], s[48:49], 0, v[130:131]
	s_mov_b32 m0, s55
	ds_read_b128 v[220:223], v199 offset:16384
	ds_read_b128 v[224:227], v199 offset:17408
	ds_read_b128 v[228:231], v199 offset:18432
	ds_read_b128 v[232:235], v199 offset:19456
	ds_read_b128 v[236:239], v199 offset:20480
	ds_read_b128 v[240:243], v199 offset:21504
	ds_read_b128 v[244:247], v199 offset:22528
	ds_read_b128 v[248:251], v199 offset:23552
	global_load_lds_dwordx4 v[252:253], off
	s_add_i32 m0, s55, 0x2000
	s_add_u32 s56, s48, 0x4000
	v_lshl_add_u64 v[252:253], s[48:49], 0, v[134:135]
	s_addc_u32 s57, s49, 0
	s_add_i32 s55, s78, s64
	global_load_lds_dwordx4 v[252:253], off
	v_lshl_add_u64 v[252:253], s[56:57], 0, v[130:131]
	s_mov_b32 m0, s55
	v_lshl_add_u64 v[204:205], s[50:51], 0, v[132:133]
	global_load_lds_dwordx4 v[252:253], off
	v_lshl_add_u64 v[252:253], s[56:57], 0, v[134:135]
	s_add_i32 m0, s55, 0x2000
	s_nop 0
	global_load_lds_dwordx4 v[252:253], off
	v_lshl_add_u64 v[252:253], s[50:51], 0, v[128:129]
	s_mov_b32 m0, s65
	s_nop 0
	global_load_lds_dwordx4 v[252:253], off
	s_mov_b32 m0, s66
	s_nop 0
	global_load_lds_dwordx4 v[204:205], off
	s_waitcnt vmcnt(8)
	s_waitcnt lgkmcnt(0)
	s_barrier
	s_setprio 1
	s_waitcnt lgkmcnt(0)
	v_mfma_f32_16x16x32_bf16 v[60:63], v[156:159], v[220:223], v[60:63]
	v_mfma_f32_16x16x32_bf16 v[56:59], v[164:167], v[220:223], v[56:59]
	v_mfma_f32_16x16x32_bf16 v[52:55], v[156:159], v[228:231], v[52:55]
	v_mfma_f32_16x16x32_bf16 v[48:51], v[164:167], v[228:231], v[48:51]
	v_mfma_f32_16x16x32_bf16 v[28:31], v[156:159], v[236:239], v[28:31]
	v_mfma_f32_16x16x32_bf16 v[24:27], v[164:167], v[236:239], v[24:27]
	v_mfma_f32_16x16x32_bf16 v[20:23], v[156:159], v[244:247], v[20:23]
	v_mfma_f32_16x16x32_bf16 v[12:15], v[164:167], v[244:247], v[12:15]
	v_mfma_f32_16x16x32_bf16 v[60:63], v[160:163], v[224:227], v[60:63]
	v_mfma_f32_16x16x32_bf16 v[56:59], v[168:171], v[224:227], v[56:59]
	v_mfma_f32_16x16x32_bf16 v[52:55], v[160:163], v[232:235], v[52:55]
	v_mfma_f32_16x16x32_bf16 v[48:51], v[168:171], v[232:235], v[48:51]
	v_mfma_f32_16x16x32_bf16 v[28:31], v[160:163], v[240:243], v[28:31]
	v_mfma_f32_16x16x32_bf16 v[24:27], v[168:171], v[240:243], v[24:27]
	v_mfma_f32_16x16x32_bf16 v[20:23], v[160:163], v[248:251], v[20:23]
	v_mfma_f32_16x16x32_bf16 v[12:15], v[168:171], v[248:251], v[12:15]
	s_setprio 0
	s_setprio 1
	v_mfma_f32_16x16x32_bf16 v[44:47], v[172:175], v[220:223], v[44:47]
	v_mfma_f32_16x16x32_bf16 v[40:43], v[212:215], v[220:223], v[40:43]
	v_mfma_f32_16x16x32_bf16 v[36:39], v[172:175], v[228:231], v[36:39]
	v_mfma_f32_16x16x32_bf16 v[32:35], v[212:215], v[228:231], v[32:35]
	v_mfma_f32_16x16x32_bf16 v[16:19], v[172:175], v[236:239], v[16:19]
	v_mfma_f32_16x16x32_bf16 v[8:11], v[212:215], v[236:239], v[8:11]
	v_mfma_f32_16x16x32_bf16 v[4:7], v[172:175], v[244:247], v[4:7]
	v_mfma_f32_16x16x32_bf16 v[0:3], v[212:215], v[244:247], v[0:3]
	v_mfma_f32_16x16x32_bf16 v[44:47], v[176:179], v[224:227], v[44:47]
	v_mfma_f32_16x16x32_bf16 v[40:43], v[216:219], v[224:227], v[40:43]
	v_mfma_f32_16x16x32_bf16 v[36:39], v[176:179], v[232:235], v[36:39]
	v_mfma_f32_16x16x32_bf16 v[32:35], v[216:219], v[232:235], v[32:35]
	v_mfma_f32_16x16x32_bf16 v[16:19], v[176:179], v[240:243], v[16:19]
	v_mfma_f32_16x16x32_bf16 v[8:11], v[216:219], v[240:243], v[8:11]
	v_mfma_f32_16x16x32_bf16 v[4:7], v[176:179], v[248:251], v[4:7]
	v_mfma_f32_16x16x32_bf16 v[0:3], v[216:219], v[248:251], v[0:3]
	s_setprio 0
	s_barrier
	s_add_i32 s55, 0, 0x18000
	s_add_i32 s56, 0, 0x1c000
	v_add_u32_e32 v168, s55, v182
	v_add_u32_e32 v206, s56, v182
	ds_read_b128 v[156:159], v168
	ds_read_b128 v[160:163], v168 offset:1024
	ds_read_b128 v[164:167], v168 offset:2048
	ds_read_b128 v[168:171], v168 offset:3072
	ds_read_b128 v[172:175], v206
	ds_read_b128 v[176:179], v206 offset:1024
	ds_read_b128 v[212:215], v206 offset:2048
	ds_read_b128 v[216:219], v206 offset:3072
	s_add_u32 s50, s50, 0x40000
	s_addc_u32 s51, s51, 0
	s_mov_b32 m0, s67
	v_lshl_add_u64 v[206:207], s[50:51], 0, v[128:129]
	ds_read_b128 v[220:223], v199 offset:32768
	ds_read_b128 v[224:227], v199 offset:33792
	ds_read_b128 v[228:231], v199 offset:34816
	ds_read_b128 v[232:235], v199 offset:35840
	ds_read_b128 v[236:239], v199 offset:36864
	ds_read_b128 v[240:243], v199 offset:37888
	ds_read_b128 v[244:247], v199 offset:38912
	ds_read_b128 v[248:251], v199 offset:39936
	global_load_lds_dwordx4 v[206:207], off
	v_lshl_add_u64 v[206:207], s[50:51], 0, v[132:133]
	s_mov_b32 m0, s68
	s_nop 0
	global_load_lds_dwordx4 v[206:207], off
	s_waitcnt vmcnt(8)
	s_waitcnt lgkmcnt(0)
	s_barrier
	s_setprio 1
	s_waitcnt lgkmcnt(0)
	v_mfma_f32_16x16x32_bf16 v[124:127], v[156:159], v[220:223], v[124:127]
	v_mfma_f32_16x16x32_bf16 v[120:123], v[164:167], v[220:223], v[120:123]
	v_mfma_f32_16x16x32_bf16 v[116:119], v[156:159], v[228:231], v[116:119]
	v_mfma_f32_16x16x32_bf16 v[112:115], v[164:167], v[228:231], v[112:115]
	v_mfma_f32_16x16x32_bf16 v[92:95], v[156:159], v[236:239], v[92:95]
	v_mfma_f32_16x16x32_bf16 v[88:91], v[164:167], v[236:239], v[88:91]
	v_mfma_f32_16x16x32_bf16 v[84:87], v[156:159], v[244:247], v[84:87]
	v_mfma_f32_16x16x32_bf16 v[80:83], v[164:167], v[244:247], v[80:83]
	v_mfma_f32_16x16x32_bf16 v[124:127], v[160:163], v[224:227], v[124:127]
	v_mfma_f32_16x16x32_bf16 v[120:123], v[168:171], v[224:227], v[120:123]
	v_mfma_f32_16x16x32_bf16 v[116:119], v[160:163], v[232:235], v[116:119]
	v_mfma_f32_16x16x32_bf16 v[112:115], v[168:171], v[232:235], v[112:115]
	v_mfma_f32_16x16x32_bf16 v[92:95], v[160:163], v[240:243], v[92:95]
	v_mfma_f32_16x16x32_bf16 v[88:91], v[168:171], v[240:243], v[88:91]
	v_mfma_f32_16x16x32_bf16 v[84:87], v[160:163], v[248:251], v[84:87]
	v_mfma_f32_16x16x32_bf16 v[80:83], v[168:171], v[248:251], v[80:83]
	s_setprio 0
	s_setprio 1
	v_mfma_f32_16x16x32_bf16 v[108:111], v[172:175], v[220:223], v[108:111]
	v_mfma_f32_16x16x32_bf16 v[104:107], v[212:215], v[220:223], v[104:107]
	v_mfma_f32_16x16x32_bf16 v[100:103], v[172:175], v[228:231], v[100:103]
	v_mfma_f32_16x16x32_bf16 v[96:99], v[212:215], v[228:231], v[96:99]
	v_mfma_f32_16x16x32_bf16 v[76:79], v[172:175], v[236:239], v[76:79]
	v_mfma_f32_16x16x32_bf16 v[72:75], v[212:215], v[236:239], v[72:75]
	v_mfma_f32_16x16x32_bf16 v[68:71], v[172:175], v[244:247], v[68:71]
	v_mfma_f32_16x16x32_bf16 v[64:67], v[212:215], v[244:247], v[64:67]
	v_mfma_f32_16x16x32_bf16 v[108:111], v[176:179], v[224:227], v[108:111]
	v_mfma_f32_16x16x32_bf16 v[104:107], v[216:219], v[224:227], v[104:107]
	v_mfma_f32_16x16x32_bf16 v[100:103], v[176:179], v[232:235], v[100:103]
	v_mfma_f32_16x16x32_bf16 v[96:99], v[216:219], v[232:235], v[96:99]
	v_mfma_f32_16x16x32_bf16 v[76:79], v[176:179], v[240:243], v[76:79]
	v_mfma_f32_16x16x32_bf16 v[72:75], v[216:219], v[240:243], v[72:75]
	v_mfma_f32_16x16x32_bf16 v[68:71], v[176:179], v[248:251], v[68:71]
	v_mfma_f32_16x16x32_bf16 v[64:67], v[216:219], v[248:251], v[64:67]
	s_setprio 0
	s_barrier
	s_add_u32 s50, s48, 0x8000
	s_addc_u32 s51, s49, 0
	s_add_i32 s55, s55, s64
	v_lshl_add_u64 v[206:207], s[50:51], 0, v[130:131]
	s_mov_b32 m0, s55
	ds_read_b128 v[220:223], v199 offset:49152
	ds_read_b128 v[224:227], v199 offset:50176
	ds_read_b128 v[228:231], v199 offset:51200
	ds_read_b128 v[232:235], v199 offset:52224
	ds_read_b128 v[236:239], v199 offset:53248
	ds_read_b128 v[240:243], v199 offset:54272
	ds_read_b128 v[244:247], v199 offset:55296
	ds_read_b128 v[248:251], v199 offset:56320
	global_load_lds_dwordx4 v[206:207], off
	s_add_i32 m0, s55, 0x2000
	s_add_u32 s48, s48, 0xc000
	v_lshl_add_u64 v[206:207], s[50:51], 0, v[134:135]
	s_addc_u32 s49, s49, 0
	s_add_i32 s50, s56, s64
	global_load_lds_dwordx4 v[206:207], off
	v_lshl_add_u64 v[206:207], s[48:49], 0, v[130:131]
	s_mov_b32 m0, s50
	v_lshl_add_u64 v[204:205], v[204:205], 0, s[14:15]
	global_load_lds_dwordx4 v[206:207], off
	v_lshl_add_u64 v[206:207], s[48:49], 0, v[134:135]
	s_add_i32 m0, s50, 0x2000
	s_nop 0
	global_load_lds_dwordx4 v[206:207], off
	v_lshl_add_u64 v[206:207], v[252:253], 0, s[14:15]
	s_mov_b32 m0, s74
	s_nop 0
	global_load_lds_dwordx4 v[206:207], off
	s_mov_b32 m0, s75
	s_nop 0
	global_load_lds_dwordx4 v[204:205], off
	s_waitcnt vmcnt(8)
	s_waitcnt lgkmcnt(0)
	s_barrier
	s_setprio 1
	s_waitcnt lgkmcnt(0)
	v_mfma_f32_16x16x32_bf16 v[60:63], v[156:159], v[220:223], v[60:63]
	v_mfma_f32_16x16x32_bf16 v[56:59], v[164:167], v[220:223], v[56:59]
	v_mfma_f32_16x16x32_bf16 v[52:55], v[156:159], v[228:231], v[52:55]
	v_mfma_f32_16x16x32_bf16 v[48:51], v[164:167], v[228:231], v[48:51]
	v_mfma_f32_16x16x32_bf16 v[28:31], v[156:159], v[236:239], v[28:31]
	v_mfma_f32_16x16x32_bf16 v[24:27], v[164:167], v[236:239], v[24:27]
	v_mfma_f32_16x16x32_bf16 v[20:23], v[156:159], v[244:247], v[20:23]
	v_mfma_f32_16x16x32_bf16 v[12:15], v[164:167], v[244:247], v[12:15]
	v_mfma_f32_16x16x32_bf16 v[60:63], v[160:163], v[224:227], v[60:63]
	v_mfma_f32_16x16x32_bf16 v[56:59], v[168:171], v[224:227], v[56:59]
	v_mfma_f32_16x16x32_bf16 v[52:55], v[160:163], v[232:235], v[52:55]
	v_mfma_f32_16x16x32_bf16 v[48:51], v[168:171], v[232:235], v[48:51]
	v_mfma_f32_16x16x32_bf16 v[28:31], v[160:163], v[240:243], v[28:31]
	v_mfma_f32_16x16x32_bf16 v[24:27], v[168:171], v[240:243], v[24:27]
	v_mfma_f32_16x16x32_bf16 v[20:23], v[160:163], v[248:251], v[20:23]
	v_mfma_f32_16x16x32_bf16 v[12:15], v[168:171], v[248:251], v[12:15]
	s_setprio 0
	s_setprio 1
	v_mfma_f32_16x16x32_bf16 v[44:47], v[172:175], v[220:223], v[44:47]
	v_mfma_f32_16x16x32_bf16 v[40:43], v[212:215], v[220:223], v[40:43]
	v_mfma_f32_16x16x32_bf16 v[36:39], v[172:175], v[228:231], v[36:39]
	v_mfma_f32_16x16x32_bf16 v[32:35], v[212:215], v[228:231], v[32:35]
	v_mfma_f32_16x16x32_bf16 v[16:19], v[172:175], v[236:239], v[16:19]
	v_mfma_f32_16x16x32_bf16 v[8:11], v[212:215], v[236:239], v[8:11]
	v_mfma_f32_16x16x32_bf16 v[4:7], v[172:175], v[244:247], v[4:7]
	v_mfma_f32_16x16x32_bf16 v[0:3], v[212:215], v[244:247], v[0:3]
	v_mfma_f32_16x16x32_bf16 v[44:47], v[176:179], v[224:227], v[44:47]
	v_mfma_f32_16x16x32_bf16 v[40:43], v[216:219], v[224:227], v[40:43]
	v_mfma_f32_16x16x32_bf16 v[36:39], v[176:179], v[232:235], v[36:39]
	v_mfma_f32_16x16x32_bf16 v[32:35], v[216:219], v[232:235], v[32:35]
	v_mfma_f32_16x16x32_bf16 v[16:19], v[176:179], v[240:243], v[16:19]
	v_mfma_f32_16x16x32_bf16 v[8:11], v[216:219], v[240:243], v[8:11]
	v_mfma_f32_16x16x32_bf16 v[4:7], v[176:179], v[248:251], v[4:7]
	v_mfma_f32_16x16x32_bf16 v[0:3], v[216:219], v[248:251], v[0:3]
	s_setprio 0
	s_add_i32 s54, s54, 2
	s_add_u32 s52, s52, 0x10000
	s_addc_u32 s53, s53, 0
	s_add_u32 s46, s46, 0x100
	s_addc_u32 s47, s47, 0
	s_cmp_gt_u32 s54, 13
	s_cbranch_scc0 .Lrot5
	s_barrier
	s_and_b64 vcc, exec, s[18:19]
	s_cbranch_vccz .LBB0_1174
	s_barrier

.LBB0_1252:
	s_ashr_i32 s11, s10, 31
	s_lshl_b64 s[16:17], s[10:11], 19
	s_add_u32 s16, s30, s16
	s_addc_u32 s17, s31, s17
	s_and_b64 s[18:19], s[0:1], exec
	s_cselect_b32 s11, s17, s27
	s_cselect_b32 s50, s16, s26
	s_ashr_i32 s13, s12, 31
	s_lshl_b64 s[18:19], s[12:13], 19
	s_add_u32 s18, s33, s18
	s_addc_u32 s19, s34, s19
	s_and_b64 s[28:29], s[0:1], exec
	s_cselect_b32 s13, s19, s25
	s_cselect_b32 s51, s18, s24
	s_add_u32 s52, s24, 0x10000
	s_addc_u32 s53, s25, 0
	s_add_u32 s24, s26, 0x40080
	v_mov_b32_e32 v0, 0
	s_addc_u32 s25, s27, 0
	s_mov_b32 s54, -2
	v_mov_b32_e32 v1, v0
	v_mov_b32_e32 v2, v0
	v_mov_b32_e32 v3, v0
	v_mov_b32_e32 v8, v0
	v_mov_b32_e32 v9, v0
	v_mov_b32_e32 v10, v0
	v_mov_b32_e32 v11, v0
	v_mov_b32_e32 v16, v0
	v_mov_b32_e32 v17, v0
	v_mov_b32_e32 v18, v0
	v_mov_b32_e32 v19, v0
	v_mov_b32_e32 v24, v0
	v_mov_b32_e32 v25, v0
	v_mov_b32_e32 v26, v0
	v_mov_b32_e32 v27, v0
	v_mov_b32_e32 v32, v0
	v_mov_b32_e32 v33, v0
	v_mov_b32_e32 v34, v0
	v_mov_b32_e32 v35, v0
	v_mov_b32_e32 v40, v0
	v_mov_b32_e32 v41, v0
	v_mov_b32_e32 v42, v0
	v_mov_b32_e32 v43, v0
	v_mov_b32_e32 v48, v0
	v_mov_b32_e32 v49, v0
	v_mov_b32_e32 v50, v0
	v_mov_b32_e32 v51, v0
	v_mov_b32_e32 v56, v0
	v_mov_b32_e32 v57, v0
	v_mov_b32_e32 v58, v0
	v_mov_b32_e32 v59, v0
	v_mov_b32_e32 v4, v0
	v_mov_b32_e32 v5, v0
	v_mov_b32_e32 v6, v0
	v_mov_b32_e32 v7, v0
	v_mov_b32_e32 v12, v0
	v_mov_b32_e32 v13, v0
	v_mov_b32_e32 v14, v0
	v_mov_b32_e32 v15, v0
	v_mov_b32_e32 v20, v0
	v_mov_b32_e32 v21, v0
	v_mov_b32_e32 v22, v0
	v_mov_b32_e32 v23, v0
	v_mov_b32_e32 v28, v0
	v_mov_b32_e32 v29, v0
	v_mov_b32_e32 v30, v0
	v_mov_b32_e32 v31, v0
	v_mov_b32_e32 v36, v0
	v_mov_b32_e32 v37, v0
	v_mov_b32_e32 v38, v0
	v_mov_b32_e32 v39, v0
	v_mov_b32_e32 v44, v0
	v_mov_b32_e32 v45, v0
	v_mov_b32_e32 v46, v0
	v_mov_b32_e32 v47, v0
	v_mov_b32_e32 v52, v0
	v_mov_b32_e32 v53, v0
	v_mov_b32_e32 v54, v0
	v_mov_b32_e32 v55, v0
	v_mov_b32_e32 v60, v0
	v_mov_b32_e32 v61, v0
	v_mov_b32_e32 v62, v0
	v_mov_b32_e32 v63, v0
	v_mov_b32_e32 v64, v0
	v_mov_b32_e32 v65, v0
	v_mov_b32_e32 v66, v0
	v_mov_b32_e32 v67, v0
	v_mov_b32_e32 v72, v0
	v_mov_b32_e32 v73, v0
	v_mov_b32_e32 v74, v0
	v_mov_b32_e32 v75, v0
	v_mov_b32_e32 v80, v0
	v_mov_b32_e32 v81, v0
	v_mov_b32_e32 v82, v0
	v_mov_b32_e32 v83, v0
	v_mov_b32_e32 v88, v0
	v_mov_b32_e32 v89, v0
	v_mov_b32_e32 v90, v0
	v_mov_b32_e32 v91, v0
	v_mov_b32_e32 v96, v0
	v_mov_b32_e32 v97, v0
	v_mov_b32_e32 v98, v0
	v_mov_b32_e32 v99, v0
	v_mov_b32_e32 v104, v0
	v_mov_b32_e32 v105, v0
	v_mov_b32_e32 v106, v0
	v_mov_b32_e32 v107, v0
	v_mov_b32_e32 v112, v0
	v_mov_b32_e32 v113, v0
	v_mov_b32_e32 v114, v0
	v_mov_b32_e32 v115, v0
	v_mov_b32_e32 v120, v0
	v_mov_b32_e32 v121, v0
	v_mov_b32_e32 v122, v0
	v_mov_b32_e32 v123, v0
	v_mov_b32_e32 v68, v0
	v_mov_b32_e32 v69, v0
	v_mov_b32_e32 v70, v0
	v_mov_b32_e32 v71, v0
	v_mov_b32_e32 v76, v0
	v_mov_b32_e32 v77, v0
	v_mov_b32_e32 v78, v0
	v_mov_b32_e32 v79, v0
	v_mov_b32_e32 v84, v0
	v_mov_b32_e32 v85, v0
	v_mov_b32_e32 v86, v0
	v_mov_b32_e32 v87, v0
	v_mov_b32_e32 v92, v0
	v_mov_b32_e32 v93, v0
	v_mov_b32_e32 v94, v0
	v_mov_b32_e32 v95, v0
	v_mov_b32_e32 v100, v0
	v_mov_b32_e32 v101, v0
	v_mov_b32_e32 v102, v0
	v_mov_b32_e32 v103, v0
	v_mov_b32_e32 v108, v0
	v_mov_b32_e32 v109, v0
	v_mov_b32_e32 v110, v0
	v_mov_b32_e32 v111, v0
	v_mov_b32_e32 v116, v0
	v_mov_b32_e32 v117, v0
	v_mov_b32_e32 v118, v0
	v_mov_b32_e32 v119, v0
	v_mov_b32_e32 v124, v0
	v_mov_b32_e32 v125, v0
	v_mov_b32_e32 v126, v0
	v_mov_b32_e32 v127, v0
	s_branch .LBB0_1253

.LBB0_1253:
	ds_read_b128 v[170:173], v167
	ds_read_b128 v[174:177], v167 offset:1024
	ds_read_b128 v[178:181], v167 offset:2048
	ds_read_b128 v[182:185], v167 offset:3072
	ds_read_b128 v[186:189], v168
	ds_read_b128 v[190:193], v168 offset:1024
	ds_read_b128 v[194:197], v168 offset:2048
	ds_read_b128 v[198:201], v168 offset:3072
	s_add_u32 s26, s24, 0xfffc0080
	s_addc_u32 s27, s25, -1
	s_cmp_eq_u32 s54, 12
	s_cselect_b32 s29, s11, s27
	s_cselect_b32 s28, s50, s26
	s_cselect_b32 s27, s13, s53
	s_cselect_b32 s26, s51, s52
	v_lshl_add_u64 v[164:165], s[24:25], 0, v[158:159]
	s_add_i32 m0, s21, 0xc000
	ds_read_b128 v[210:213], v169
	ds_read_b128 v[214:217], v169 offset:1024
	ds_read_b128 v[218:221], v169 offset:2048
	ds_read_b128 v[222:225], v169 offset:3072
	ds_read_b128 v[226:229], v169 offset:4096
	ds_read_b128 v[230:233], v169 offset:5120
	ds_read_b128 v[234:237], v169 offset:6144
	ds_read_b128 v[238:241], v169 offset:7168
	global_load_lds_dwordx4 v[164:165], off
	v_lshl_add_u64 v[164:165], s[24:25], 0, v[156:157]
	s_add_i32 m0, s21, 0xe000
	s_nop 0
	global_load_lds_dwordx4 v[164:165], off
	s_waitcnt vmcnt(8)
	s_waitcnt lgkmcnt(0)
	s_barrier
	s_setprio 1
	s_waitcnt lgkmcnt(0)
	v_mfma_f32_16x16x32_bf16 v[124:127], v[170:173], v[210:213], v[124:127]
	v_mfma_f32_16x16x32_bf16 v[116:119], v[178:181], v[210:213], v[116:119]
	v_mfma_f32_16x16x32_bf16 v[108:111], v[170:173], v[218:221], v[108:111]
	v_mfma_f32_16x16x32_bf16 v[100:103], v[178:181], v[218:221], v[100:103]
	v_mfma_f32_16x16x32_bf16 v[92:95], v[170:173], v[226:229], v[92:95]
	v_mfma_f32_16x16x32_bf16 v[84:87], v[178:181], v[226:229], v[84:87]
	v_mfma_f32_16x16x32_bf16 v[76:79], v[170:173], v[234:237], v[76:79]
	v_mfma_f32_16x16x32_bf16 v[68:71], v[178:181], v[234:237], v[68:71]
	v_mfma_f32_16x16x32_bf16 v[124:127], v[174:177], v[214:217], v[124:127]
	v_mfma_f32_16x16x32_bf16 v[116:119], v[182:185], v[214:217], v[116:119]
	v_mfma_f32_16x16x32_bf16 v[108:111], v[174:177], v[222:225], v[108:111]
	v_mfma_f32_16x16x32_bf16 v[100:103], v[182:185], v[222:225], v[100:103]
	v_mfma_f32_16x16x32_bf16 v[92:95], v[174:177], v[230:233], v[92:95]
	v_mfma_f32_16x16x32_bf16 v[84:87], v[182:185], v[230:233], v[84:87]
	v_mfma_f32_16x16x32_bf16 v[76:79], v[174:177], v[238:241], v[76:79]
	v_mfma_f32_16x16x32_bf16 v[68:71], v[182:185], v[238:241], v[68:71]
	s_setprio 0
	s_setprio 1
	v_mfma_f32_16x16x32_bf16 v[120:123], v[186:189], v[210:213], v[120:123]
	v_mfma_f32_16x16x32_bf16 v[112:115], v[194:197], v[210:213], v[112:115]
	v_mfma_f32_16x16x32_bf16 v[104:107], v[186:189], v[218:221], v[104:107]
	v_mfma_f32_16x16x32_bf16 v[96:99], v[194:197], v[218:221], v[96:99]
	v_mfma_f32_16x16x32_bf16 v[88:91], v[186:189], v[226:229], v[88:91]
	v_mfma_f32_16x16x32_bf16 v[80:83], v[194:197], v[226:229], v[80:83]
	v_mfma_f32_16x16x32_bf16 v[72:75], v[186:189], v[234:237], v[72:75]
	v_mfma_f32_16x16x32_bf16 v[64:67], v[194:197], v[234:237], v[64:67]
	v_mfma_f32_16x16x32_bf16 v[120:123], v[190:193], v[214:217], v[120:123]
	v_mfma_f32_16x16x32_bf16 v[112:115], v[198:201], v[214:217], v[112:115]
	v_mfma_f32_16x16x32_bf16 v[104:107], v[190:193], v[222:225], v[104:107]
	v_mfma_f32_16x16x32_bf16 v[96:99], v[198:201], v[222:225], v[96:99]
	v_mfma_f32_16x16x32_bf16 v[88:91], v[190:193], v[230:233], v[88:91]
	v_mfma_f32_16x16x32_bf16 v[80:83], v[198:201], v[230:233], v[80:83]
	v_mfma_f32_16x16x32_bf16 v[72:75], v[190:193], v[238:241], v[72:75]
	v_mfma_f32_16x16x32_bf16 v[64:67], v[198:201], v[238:241], v[64:67]
	s_setprio 0
	s_barrier
	s_add_i32 s55, s48, s35
	v_lshl_add_u64 v[164:165], s[26:27], 0, v[134:135]
	s_mov_b32 m0, s55
	ds_read_b128 v[210:213], v169 offset:16384
	ds_read_b128 v[214:217], v169 offset:17408
	ds_read_b128 v[218:221], v169 offset:18432
	ds_read_b128 v[222:225], v169 offset:19456
	ds_read_b128 v[226:229], v169 offset:20480
	ds_read_b128 v[230:233], v169 offset:21504
	ds_read_b128 v[234:237], v169 offset:22528
	ds_read_b128 v[238:241], v169 offset:23552
	global_load_lds_dwordx4 v[164:165], off
	s_add_i32 m0, s55, 0x2000
	s_add_u32 s56, s26, 0x4000
	v_lshl_add_u64 v[164:165], s[26:27], 0, v[130:131]
	s_addc_u32 s57, s27, 0
	s_add_i32 s55, s49, s35
	global_load_lds_dwordx4 v[164:165], off
	v_lshl_add_u64 v[164:165], s[56:57], 0, v[134:135]
	s_mov_b32 m0, s55
	v_lshl_add_u64 v[204:205], s[28:29], 0, v[132:133]
	global_load_lds_dwordx4 v[164:165], off
	v_lshl_add_u64 v[164:165], s[56:57], 0, v[130:131]
	s_add_i32 m0, s55, 0x2000
	s_nop 0
	global_load_lds_dwordx4 v[164:165], off
	v_lshl_add_u64 v[164:165], s[28:29], 0, v[136:137]
	s_mov_b32 m0, s21
	s_nop 0
	global_load_lds_dwordx4 v[164:165], off
	s_mov_b32 m0, s23
	s_nop 0
	global_load_lds_dwordx4 v[204:205], off
	s_waitcnt vmcnt(8)
	s_waitcnt lgkmcnt(0)
	s_barrier
	s_setprio 1
	s_waitcnt lgkmcnt(0)
	v_mfma_f32_16x16x32_bf16 v[60:63], v[170:173], v[210:213], v[60:63]
	v_mfma_f32_16x16x32_bf16 v[52:55], v[178:181], v[210:213], v[52:55]
	v_mfma_f32_16x16x32_bf16 v[44:47], v[170:173], v[218:221], v[44:47]
	v_mfma_f32_16x16x32_bf16 v[36:39], v[178:181], v[218:221], v[36:39]
	v_mfma_f32_16x16x32_bf16 v[28:31], v[170:173], v[226:229], v[28:31]
	v_mfma_f32_16x16x32_bf16 v[20:23], v[178:181], v[226:229], v[20:23]
	v_mfma_f32_16x16x32_bf16 v[12:15], v[170:173], v[234:237], v[12:15]
	v_mfma_f32_16x16x32_bf16 v[4:7], v[178:181], v[234:237], v[4:7]
	v_mfma_f32_16x16x32_bf16 v[60:63], v[174:177], v[214:217], v[60:63]
	v_mfma_f32_16x16x32_bf16 v[52:55], v[182:185], v[214:217], v[52:55]
	v_mfma_f32_16x16x32_bf16 v[44:47], v[174:177], v[222:225], v[44:47]
	v_mfma_f32_16x16x32_bf16 v[36:39], v[182:185], v[222:225], v[36:39]
	v_mfma_f32_16x16x32_bf16 v[28:31], v[174:177], v[230:233], v[28:31]
	v_mfma_f32_16x16x32_bf16 v[20:23], v[182:185], v[230:233], v[20:23]
	v_mfma_f32_16x16x32_bf16 v[12:15], v[174:177], v[238:241], v[12:15]
	v_mfma_f32_16x16x32_bf16 v[4:7], v[182:185], v[238:241], v[4:7]
	s_setprio 0
	s_setprio 1
	v_mfma_f32_16x16x32_bf16 v[56:59], v[186:189], v[210:213], v[56:59]
	v_mfma_f32_16x16x32_bf16 v[48:51], v[194:197], v[210:213], v[48:51]
	v_mfma_f32_16x16x32_bf16 v[40:43], v[186:189], v[218:221], v[40:43]
	v_mfma_f32_16x16x32_bf16 v[32:35], v[194:197], v[218:221], v[32:35]
	v_mfma_f32_16x16x32_bf16 v[24:27], v[186:189], v[226:229], v[24:27]
	v_mfma_f32_16x16x32_bf16 v[16:19], v[194:197], v[226:229], v[16:19]
	v_mfma_f32_16x16x32_bf16 v[8:11], v[186:189], v[234:237], v[8:11]
	v_mfma_f32_16x16x32_bf16 v[0:3], v[194:197], v[234:237], v[0:3]
	v_mfma_f32_16x16x32_bf16 v[56:59], v[190:193], v[214:217], v[56:59]
	v_mfma_f32_16x16x32_bf16 v[48:51], v[198:201], v[214:217], v[48:51]
	v_mfma_f32_16x16x32_bf16 v[40:43], v[190:193], v[222:225], v[40:43]
	v_mfma_f32_16x16x32_bf16 v[32:35], v[198:201], v[222:225], v[32:35]
	v_mfma_f32_16x16x32_bf16 v[24:27], v[190:193], v[230:233], v[24:27]
	v_mfma_f32_16x16x32_bf16 v[16:19], v[198:201], v[230:233], v[16:19]
	v_mfma_f32_16x16x32_bf16 v[8:11], v[190:193], v[238:241], v[8:11]
	v_mfma_f32_16x16x32_bf16 v[0:3], v[198:201], v[238:241], v[0:3]
	s_setprio 0
	s_barrier
	s_add_i32 s55, 0, 0x18000
	s_add_i32 s56, 0, 0x1c000
	v_add_u32_e32 v182, s55, v129
	v_add_u32_e32 v198, s56, v129
	ds_read_b128 v[170:173], v182
	ds_read_b128 v[174:177], v182 offset:1024
	ds_read_b128 v[178:181], v182 offset:2048
	ds_read_b128 v[182:185], v182 offset:3072
	ds_read_b128 v[186:189], v198
	ds_read_b128 v[190:193], v198 offset:1024
	ds_read_b128 v[194:197], v198 offset:2048
	ds_read_b128 v[198:201], v198 offset:3072
	s_add_u32 s28, s28, 0x40000
	s_addc_u32 s29, s29, 0
	s_mov_b32 m0, s39
	v_lshl_add_u64 v[206:207], s[28:29], 0, v[136:137]
	ds_read_b128 v[210:213], v169 offset:32768
	ds_read_b128 v[214:217], v169 offset:33792
	ds_read_b128 v[218:221], v169 offset:34816
	ds_read_b128 v[222:225], v169 offset:35840
	ds_read_b128 v[226:229], v169 offset:36864
	ds_read_b128 v[230:233], v169 offset:37888
	ds_read_b128 v[234:237], v169 offset:38912
	ds_read_b128 v[238:241], v169 offset:39936
	global_load_lds_dwordx4 v[206:207], off
	v_lshl_add_u64 v[206:207], s[28:29], 0, v[132:133]
	s_mov_b32 m0, s40
	s_nop 0
	global_load_lds_dwordx4 v[206:207], off
	s_waitcnt vmcnt(8)
	s_waitcnt lgkmcnt(0)
	s_barrier
	s_setprio 1
	s_waitcnt lgkmcnt(0)
	v_mfma_f32_16x16x32_bf16 v[124:127], v[170:173], v[210:213], v[124:127]
	v_mfma_f32_16x16x32_bf16 v[116:119], v[178:181], v[210:213], v[116:119]
	v_mfma_f32_16x16x32_bf16 v[108:111], v[170:173], v[218:221], v[108:111]
	v_mfma_f32_16x16x32_bf16 v[100:103], v[178:181], v[218:221], v[100:103]
	v_mfma_f32_16x16x32_bf16 v[92:95], v[170:173], v[226:229], v[92:95]
	v_mfma_f32_16x16x32_bf16 v[84:87], v[178:181], v[226:229], v[84:87]
	v_mfma_f32_16x16x32_bf16 v[76:79], v[170:173], v[234:237], v[76:79]
	v_mfma_f32_16x16x32_bf16 v[68:71], v[178:181], v[234:237], v[68:71]
	v_mfma_f32_16x16x32_bf16 v[124:127], v[174:177], v[214:217], v[124:127]
	v_mfma_f32_16x16x32_bf16 v[116:119], v[182:185], v[214:217], v[116:119]
	v_mfma_f32_16x16x32_bf16 v[108:111], v[174:177], v[222:225], v[108:111]
	v_mfma_f32_16x16x32_bf16 v[100:103], v[182:185], v[222:225], v[100:103]
	v_mfma_f32_16x16x32_bf16 v[92:95], v[174:177], v[230:233], v[92:95]
	v_mfma_f32_16x16x32_bf16 v[84:87], v[182:185], v[230:233], v[84:87]
	v_mfma_f32_16x16x32_bf16 v[76:79], v[174:177], v[238:241], v[76:79]
	v_mfma_f32_16x16x32_bf16 v[68:71], v[182:185], v[238:241], v[68:71]
	s_setprio 0
	s_setprio 1
	v_mfma_f32_16x16x32_bf16 v[120:123], v[186:189], v[210:213], v[120:123]
	v_mfma_f32_16x16x32_bf16 v[112:115], v[194:197], v[210:213], v[112:115]
	v_mfma_f32_16x16x32_bf16 v[104:107], v[186:189], v[218:221], v[104:107]
	v_mfma_f32_16x16x32_bf16 v[96:99], v[194:197], v[218:221], v[96:99]
	v_mfma_f32_16x16x32_bf16 v[88:91], v[186:189], v[226:229], v[88:91]
	v_mfma_f32_16x16x32_bf16 v[80:83], v[194:197], v[226:229], v[80:83]
	v_mfma_f32_16x16x32_bf16 v[72:75], v[186:189], v[234:237], v[72:75]
	v_mfma_f32_16x16x32_bf16 v[64:67], v[194:197], v[234:237], v[64:67]
	v_mfma_f32_16x16x32_bf16 v[120:123], v[190:193], v[214:217], v[120:123]
	v_mfma_f32_16x16x32_bf16 v[112:115], v[198:201], v[214:217], v[112:115]
	v_mfma_f32_16x16x32_bf16 v[104:107], v[190:193], v[222:225], v[104:107]
	v_mfma_f32_16x16x32_bf16 v[96:99], v[198:201], v[222:225], v[96:99]
	v_mfma_f32_16x16x32_bf16 v[88:91], v[190:193], v[230:233], v[88:91]
	v_mfma_f32_16x16x32_bf16 v[80:83], v[198:201], v[230:233], v[80:83]
	v_mfma_f32_16x16x32_bf16 v[72:75], v[190:193], v[238:241], v[72:75]
	v_mfma_f32_16x16x32_bf16 v[64:67], v[198:201], v[238:241], v[64:67]
	s_setprio 0
	s_barrier
	s_add_u32 s28, s26, 0x8000
	s_addc_u32 s29, s27, 0
	s_add_i32 s55, s55, s35
	v_lshl_add_u64 v[206:207], s[28:29], 0, v[134:135]
	s_mov_b32 m0, s55
	ds_read_b128 v[210:213], v169 offset:49152
	ds_read_b128 v[214:217], v169 offset:50176
	ds_read_b128 v[218:221], v169 offset:51200
	ds_read_b128 v[222:225], v169 offset:52224
	ds_read_b128 v[226:229], v169 offset:53248
	ds_read_b128 v[230:233], v169 offset:54272
	ds_read_b128 v[234:237], v169 offset:55296
	ds_read_b128 v[238:241], v169 offset:56320
	global_load_lds_dwordx4 v[206:207], off
	s_add_i32 m0, s55, 0x2000
	s_add_u32 s26, s26, 0xc000
	v_lshl_add_u64 v[206:207], s[28:29], 0, v[130:131]
	s_addc_u32 s27, s27, 0
	s_add_i32 s28, s56, s35
	global_load_lds_dwordx4 v[206:207], off
	v_lshl_add_u64 v[206:207], s[26:27], 0, v[134:135]
	s_mov_b32 m0, s28
	v_lshl_add_u64 v[164:165], v[164:165], 0, s[6:7]
	global_load_lds_dwordx4 v[206:207], off
	v_lshl_add_u64 v[206:207], s[26:27], 0, v[130:131]
	s_add_i32 m0, s28, 0x2000
	s_nop 0
	global_load_lds_dwordx4 v[206:207], off
	s_mov_b32 m0, s45
	s_nop 0
	global_load_lds_dwordx4 v[164:165], off
	v_lshl_add_u64 v[164:165], v[204:205], 0, s[6:7]
	s_mov_b32 m0, s46
	s_nop 0
	global_load_lds_dwordx4 v[164:165], off
	s_waitcnt vmcnt(8)
	s_waitcnt lgkmcnt(0)
	s_barrier
	s_setprio 1
	s_waitcnt lgkmcnt(0)
	v_mfma_f32_16x16x32_bf16 v[60:63], v[170:173], v[210:213], v[60:63]
	v_mfma_f32_16x16x32_bf16 v[52:55], v[178:181], v[210:213], v[52:55]
	v_mfma_f32_16x16x32_bf16 v[44:47], v[170:173], v[218:221], v[44:47]
	v_mfma_f32_16x16x32_bf16 v[36:39], v[178:181], v[218:221], v[36:39]
	v_mfma_f32_16x16x32_bf16 v[28:31], v[170:173], v[226:229], v[28:31]
	v_mfma_f32_16x16x32_bf16 v[20:23], v[178:181], v[226:229], v[20:23]
	v_mfma_f32_16x16x32_bf16 v[12:15], v[170:173], v[234:237], v[12:15]
	v_mfma_f32_16x16x32_bf16 v[4:7], v[178:181], v[234:237], v[4:7]
	v_mfma_f32_16x16x32_bf16 v[60:63], v[174:177], v[214:217], v[60:63]
	v_mfma_f32_16x16x32_bf16 v[52:55], v[182:185], v[214:217], v[52:55]
	v_mfma_f32_16x16x32_bf16 v[44:47], v[174:177], v[222:225], v[44:47]
	v_mfma_f32_16x16x32_bf16 v[36:39], v[182:185], v[222:225], v[36:39]
	v_mfma_f32_16x16x32_bf16 v[28:31], v[174:177], v[230:233], v[28:31]
	v_mfma_f32_16x16x32_bf16 v[20:23], v[182:185], v[230:233], v[20:23]
	v_mfma_f32_16x16x32_bf16 v[12:15], v[174:177], v[238:241], v[12:15]
	v_mfma_f32_16x16x32_bf16 v[4:7], v[182:185], v[238:241], v[4:7]
	s_setprio 0
	s_setprio 1
	v_mfma_f32_16x16x32_bf16 v[56:59], v[186:189], v[210:213], v[56:59]
	v_mfma_f32_16x16x32_bf16 v[48:51], v[194:197], v[210:213], v[48:51]
	v_mfma_f32_16x16x32_bf16 v[40:43], v[186:189], v[218:221], v[40:43]
	v_mfma_f32_16x16x32_bf16 v[32:35], v[194:197], v[218:221], v[32:35]
	v_mfma_f32_16x16x32_bf16 v[24:27], v[186:189], v[226:229], v[24:27]
	v_mfma_f32_16x16x32_bf16 v[16:19], v[194:197], v[226:229], v[16:19]
	v_mfma_f32_16x16x32_bf16 v[8:11], v[186:189], v[234:237], v[8:11]
	v_mfma_f32_16x16x32_bf16 v[0:3], v[194:197], v[234:237], v[0:3]
	v_mfma_f32_16x16x32_bf16 v[56:59], v[190:193], v[214:217], v[56:59]
	v_mfma_f32_16x16x32_bf16 v[48:51], v[198:201], v[214:217], v[48:51]
	v_mfma_f32_16x16x32_bf16 v[40:43], v[190:193], v[222:225], v[40:43]
	v_mfma_f32_16x16x32_bf16 v[32:35], v[198:201], v[222:225], v[32:35]
	v_mfma_f32_16x16x32_bf16 v[24:27], v[190:193], v[230:233], v[24:27]
	v_mfma_f32_16x16x32_bf16 v[16:19], v[198:201], v[230:233], v[16:19]
	v_mfma_f32_16x16x32_bf16 v[8:11], v[190:193], v[238:241], v[8:11]
	v_mfma_f32_16x16x32_bf16 v[0:3], v[198:201], v[238:241], v[0:3]
	s_setprio 0
	s_add_i32 s54, s54, 2
	s_add_u32 s52, s52, 0x10000
	s_addc_u32 s53, s53, 0
	s_add_u32 s24, s24, 0x100
	s_addc_u32 s25, s25, 0
	s_cmp_gt_u32 s54, 13
	s_cbranch_scc0 .Lrot6
	s_barrier
	s_and_b64 vcc, exec, s[8:9]
	s_cbranch_vccz .LBB0_1256
	s_barrier

.LBB0_1480:
	s_add_u32 s68, s36, 0x10000
	s_addc_u32 s69, s37, 0
	s_add_u32 s36, s38, 0xc000
	v_mov_b32_e32 v0, 0
	s_addc_u32 s37, s39, 0
	s_mov_b32 s70, -2
	v_mov_b32_e32 v1, v0
	v_mov_b32_e32 v2, v0
	v_mov_b32_e32 v3, v0
	v_mov_b32_e32 v4, v0
	v_mov_b32_e32 v5, v0
	v_mov_b32_e32 v6, v0
	v_mov_b32_e32 v7, v0
	v_mov_b32_e32 v8, v0
	v_mov_b32_e32 v9, v0
	v_mov_b32_e32 v10, v0
	v_mov_b32_e32 v11, v0
	v_mov_b32_e32 v16, v0
	v_mov_b32_e32 v17, v0
	v_mov_b32_e32 v18, v0
	v_mov_b32_e32 v19, v0
	v_mov_b32_e32 v32, v0
	v_mov_b32_e32 v33, v0
	v_mov_b32_e32 v34, v0
	v_mov_b32_e32 v35, v0
	v_mov_b32_e32 v36, v0
	v_mov_b32_e32 v37, v0
	v_mov_b32_e32 v38, v0
	v_mov_b32_e32 v39, v0
	v_mov_b32_e32 v40, v0
	v_mov_b32_e32 v41, v0
	v_mov_b32_e32 v42, v0
	v_mov_b32_e32 v43, v0
	v_mov_b32_e32 v44, v0
	v_mov_b32_e32 v45, v0
	v_mov_b32_e32 v46, v0
	v_mov_b32_e32 v47, v0
	v_mov_b32_e32 v12, v0
	v_mov_b32_e32 v13, v0
	v_mov_b32_e32 v14, v0
	v_mov_b32_e32 v15, v0
	v_mov_b32_e32 v20, v0
	v_mov_b32_e32 v21, v0
	v_mov_b32_e32 v22, v0
	v_mov_b32_e32 v23, v0
	v_mov_b32_e32 v24, v0
	v_mov_b32_e32 v25, v0
	v_mov_b32_e32 v26, v0
	v_mov_b32_e32 v27, v0
	v_mov_b32_e32 v28, v0
	v_mov_b32_e32 v29, v0
	v_mov_b32_e32 v30, v0
	v_mov_b32_e32 v31, v0
	v_mov_b32_e32 v48, v0
	v_mov_b32_e32 v49, v0
	v_mov_b32_e32 v50, v0
	v_mov_b32_e32 v51, v0
	v_mov_b32_e32 v52, v0
	v_mov_b32_e32 v53, v0
	v_mov_b32_e32 v54, v0
	v_mov_b32_e32 v55, v0
	v_mov_b32_e32 v56, v0
	v_mov_b32_e32 v57, v0
	v_mov_b32_e32 v58, v0
	v_mov_b32_e32 v59, v0
	v_mov_b32_e32 v60, v0
	v_mov_b32_e32 v61, v0
	v_mov_b32_e32 v62, v0
	v_mov_b32_e32 v63, v0
	v_mov_b32_e32 v64, v0
	v_mov_b32_e32 v65, v0
	v_mov_b32_e32 v66, v0
	v_mov_b32_e32 v67, v0
	v_mov_b32_e32 v68, v0
	v_mov_b32_e32 v69, v0
	v_mov_b32_e32 v70, v0
	v_mov_b32_e32 v71, v0
	v_mov_b32_e32 v72, v0
	v_mov_b32_e32 v73, v0
	v_mov_b32_e32 v74, v0
	v_mov_b32_e32 v75, v0
	v_mov_b32_e32 v76, v0
	v_mov_b32_e32 v77, v0
	v_mov_b32_e32 v78, v0
	v_mov_b32_e32 v79, v0
	v_mov_b32_e32 v96, v0
	v_mov_b32_e32 v97, v0
	v_mov_b32_e32 v98, v0
	v_mov_b32_e32 v99, v0
	v_mov_b32_e32 v100, v0
	v_mov_b32_e32 v101, v0
	v_mov_b32_e32 v102, v0
	v_mov_b32_e32 v103, v0
	v_mov_b32_e32 v104, v0
	v_mov_b32_e32 v105, v0
	v_mov_b32_e32 v106, v0
	v_mov_b32_e32 v107, v0
	v_mov_b32_e32 v108, v0
	v_mov_b32_e32 v109, v0
	v_mov_b32_e32 v110, v0
	v_mov_b32_e32 v111, v0
	v_mov_b32_e32 v80, v0
	v_mov_b32_e32 v81, v0
	v_mov_b32_e32 v82, v0
	v_mov_b32_e32 v83, v0
	v_mov_b32_e32 v84, v0
	v_mov_b32_e32 v85, v0
	v_mov_b32_e32 v86, v0
	v_mov_b32_e32 v87, v0
	v_mov_b32_e32 v88, v0
	v_mov_b32_e32 v89, v0
	v_mov_b32_e32 v90, v0
	v_mov_b32_e32 v91, v0
	v_mov_b32_e32 v92, v0
	v_mov_b32_e32 v93, v0
	v_mov_b32_e32 v94, v0
	v_mov_b32_e32 v95, v0
	v_mov_b32_e32 v112, v0
	v_mov_b32_e32 v113, v0
	v_mov_b32_e32 v114, v0
	v_mov_b32_e32 v115, v0
	v_mov_b32_e32 v116, v0
	v_mov_b32_e32 v117, v0
	v_mov_b32_e32 v118, v0
	v_mov_b32_e32 v119, v0
	v_mov_b32_e32 v120, v0
	v_mov_b32_e32 v121, v0
	v_mov_b32_e32 v122, v0
	v_mov_b32_e32 v123, v0
	v_mov_b32_e32 v124, v0
	v_mov_b32_e32 v125, v0
	v_mov_b32_e32 v126, v0
	v_mov_b32_e32 v127, v0
	s_branch .LBB0_1481

.LBB0_1481:
	v_add_u32_e32 v168, s61, v182
	v_add_u32_e32 v204, s62, v182
	ds_read_b128 v[156:159], v168
	ds_read_b128 v[160:163], v168 offset:1024
	ds_read_b128 v[164:167], v168 offset:2048
	ds_read_b128 v[168:171], v168 offset:3072
	ds_read_b128 v[172:175], v204
	ds_read_b128 v[176:179], v204 offset:1024
	ds_read_b128 v[212:215], v204 offset:2048
	ds_read_b128 v[216:219], v204 offset:3072
	s_add_u32 s38, s36, 0x4000
	s_addc_u32 s39, s37, 0
	s_cmp_eq_u32 s70, 40
	s_cselect_b32 s42, s0, s38
	s_cselect_b32 s43, s1, s39
	s_cselect_b32 s40, s34, s68
	s_cselect_b32 s41, s35, s69
	s_add_u32 s38, s42, 0x8000
	s_addc_u32 s39, s43, 0
	v_lshl_add_u64 v[204:205], s[36:37], 0, v[150:151]
	s_add_i32 m0, s48, 0xc000
	ds_read_b128 v[220:223], v199
	ds_read_b128 v[224:227], v199 offset:1024
	ds_read_b128 v[228:231], v199 offset:2048
	ds_read_b128 v[232:235], v199 offset:3072
	ds_read_b128 v[236:239], v199 offset:4096
	ds_read_b128 v[240:243], v199 offset:5120
	ds_read_b128 v[244:247], v199 offset:6144
	ds_read_b128 v[248:251], v199 offset:7168
	global_load_lds_dwordx4 v[204:205], off
	v_lshl_add_u64 v[204:205], s[36:37], 0, v[148:149]
	s_add_i32 m0, s48, 0xe000
	s_nop 0
	global_load_lds_dwordx4 v[204:205], off
	s_waitcnt vmcnt(8)
	s_waitcnt lgkmcnt(0)
	s_barrier
	s_setprio 1
	s_waitcnt lgkmcnt(0)
	v_mfma_f32_16x16x32_bf16 v[124:127], v[156:159], v[220:223], v[124:127]
	v_mfma_f32_16x16x32_bf16 v[120:123], v[164:167], v[220:223], v[120:123]
	v_mfma_f32_16x16x32_bf16 v[116:119], v[156:159], v[228:231], v[116:119]
	v_mfma_f32_16x16x32_bf16 v[112:115], v[164:167], v[228:231], v[112:115]
	v_mfma_f32_16x16x32_bf16 v[92:95], v[156:159], v[236:239], v[92:95]
	v_mfma_f32_16x16x32_bf16 v[88:91], v[164:167], v[236:239], v[88:91]
	v_mfma_f32_16x16x32_bf16 v[84:87], v[156:159], v[244:247], v[84:87]
	v_mfma_f32_16x16x32_bf16 v[80:83], v[164:167], v[244:247], v[80:83]
	v_mfma_f32_16x16x32_bf16 v[124:127], v[160:163], v[224:227], v[124:127]
	v_mfma_f32_16x16x32_bf16 v[120:123], v[168:171], v[224:227], v[120:123]
	v_mfma_f32_16x16x32_bf16 v[116:119], v[160:163], v[232:235], v[116:119]
	v_mfma_f32_16x16x32_bf16 v[112:115], v[168:171], v[232:235], v[112:115]
	v_mfma_f32_16x16x32_bf16 v[92:95], v[160:163], v[240:243], v[92:95]
	v_mfma_f32_16x16x32_bf16 v[88:91], v[168:171], v[240:243], v[88:91]
	v_mfma_f32_16x16x32_bf16 v[84:87], v[160:163], v[248:251], v[84:87]
	v_mfma_f32_16x16x32_bf16 v[80:83], v[168:171], v[248:251], v[80:83]
	s_setprio 0
	s_setprio 1
	v_mfma_f32_16x16x32_bf16 v[108:111], v[172:175], v[220:223], v[108:111]
	v_mfma_f32_16x16x32_bf16 v[104:107], v[212:215], v[220:223], v[104:107]
	v_mfma_f32_16x16x32_bf16 v[100:103], v[172:175], v[228:231], v[100:103]
	v_mfma_f32_16x16x32_bf16 v[96:99], v[212:215], v[228:231], v[96:99]
	v_mfma_f32_16x16x32_bf16 v[76:79], v[172:175], v[236:239], v[76:79]
	v_mfma_f32_16x16x32_bf16 v[72:75], v[212:215], v[236:239], v[72:75]
	v_mfma_f32_16x16x32_bf16 v[68:71], v[172:175], v[244:247], v[68:71]
	v_mfma_f32_16x16x32_bf16 v[64:67], v[212:215], v[244:247], v[64:67]
	v_mfma_f32_16x16x32_bf16 v[108:111], v[176:179], v[224:227], v[108:111]
	v_mfma_f32_16x16x32_bf16 v[104:107], v[216:219], v[224:227], v[104:107]
	v_mfma_f32_16x16x32_bf16 v[100:103], v[176:179], v[232:235], v[100:103]
	v_mfma_f32_16x16x32_bf16 v[96:99], v[216:219], v[232:235], v[96:99]
	v_mfma_f32_16x16x32_bf16 v[76:79], v[176:179], v[240:243], v[76:79]
	v_mfma_f32_16x16x32_bf16 v[72:75], v[216:219], v[240:243], v[72:75]
	v_mfma_f32_16x16x32_bf16 v[68:71], v[176:179], v[248:251], v[68:71]
	v_mfma_f32_16x16x32_bf16 v[64:67], v[216:219], v[248:251], v[64:67]
	s_setprio 0
	s_barrier
	s_add_i32 s71, s61, s47
	v_lshl_add_u64 v[204:205], s[40:41], 0, v[128:129]
	s_mov_b32 m0, s71
	ds_read_b128 v[220:223], v199 offset:16384
	ds_read_b128 v[224:227], v199 offset:17408
	ds_read_b128 v[228:231], v199 offset:18432
	ds_read_b128 v[232:235], v199 offset:19456
	ds_read_b128 v[236:239], v199 offset:20480
	ds_read_b128 v[240:243], v199 offset:21504
	ds_read_b128 v[244:247], v199 offset:22528
	ds_read_b128 v[248:251], v199 offset:23552
	global_load_lds_dwordx4 v[204:205], off
	s_add_i32 m0, s71, 0x2000
	s_add_u32 s72, s40, 0x4000
	v_lshl_add_u64 v[204:205], s[40:41], 0, v[130:131]
	s_addc_u32 s73, s41, 0
	s_add_i32 s71, s62, s47
	global_load_lds_dwordx4 v[204:205], off
	v_lshl_add_u64 v[204:205], s[72:73], 0, v[128:129]
	s_mov_b32 m0, s71
	s_nop 0
	global_load_lds_dwordx4 v[204:205], off
	v_lshl_add_u64 v[204:205], s[72:73], 0, v[130:131]
	s_add_i32 m0, s71, 0x2000
	s_nop 0
	global_load_lds_dwordx4 v[204:205], off
	v_lshl_add_u64 v[204:205], s[42:43], 0, v[128:129]
	s_mov_b32 m0, s48
	s_nop 0
	global_load_lds_dwordx4 v[204:205], off
	v_lshl_add_u64 v[204:205], s[42:43], 0, v[130:131]
	s_mov_b32 m0, s49
	s_nop 0
	global_load_lds_dwordx4 v[204:205], off
	s_waitcnt vmcnt(8)
	s_waitcnt lgkmcnt(0)
	s_barrier
	s_setprio 1
	s_waitcnt lgkmcnt(0)
	v_mfma_f32_16x16x32_bf16 v[60:63], v[156:159], v[220:223], v[60:63]
	v_mfma_f32_16x16x32_bf16 v[56:59], v[164:167], v[220:223], v[56:59]
	v_mfma_f32_16x16x32_bf16 v[52:55], v[156:159], v[228:231], v[52:55]
	v_mfma_f32_16x16x32_bf16 v[48:51], v[164:167], v[228:231], v[48:51]
	v_mfma_f32_16x16x32_bf16 v[28:31], v[156:159], v[236:239], v[28:31]
	v_mfma_f32_16x16x32_bf16 v[24:27], v[164:167], v[236:239], v[24:27]
	v_mfma_f32_16x16x32_bf16 v[20:23], v[156:159], v[244:247], v[20:23]
	v_mfma_f32_16x16x32_bf16 v[12:15], v[164:167], v[244:247], v[12:15]
	v_mfma_f32_16x16x32_bf16 v[60:63], v[160:163], v[224:227], v[60:63]
	v_mfma_f32_16x16x32_bf16 v[56:59], v[168:171], v[224:227], v[56:59]
	v_mfma_f32_16x16x32_bf16 v[52:55], v[160:163], v[232:235], v[52:55]
	v_mfma_f32_16x16x32_bf16 v[48:51], v[168:171], v[232:235], v[48:51]
	v_mfma_f32_16x16x32_bf16 v[28:31], v[160:163], v[240:243], v[28:31]
	v_mfma_f32_16x16x32_bf16 v[24:27], v[168:171], v[240:243], v[24:27]
	v_mfma_f32_16x16x32_bf16 v[20:23], v[160:163], v[248:251], v[20:23]
	v_mfma_f32_16x16x32_bf16 v[12:15], v[168:171], v[248:251], v[12:15]
	s_setprio 0
	s_setprio 1
	v_mfma_f32_16x16x32_bf16 v[44:47], v[172:175], v[220:223], v[44:47]
	v_mfma_f32_16x16x32_bf16 v[40:43], v[212:215], v[220:223], v[40:43]
	v_mfma_f32_16x16x32_bf16 v[36:39], v[172:175], v[228:231], v[36:39]
	v_mfma_f32_16x16x32_bf16 v[32:35], v[212:215], v[228:231], v[32:35]
	v_mfma_f32_16x16x32_bf16 v[16:19], v[172:175], v[236:239], v[16:19]
	v_mfma_f32_16x16x32_bf16 v[8:11], v[212:215], v[236:239], v[8:11]
	v_mfma_f32_16x16x32_bf16 v[4:7], v[172:175], v[244:247], v[4:7]
	v_mfma_f32_16x16x32_bf16 v[0:3], v[212:215], v[244:247], v[0:3]
	v_mfma_f32_16x16x32_bf16 v[44:47], v[176:179], v[224:227], v[44:47]
	v_mfma_f32_16x16x32_bf16 v[40:43], v[216:219], v[224:227], v[40:43]
	v_mfma_f32_16x16x32_bf16 v[36:39], v[176:179], v[232:235], v[36:39]
	v_mfma_f32_16x16x32_bf16 v[32:35], v[216:219], v[232:235], v[32:35]
	v_mfma_f32_16x16x32_bf16 v[16:19], v[176:179], v[240:243], v[16:19]
	v_mfma_f32_16x16x32_bf16 v[8:11], v[216:219], v[240:243], v[8:11]
	v_mfma_f32_16x16x32_bf16 v[4:7], v[176:179], v[248:251], v[4:7]
	v_mfma_f32_16x16x32_bf16 v[0:3], v[216:219], v[248:251], v[0:3]
	s_setprio 0
	s_barrier
	s_add_i32 s71, 0, 0x18000
	s_add_i32 s72, 0, 0x1c000
	v_add_u32_e32 v168, s71, v182
	v_add_u32_e32 v204, s72, v182
	ds_read_b128 v[156:159], v168
	ds_read_b128 v[160:163], v168 offset:1024
	ds_read_b128 v[164:167], v168 offset:2048
	ds_read_b128 v[168:171], v168 offset:3072
	ds_read_b128 v[172:175], v204
	ds_read_b128 v[176:179], v204 offset:1024
	ds_read_b128 v[212:215], v204 offset:2048
	ds_read_b128 v[216:219], v204 offset:3072
	s_add_u32 s42, s42, 0x4000
	s_addc_u32 s43, s43, 0
	s_mov_b32 m0, s50
	v_lshl_add_u64 v[204:205], s[42:43], 0, v[128:129]
	ds_read_b128 v[220:223], v199 offset:32768
	ds_read_b128 v[224:227], v199 offset:33792
	ds_read_b128 v[228:231], v199 offset:34816
	ds_read_b128 v[232:235], v199 offset:35840
	ds_read_b128 v[236:239], v199 offset:36864
	ds_read_b128 v[240:243], v199 offset:37888
	ds_read_b128 v[244:247], v199 offset:38912
	ds_read_b128 v[248:251], v199 offset:39936
	global_load_lds_dwordx4 v[204:205], off
	v_lshl_add_u64 v[204:205], s[42:43], 0, v[130:131]
	s_mov_b32 m0, s51
	s_nop 0
	global_load_lds_dwordx4 v[204:205], off
	s_waitcnt vmcnt(8)
	s_waitcnt lgkmcnt(0)
	s_barrier
	s_setprio 1
	s_waitcnt lgkmcnt(0)
	v_mfma_f32_16x16x32_bf16 v[124:127], v[156:159], v[220:223], v[124:127]
	v_mfma_f32_16x16x32_bf16 v[120:123], v[164:167], v[220:223], v[120:123]
	v_mfma_f32_16x16x32_bf16 v[116:119], v[156:159], v[228:231], v[116:119]
	v_mfma_f32_16x16x32_bf16 v[112:115], v[164:167], v[228:231], v[112:115]
	v_mfma_f32_16x16x32_bf16 v[92:95], v[156:159], v[236:239], v[92:95]
	v_mfma_f32_16x16x32_bf16 v[88:91], v[164:167], v[236:239], v[88:91]
	v_mfma_f32_16x16x32_bf16 v[84:87], v[156:159], v[244:247], v[84:87]
	v_mfma_f32_16x16x32_bf16 v[80:83], v[164:167], v[244:247], v[80:83]
	v_mfma_f32_16x16x32_bf16 v[124:127], v[160:163], v[224:227], v[124:127]
	v_mfma_f32_16x16x32_bf16 v[120:123], v[168:171], v[224:227], v[120:123]
	v_mfma_f32_16x16x32_bf16 v[116:119], v[160:163], v[232:235], v[116:119]
	v_mfma_f32_16x16x32_bf16 v[112:115], v[168:171], v[232:235], v[112:115]
	v_mfma_f32_16x16x32_bf16 v[92:95], v[160:163], v[240:243], v[92:95]
	v_mfma_f32_16x16x32_bf16 v[88:91], v[168:171], v[240:243], v[88:91]
	v_mfma_f32_16x16x32_bf16 v[84:87], v[160:163], v[248:251], v[84:87]
	v_mfma_f32_16x16x32_bf16 v[80:83], v[168:171], v[248:251], v[80:83]
	s_setprio 0
	s_setprio 1
	v_mfma_f32_16x16x32_bf16 v[108:111], v[172:175], v[220:223], v[108:111]
	v_mfma_f32_16x16x32_bf16 v[104:107], v[212:215], v[220:223], v[104:107]
	v_mfma_f32_16x16x32_bf16 v[100:103], v[172:175], v[228:231], v[100:103]
	v_mfma_f32_16x16x32_bf16 v[96:99], v[212:215], v[228:231], v[96:99]
	v_mfma_f32_16x16x32_bf16 v[76:79], v[172:175], v[236:239], v[76:79]
	v_mfma_f32_16x16x32_bf16 v[72:75], v[212:215], v[236:239], v[72:75]
	v_mfma_f32_16x16x32_bf16 v[68:71], v[172:175], v[244:247], v[68:71]
	v_mfma_f32_16x16x32_bf16 v[64:67], v[212:215], v[244:247], v[64:67]
	v_mfma_f32_16x16x32_bf16 v[108:111], v[176:179], v[224:227], v[108:111]
	v_mfma_f32_16x16x32_bf16 v[104:107], v[216:219], v[224:227], v[104:107]
	v_mfma_f32_16x16x32_bf16 v[100:103], v[176:179], v[232:235], v[100:103]
	v_mfma_f32_16x16x32_bf16 v[96:99], v[216:219], v[232:235], v[96:99]
	v_mfma_f32_16x16x32_bf16 v[76:79], v[176:179], v[240:243], v[76:79]
	v_mfma_f32_16x16x32_bf16 v[72:75], v[216:219], v[240:243], v[72:75]
	v_mfma_f32_16x16x32_bf16 v[68:71], v[176:179], v[248:251], v[68:71]
	v_mfma_f32_16x16x32_bf16 v[64:67], v[216:219], v[248:251], v[64:67]
	s_setprio 0
	s_barrier
	s_add_u32 s42, s40, 0x8000
	s_addc_u32 s43, s41, 0
	s_add_i32 s71, s71, s47
	v_lshl_add_u64 v[204:205], s[42:43], 0, v[128:129]
	s_mov_b32 m0, s71
	ds_read_b128 v[220:223], v199 offset:49152
	ds_read_b128 v[224:227], v199 offset:50176
	ds_read_b128 v[228:231], v199 offset:51200
	ds_read_b128 v[232:235], v199 offset:52224
	ds_read_b128 v[236:239], v199 offset:53248
	ds_read_b128 v[240:243], v199 offset:54272
	ds_read_b128 v[244:247], v199 offset:55296
	ds_read_b128 v[248:251], v199 offset:56320
	global_load_lds_dwordx4 v[204:205], off
	s_add_i32 m0, s71, 0x2000
	s_add_u32 s40, s40, 0xc000
	v_lshl_add_u64 v[204:205], s[42:43], 0, v[130:131]
	s_addc_u32 s41, s41, 0
	s_add_i32 s42, s72, s47
	global_load_lds_dwordx4 v[204:205], off
	v_lshl_add_u64 v[204:205], s[40:41], 0, v[128:129]
	s_mov_b32 m0, s42
	s_nop 0
	global_load_lds_dwordx4 v[204:205], off
	v_lshl_add_u64 v[204:205], s[40:41], 0, v[130:131]
	s_add_i32 m0, s42, 0x2000
	s_nop 0
	global_load_lds_dwordx4 v[204:205], off
	v_lshl_add_u64 v[204:205], s[38:39], 0, v[128:129]
	s_mov_b32 m0, s57
	s_nop 0
	global_load_lds_dwordx4 v[204:205], off
	v_lshl_add_u64 v[204:205], s[38:39], 0, v[130:131]
	s_mov_b32 m0, s58
	s_nop 0
	global_load_lds_dwordx4 v[204:205], off
	s_waitcnt vmcnt(8)
	s_waitcnt lgkmcnt(0)
	s_barrier
	s_setprio 1
	s_waitcnt lgkmcnt(0)
	v_mfma_f32_16x16x32_bf16 v[60:63], v[156:159], v[220:223], v[60:63]
	v_mfma_f32_16x16x32_bf16 v[56:59], v[164:167], v[220:223], v[56:59]
	v_mfma_f32_16x16x32_bf16 v[52:55], v[156:159], v[228:231], v[52:55]
	v_mfma_f32_16x16x32_bf16 v[48:51], v[164:167], v[228:231], v[48:51]
	v_mfma_f32_16x16x32_bf16 v[28:31], v[156:159], v[236:239], v[28:31]
	v_mfma_f32_16x16x32_bf16 v[24:27], v[164:167], v[236:239], v[24:27]
	v_mfma_f32_16x16x32_bf16 v[20:23], v[156:159], v[244:247], v[20:23]
	v_mfma_f32_16x16x32_bf16 v[12:15], v[164:167], v[244:247], v[12:15]
	v_mfma_f32_16x16x32_bf16 v[60:63], v[160:163], v[224:227], v[60:63]
	v_mfma_f32_16x16x32_bf16 v[56:59], v[168:171], v[224:227], v[56:59]
	v_mfma_f32_16x16x32_bf16 v[52:55], v[160:163], v[232:235], v[52:55]
	v_mfma_f32_16x16x32_bf16 v[48:51], v[168:171], v[232:235], v[48:51]
	v_mfma_f32_16x16x32_bf16 v[28:31], v[160:163], v[240:243], v[28:31]
	v_mfma_f32_16x16x32_bf16 v[24:27], v[168:171], v[240:243], v[24:27]
	v_mfma_f32_16x16x32_bf16 v[20:23], v[160:163], v[248:251], v[20:23]
	v_mfma_f32_16x16x32_bf16 v[12:15], v[168:171], v[248:251], v[12:15]
	s_setprio 0
	s_setprio 1
	v_mfma_f32_16x16x32_bf16 v[44:47], v[172:175], v[220:223], v[44:47]
	v_mfma_f32_16x16x32_bf16 v[40:43], v[212:215], v[220:223], v[40:43]
	v_mfma_f32_16x16x32_bf16 v[36:39], v[172:175], v[228:231], v[36:39]
	v_mfma_f32_16x16x32_bf16 v[32:35], v[212:215], v[228:231], v[32:35]
	v_mfma_f32_16x16x32_bf16 v[16:19], v[172:175], v[236:239], v[16:19]
	v_mfma_f32_16x16x32_bf16 v[8:11], v[212:215], v[236:239], v[8:11]
	v_mfma_f32_16x16x32_bf16 v[4:7], v[172:175], v[244:247], v[4:7]
	v_mfma_f32_16x16x32_bf16 v[0:3], v[212:215], v[244:247], v[0:3]
	v_mfma_f32_16x16x32_bf16 v[44:47], v[176:179], v[224:227], v[44:47]
	v_mfma_f32_16x16x32_bf16 v[40:43], v[216:219], v[224:227], v[40:43]
	v_mfma_f32_16x16x32_bf16 v[36:39], v[176:179], v[232:235], v[36:39]
	v_mfma_f32_16x16x32_bf16 v[32:35], v[216:219], v[232:235], v[32:35]
	v_mfma_f32_16x16x32_bf16 v[16:19], v[176:179], v[240:243], v[16:19]
	v_mfma_f32_16x16x32_bf16 v[8:11], v[216:219], v[240:243], v[8:11]
	v_mfma_f32_16x16x32_bf16 v[4:7], v[176:179], v[248:251], v[4:7]
	v_mfma_f32_16x16x32_bf16 v[0:3], v[216:219], v[248:251], v[0:3]
	s_setprio 0
	s_add_i32 s70, s70, 2
	s_add_u32 s68, s68, 0x10000
	s_addc_u32 s69, s69, 0
	s_add_u32 s36, s36, 0x10000
	s_addc_u32 s37, s37, 0
	s_cmp_gt_u32 s70, 41
	s_cbranch_scc0 .Lrot7
	s_barrier
	s_and_b64 vcc, exec, s[18:19]
	s_cbranch_vccz .LBB0_1484
	s_barrier

.LBB0_1562:
	s_ashr_i32 s9, s8, 31
	s_lshl_b64 s[12:13], s[8:9], 19
	s_add_u32 s12, s28, s12
	s_addc_u32 s13, s29, s13
	s_cmp_eq_u32 s53, 2
	s_cselect_b32 s55, 0x40000, 0
	s_add_u32 s12, s12, s55
	s_addc_u32 s13, s13, 0
	s_and_b64 s[14:15], s[0:1], exec
	s_cselect_b32 s9, s13, s23
	s_cselect_b32 s45, s12, s22
	s_ashr_i32 s11, s10, 31
	s_lshl_b64 s[14:15], s[10:11], 19
	s_add_u32 s14, s30, s14
	s_addc_u32 s15, s31, s15
	s_and_b64 s[24:25], s[0:1], exec
	s_cselect_b32 s11, s15, s21
	s_cselect_b32 s46, s14, s20
	s_add_u32 s47, s20, 0x10000
	s_addc_u32 s48, s21, 0
	s_add_u32 s20, s22, 0x40080
	v_mov_b32_e32 v0, 0
	s_addc_u32 s21, s23, 0
	s_mov_b32 s49, -2
	v_mov_b32_e32 v1, v0
	v_mov_b32_e32 v2, v0
	v_mov_b32_e32 v3, v0
	v_mov_b32_e32 v8, v0
	v_mov_b32_e32 v9, v0
	v_mov_b32_e32 v10, v0
	v_mov_b32_e32 v11, v0
	v_mov_b32_e32 v16, v0
	v_mov_b32_e32 v17, v0
	v_mov_b32_e32 v18, v0
	v_mov_b32_e32 v19, v0
	v_mov_b32_e32 v24, v0
	v_mov_b32_e32 v25, v0
	v_mov_b32_e32 v26, v0
	v_mov_b32_e32 v27, v0
	v_mov_b32_e32 v32, v0
	v_mov_b32_e32 v33, v0
	v_mov_b32_e32 v34, v0
	v_mov_b32_e32 v35, v0
	v_mov_b32_e32 v40, v0
	v_mov_b32_e32 v41, v0
	v_mov_b32_e32 v42, v0
	v_mov_b32_e32 v43, v0
	v_mov_b32_e32 v48, v0
	v_mov_b32_e32 v49, v0
	v_mov_b32_e32 v50, v0
	v_mov_b32_e32 v51, v0
	v_mov_b32_e32 v56, v0
	v_mov_b32_e32 v57, v0
	v_mov_b32_e32 v58, v0
	v_mov_b32_e32 v59, v0
	v_mov_b32_e32 v4, v0
	v_mov_b32_e32 v5, v0
	v_mov_b32_e32 v6, v0
	v_mov_b32_e32 v7, v0
	v_mov_b32_e32 v12, v0
	v_mov_b32_e32 v13, v0
	v_mov_b32_e32 v14, v0
	v_mov_b32_e32 v15, v0
	v_mov_b32_e32 v20, v0
	v_mov_b32_e32 v21, v0
	v_mov_b32_e32 v22, v0
	v_mov_b32_e32 v23, v0
	v_mov_b32_e32 v28, v0
	v_mov_b32_e32 v29, v0
	v_mov_b32_e32 v30, v0
	v_mov_b32_e32 v31, v0
	v_mov_b32_e32 v36, v0
	v_mov_b32_e32 v37, v0
	v_mov_b32_e32 v38, v0
	v_mov_b32_e32 v39, v0
	v_mov_b32_e32 v44, v0
	v_mov_b32_e32 v45, v0
	v_mov_b32_e32 v46, v0
	v_mov_b32_e32 v47, v0
	v_mov_b32_e32 v52, v0
	v_mov_b32_e32 v53, v0
	v_mov_b32_e32 v54, v0
	v_mov_b32_e32 v55, v0
	v_mov_b32_e32 v60, v0
	v_mov_b32_e32 v61, v0
	v_mov_b32_e32 v62, v0
	v_mov_b32_e32 v63, v0
	v_mov_b32_e32 v64, v0
	v_mov_b32_e32 v65, v0
	v_mov_b32_e32 v66, v0
	v_mov_b32_e32 v67, v0
	v_mov_b32_e32 v72, v0
	v_mov_b32_e32 v73, v0
	v_mov_b32_e32 v74, v0
	v_mov_b32_e32 v75, v0
	v_mov_b32_e32 v80, v0
	v_mov_b32_e32 v81, v0
	v_mov_b32_e32 v82, v0
	v_mov_b32_e32 v83, v0
	v_mov_b32_e32 v88, v0
	v_mov_b32_e32 v89, v0
	v_mov_b32_e32 v90, v0
	v_mov_b32_e32 v91, v0
	v_mov_b32_e32 v96, v0
	v_mov_b32_e32 v97, v0
	v_mov_b32_e32 v98, v0
	v_mov_b32_e32 v99, v0
	v_mov_b32_e32 v104, v0
	v_mov_b32_e32 v105, v0
	v_mov_b32_e32 v106, v0
	v_mov_b32_e32 v107, v0
	v_mov_b32_e32 v112, v0
	v_mov_b32_e32 v113, v0
	v_mov_b32_e32 v114, v0
	v_mov_b32_e32 v115, v0
	v_mov_b32_e32 v120, v0
	v_mov_b32_e32 v121, v0
	v_mov_b32_e32 v122, v0
	v_mov_b32_e32 v123, v0
	v_mov_b32_e32 v68, v0
	v_mov_b32_e32 v69, v0
	v_mov_b32_e32 v70, v0
	v_mov_b32_e32 v71, v0
	v_mov_b32_e32 v76, v0
	v_mov_b32_e32 v77, v0
	v_mov_b32_e32 v78, v0
	v_mov_b32_e32 v79, v0
	v_mov_b32_e32 v84, v0
	v_mov_b32_e32 v85, v0
	v_mov_b32_e32 v86, v0
	v_mov_b32_e32 v87, v0
	v_mov_b32_e32 v92, v0
	v_mov_b32_e32 v93, v0
	v_mov_b32_e32 v94, v0
	v_mov_b32_e32 v95, v0
	v_mov_b32_e32 v100, v0
	v_mov_b32_e32 v101, v0
	v_mov_b32_e32 v102, v0
	v_mov_b32_e32 v103, v0
	v_mov_b32_e32 v108, v0
	v_mov_b32_e32 v109, v0
	v_mov_b32_e32 v110, v0
	v_mov_b32_e32 v111, v0
	v_mov_b32_e32 v116, v0
	v_mov_b32_e32 v117, v0
	v_mov_b32_e32 v118, v0
	v_mov_b32_e32 v119, v0
	v_mov_b32_e32 v124, v0
	v_mov_b32_e32 v125, v0
	v_mov_b32_e32 v126, v0
	v_mov_b32_e32 v127, v0
	s_branch .LBB0_1563
.Lrot8:
	s_barrier
.LBB0_1563:
	ds_read_b128 v[168:171], v165
	ds_read_b128 v[172:175], v165 offset:1024
	ds_read_b128 v[176:179], v165 offset:2048
	ds_read_b128 v[180:183], v165 offset:3072
	ds_read_b128 v[184:187], v166
	ds_read_b128 v[188:191], v166 offset:1024
	ds_read_b128 v[192:195], v166 offset:2048
	ds_read_b128 v[196:199], v166 offset:3072
	s_add_u32 s22, s20, 0xfffc0080
	s_addc_u32 s23, s21, -1
	s_cmp_eq_u32 s49, 12
	s_cselect_b32 s25, s9, s23
	s_cselect_b32 s24, s45, s22
	s_cselect_b32 s23, s11, s48
	s_cselect_b32 s22, s46, s47
	v_lshl_add_u64 v[162:163], s[20:21], 0, v[156:157]
	s_add_i32 m0, s17, 0xc000
	ds_read_b128 v[210:213], v167
	ds_read_b128 v[214:217], v167 offset:1024
	ds_read_b128 v[218:221], v167 offset:2048
	ds_read_b128 v[222:225], v167 offset:3072
	ds_read_b128 v[226:229], v167 offset:4096
	ds_read_b128 v[230:233], v167 offset:5120
	ds_read_b128 v[234:237], v167 offset:6144
	ds_read_b128 v[238:241], v167 offset:7168
	global_load_lds_dwordx4 v[162:163], off
	v_lshl_add_u64 v[162:163], s[20:21], 0, v[154:155]
	s_add_i32 m0, s17, 0xe000
	s_nop 0
	global_load_lds_dwordx4 v[162:163], off
	s_waitcnt vmcnt(8)
	s_waitcnt lgkmcnt(0)
	s_barrier
	s_setprio 1
	s_waitcnt lgkmcnt(0)
	v_mfma_f32_16x16x32_bf16 v[124:127], v[168:171], v[210:213], v[124:127]
	v_mfma_f32_16x16x32_bf16 v[116:119], v[176:179], v[210:213], v[116:119]
	v_mfma_f32_16x16x32_bf16 v[108:111], v[168:171], v[218:221], v[108:111]
	v_mfma_f32_16x16x32_bf16 v[100:103], v[176:179], v[218:221], v[100:103]
	v_mfma_f32_16x16x32_bf16 v[92:95], v[168:171], v[226:229], v[92:95]
	v_mfma_f32_16x16x32_bf16 v[84:87], v[176:179], v[226:229], v[84:87]
	v_mfma_f32_16x16x32_bf16 v[76:79], v[168:171], v[234:237], v[76:79]
	v_mfma_f32_16x16x32_bf16 v[68:71], v[176:179], v[234:237], v[68:71]
	v_mfma_f32_16x16x32_bf16 v[124:127], v[172:175], v[214:217], v[124:127]
	v_mfma_f32_16x16x32_bf16 v[116:119], v[180:183], v[214:217], v[116:119]
	v_mfma_f32_16x16x32_bf16 v[108:111], v[172:175], v[222:225], v[108:111]
	v_mfma_f32_16x16x32_bf16 v[100:103], v[180:183], v[222:225], v[100:103]
	v_mfma_f32_16x16x32_bf16 v[92:95], v[172:175], v[230:233], v[92:95]
	v_mfma_f32_16x16x32_bf16 v[84:87], v[180:183], v[230:233], v[84:87]
	v_mfma_f32_16x16x32_bf16 v[76:79], v[172:175], v[238:241], v[76:79]
	v_mfma_f32_16x16x32_bf16 v[68:71], v[180:183], v[238:241], v[68:71]
	s_setprio 0
	s_setprio 1
	v_mfma_f32_16x16x32_bf16 v[120:123], v[184:187], v[210:213], v[120:123]
	v_mfma_f32_16x16x32_bf16 v[112:115], v[192:195], v[210:213], v[112:115]
	v_mfma_f32_16x16x32_bf16 v[104:107], v[184:187], v[218:221], v[104:107]
	v_mfma_f32_16x16x32_bf16 v[96:99], v[192:195], v[218:221], v[96:99]
	v_mfma_f32_16x16x32_bf16 v[88:91], v[184:187], v[226:229], v[88:91]
	v_mfma_f32_16x16x32_bf16 v[80:83], v[192:195], v[226:229], v[80:83]
	v_mfma_f32_16x16x32_bf16 v[72:75], v[184:187], v[234:237], v[72:75]
	v_mfma_f32_16x16x32_bf16 v[64:67], v[192:195], v[234:237], v[64:67]
	v_mfma_f32_16x16x32_bf16 v[120:123], v[188:191], v[214:217], v[120:123]
	v_mfma_f32_16x16x32_bf16 v[112:115], v[196:199], v[214:217], v[112:115]
	v_mfma_f32_16x16x32_bf16 v[104:107], v[188:191], v[222:225], v[104:107]
	v_mfma_f32_16x16x32_bf16 v[96:99], v[196:199], v[222:225], v[96:99]
	v_mfma_f32_16x16x32_bf16 v[88:91], v[188:191], v[230:233], v[88:91]
	v_mfma_f32_16x16x32_bf16 v[80:83], v[196:199], v[230:233], v[80:83]
	v_mfma_f32_16x16x32_bf16 v[72:75], v[188:191], v[238:241], v[72:75]
	v_mfma_f32_16x16x32_bf16 v[64:67], v[196:199], v[238:241], v[64:67]
	s_setprio 0
	s_barrier
	s_add_i32 s50, s43, s33
	v_lshl_add_u64 v[162:163], s[22:23], 0, v[132:133]
	s_mov_b32 m0, s50
	s_cmp_lg_u32 s54, 0
	s_cbranch_scc1 .Lts0_skip1
	ds_read_b128 v[210:213], v167 offset:16384
	ds_read_b128 v[214:217], v167 offset:17408
	ds_read_b128 v[218:221], v167 offset:18432
	ds_read_b128 v[222:225], v167 offset:19456
	ds_read_b128 v[226:229], v167 offset:20480
	ds_read_b128 v[230:233], v167 offset:21504
	ds_read_b128 v[234:237], v167 offset:22528
	ds_read_b128 v[238:241], v167 offset:23552

.Lts0_skip2:
	s_add_i32 s49, s49, 2
	s_add_u32 s47, s47, 0x10000
	s_addc_u32 s48, s48, 0
	s_add_u32 s20, s20, 0x100
	s_addc_u32 s21, s21, 0
	s_cmp_gt_u32 s49, 13
	s_cbranch_scc0 .Lrot8
	s_barrier
	s_and_b64 vcc, exec, s[6:7]
	s_cbranch_vccz .LBB0_1566
	s_barrier

.LBB0_1644:
	s_add_u32 s45, s36, 0x10000
	s_addc_u32 s46, s37, 0
	s_add_u32 s36, s38, 0xc000
	v_mov_b32_e32 v0, 0
	s_addc_u32 s37, s39, 0
	s_mov_b32 s47, -2
	v_mov_b32_e32 v1, v0
	v_mov_b32_e32 v2, v0
	v_mov_b32_e32 v3, v0
	v_mov_b32_e32 v4, v0
	v_mov_b32_e32 v5, v0
	v_mov_b32_e32 v6, v0
	v_mov_b32_e32 v7, v0
	v_mov_b32_e32 v8, v0
	v_mov_b32_e32 v9, v0
	v_mov_b32_e32 v10, v0
	v_mov_b32_e32 v11, v0
	v_mov_b32_e32 v16, v0
	v_mov_b32_e32 v17, v0
	v_mov_b32_e32 v18, v0
	v_mov_b32_e32 v19, v0
	v_mov_b32_e32 v32, v0
	v_mov_b32_e32 v33, v0
	v_mov_b32_e32 v34, v0
	v_mov_b32_e32 v35, v0
	v_mov_b32_e32 v36, v0
	v_mov_b32_e32 v37, v0
	v_mov_b32_e32 v38, v0
	v_mov_b32_e32 v39, v0
	v_mov_b32_e32 v40, v0
	v_mov_b32_e32 v41, v0
	v_mov_b32_e32 v42, v0
	v_mov_b32_e32 v43, v0
	v_mov_b32_e32 v44, v0
	v_mov_b32_e32 v45, v0
	v_mov_b32_e32 v46, v0
	v_mov_b32_e32 v47, v0
	v_mov_b32_e32 v12, v0
	v_mov_b32_e32 v13, v0
	v_mov_b32_e32 v14, v0
	v_mov_b32_e32 v15, v0
	v_mov_b32_e32 v20, v0
	v_mov_b32_e32 v21, v0
	v_mov_b32_e32 v22, v0
	v_mov_b32_e32 v23, v0
	v_mov_b32_e32 v24, v0
	v_mov_b32_e32 v25, v0
	v_mov_b32_e32 v26, v0
	v_mov_b32_e32 v27, v0
	v_mov_b32_e32 v28, v0
	v_mov_b32_e32 v29, v0
	v_mov_b32_e32 v30, v0
	v_mov_b32_e32 v31, v0
	v_mov_b32_e32 v48, v0
	v_mov_b32_e32 v49, v0
	v_mov_b32_e32 v50, v0
	v_mov_b32_e32 v51, v0
	v_mov_b32_e32 v52, v0
	v_mov_b32_e32 v53, v0
	v_mov_b32_e32 v54, v0
	v_mov_b32_e32 v55, v0
	v_mov_b32_e32 v56, v0
	v_mov_b32_e32 v57, v0
	v_mov_b32_e32 v58, v0
	v_mov_b32_e32 v59, v0
	v_mov_b32_e32 v60, v0
	v_mov_b32_e32 v61, v0
	v_mov_b32_e32 v62, v0
	v_mov_b32_e32 v63, v0
	v_mov_b32_e32 v64, v0
	v_mov_b32_e32 v65, v0
	v_mov_b32_e32 v66, v0
	v_mov_b32_e32 v67, v0
	v_mov_b32_e32 v68, v0
	v_mov_b32_e32 v69, v0
	v_mov_b32_e32 v70, v0
	v_mov_b32_e32 v71, v0
	v_mov_b32_e32 v72, v0
	v_mov_b32_e32 v73, v0
	v_mov_b32_e32 v74, v0
	v_mov_b32_e32 v75, v0
	v_mov_b32_e32 v76, v0
	v_mov_b32_e32 v77, v0
	v_mov_b32_e32 v78, v0
	v_mov_b32_e32 v79, v0
	v_mov_b32_e32 v96, v0
	v_mov_b32_e32 v97, v0
	v_mov_b32_e32 v98, v0
	v_mov_b32_e32 v99, v0
	v_mov_b32_e32 v100, v0
	v_mov_b32_e32 v101, v0
	v_mov_b32_e32 v102, v0
	v_mov_b32_e32 v103, v0
	v_mov_b32_e32 v104, v0
	v_mov_b32_e32 v105, v0
	v_mov_b32_e32 v106, v0
	v_mov_b32_e32 v107, v0
	v_mov_b32_e32 v108, v0
	v_mov_b32_e32 v109, v0
	v_mov_b32_e32 v110, v0
	v_mov_b32_e32 v111, v0
	v_mov_b32_e32 v80, v0
	v_mov_b32_e32 v81, v0
	v_mov_b32_e32 v82, v0
	v_mov_b32_e32 v83, v0
	v_mov_b32_e32 v84, v0
	v_mov_b32_e32 v85, v0
	v_mov_b32_e32 v86, v0
	v_mov_b32_e32 v87, v0
	v_mov_b32_e32 v88, v0
	v_mov_b32_e32 v89, v0
	v_mov_b32_e32 v90, v0
	v_mov_b32_e32 v91, v0
	v_mov_b32_e32 v92, v0
	v_mov_b32_e32 v93, v0
	v_mov_b32_e32 v94, v0
	v_mov_b32_e32 v95, v0
	v_mov_b32_e32 v112, v0
	v_mov_b32_e32 v113, v0
	v_mov_b32_e32 v114, v0
	v_mov_b32_e32 v115, v0
	v_mov_b32_e32 v116, v0
	v_mov_b32_e32 v117, v0
	v_mov_b32_e32 v118, v0
	v_mov_b32_e32 v119, v0
	v_mov_b32_e32 v120, v0
	v_mov_b32_e32 v121, v0
	v_mov_b32_e32 v122, v0
	v_mov_b32_e32 v123, v0
	v_mov_b32_e32 v124, v0
	v_mov_b32_e32 v125, v0
	v_mov_b32_e32 v126, v0
	v_mov_b32_e32 v127, v0
	s_branch .LBB0_1645

.LBB0_1645:
	v_add_u32_e32 v168, s69, v182
	v_add_u32_e32 v204, s70, v182
	ds_read_b128 v[156:159], v168
	ds_read_b128 v[160:163], v168 offset:1024
	ds_read_b128 v[164:167], v168 offset:2048
	ds_read_b128 v[168:171], v168 offset:3072
	ds_read_b128 v[172:175], v204
	ds_read_b128 v[176:179], v204 offset:1024
	ds_read_b128 v[212:215], v204 offset:2048
	ds_read_b128 v[216:219], v204 offset:3072
	s_add_u32 s38, s36, 0x4000
	s_addc_u32 s39, s37, 0
	s_cmp_eq_u32 s47, 40
	s_cselect_b32 s42, s0, s38
	s_cselect_b32 s43, s1, s39
	s_cselect_b32 s40, s34, s45
	s_cselect_b32 s41, s35, s46
	s_add_u32 s38, s42, 0x8000
	s_addc_u32 s39, s43, 0
	v_lshl_add_u64 v[204:205], s[36:37], 0, v[150:151]
	s_add_i32 m0, s56, 0xc000
	ds_read_b128 v[220:223], v199
	ds_read_b128 v[224:227], v199 offset:1024
	ds_read_b128 v[228:231], v199 offset:2048
	ds_read_b128 v[232:235], v199 offset:3072
	ds_read_b128 v[236:239], v199 offset:4096
	ds_read_b128 v[240:243], v199 offset:5120
	ds_read_b128 v[244:247], v199 offset:6144
	ds_read_b128 v[248:251], v199 offset:7168
	global_load_lds_dwordx4 v[204:205], off
	v_lshl_add_u64 v[204:205], s[36:37], 0, v[148:149]
	s_add_i32 m0, s56, 0xe000
	s_nop 0
	global_load_lds_dwordx4 v[204:205], off
	s_waitcnt vmcnt(8)
	s_waitcnt lgkmcnt(0)
	s_barrier
	s_setprio 1
	s_waitcnt lgkmcnt(0)
	v_mfma_f32_16x16x32_bf16 v[124:127], v[156:159], v[220:223], v[124:127]
	v_mfma_f32_16x16x32_bf16 v[120:123], v[164:167], v[220:223], v[120:123]
	v_mfma_f32_16x16x32_bf16 v[116:119], v[156:159], v[228:231], v[116:119]
	v_mfma_f32_16x16x32_bf16 v[112:115], v[164:167], v[228:231], v[112:115]
	v_mfma_f32_16x16x32_bf16 v[92:95], v[156:159], v[236:239], v[92:95]
	v_mfma_f32_16x16x32_bf16 v[88:91], v[164:167], v[236:239], v[88:91]
	v_mfma_f32_16x16x32_bf16 v[84:87], v[156:159], v[244:247], v[84:87]
	v_mfma_f32_16x16x32_bf16 v[80:83], v[164:167], v[244:247], v[80:83]
	v_mfma_f32_16x16x32_bf16 v[124:127], v[160:163], v[224:227], v[124:127]
	v_mfma_f32_16x16x32_bf16 v[120:123], v[168:171], v[224:227], v[120:123]
	v_mfma_f32_16x16x32_bf16 v[116:119], v[160:163], v[232:235], v[116:119]
	v_mfma_f32_16x16x32_bf16 v[112:115], v[168:171], v[232:235], v[112:115]
	v_mfma_f32_16x16x32_bf16 v[92:95], v[160:163], v[240:243], v[92:95]
	v_mfma_f32_16x16x32_bf16 v[88:91], v[168:171], v[240:243], v[88:91]
	v_mfma_f32_16x16x32_bf16 v[84:87], v[160:163], v[248:251], v[84:87]
	v_mfma_f32_16x16x32_bf16 v[80:83], v[168:171], v[248:251], v[80:83]
	s_setprio 0
	s_setprio 1
	v_mfma_f32_16x16x32_bf16 v[108:111], v[172:175], v[220:223], v[108:111]
	v_mfma_f32_16x16x32_bf16 v[104:107], v[212:215], v[220:223], v[104:107]
	v_mfma_f32_16x16x32_bf16 v[100:103], v[172:175], v[228:231], v[100:103]
	v_mfma_f32_16x16x32_bf16 v[96:99], v[212:215], v[228:231], v[96:99]
	v_mfma_f32_16x16x32_bf16 v[76:79], v[172:175], v[236:239], v[76:79]
	v_mfma_f32_16x16x32_bf16 v[72:75], v[212:215], v[236:239], v[72:75]
	v_mfma_f32_16x16x32_bf16 v[68:71], v[172:175], v[244:247], v[68:71]
	v_mfma_f32_16x16x32_bf16 v[64:67], v[212:215], v[244:247], v[64:67]
	v_mfma_f32_16x16x32_bf16 v[108:111], v[176:179], v[224:227], v[108:111]
	v_mfma_f32_16x16x32_bf16 v[104:107], v[216:219], v[224:227], v[104:107]
	v_mfma_f32_16x16x32_bf16 v[100:103], v[176:179], v[232:235], v[100:103]
	v_mfma_f32_16x16x32_bf16 v[96:99], v[216:219], v[232:235], v[96:99]
	v_mfma_f32_16x16x32_bf16 v[76:79], v[176:179], v[240:243], v[76:79]
	v_mfma_f32_16x16x32_bf16 v[72:75], v[216:219], v[240:243], v[72:75]
	v_mfma_f32_16x16x32_bf16 v[68:71], v[176:179], v[248:251], v[68:71]
	v_mfma_f32_16x16x32_bf16 v[64:67], v[216:219], v[248:251], v[64:67]
	s_setprio 0
	s_barrier
	s_add_i32 s48, s69, s55
	v_lshl_add_u64 v[204:205], s[40:41], 0, v[128:129]
	s_mov_b32 m0, s48
	ds_read_b128 v[220:223], v199 offset:16384
	ds_read_b128 v[224:227], v199 offset:17408
	ds_read_b128 v[228:231], v199 offset:18432
	ds_read_b128 v[232:235], v199 offset:19456
	ds_read_b128 v[236:239], v199 offset:20480
	ds_read_b128 v[240:243], v199 offset:21504
	ds_read_b128 v[244:247], v199 offset:22528
	ds_read_b128 v[248:251], v199 offset:23552
	global_load_lds_dwordx4 v[204:205], off
	s_add_i32 m0, s48, 0x2000
	s_add_u32 s48, s40, 0x4000
	v_lshl_add_u64 v[204:205], s[40:41], 0, v[130:131]
	s_addc_u32 s49, s41, 0
	s_add_i32 s50, s70, s55
	global_load_lds_dwordx4 v[204:205], off
	v_lshl_add_u64 v[204:205], s[48:49], 0, v[128:129]
	s_mov_b32 m0, s50
	s_nop 0
	global_load_lds_dwordx4 v[204:205], off
	v_lshl_add_u64 v[204:205], s[48:49], 0, v[130:131]
	s_add_i32 m0, s50, 0x2000
	s_nop 0
	global_load_lds_dwordx4 v[204:205], off
	v_lshl_add_u64 v[204:205], s[42:43], 0, v[128:129]
	s_mov_b32 m0, s56
	s_nop 0
	global_load_lds_dwordx4 v[204:205], off
	v_lshl_add_u64 v[204:205], s[42:43], 0, v[130:131]
	s_mov_b32 m0, s57
	s_nop 0
	global_load_lds_dwordx4 v[204:205], off
	s_waitcnt vmcnt(8)
	s_waitcnt lgkmcnt(0)
	s_barrier
	s_setprio 1
	s_waitcnt lgkmcnt(0)
	v_mfma_f32_16x16x32_bf16 v[60:63], v[156:159], v[220:223], v[60:63]
	v_mfma_f32_16x16x32_bf16 v[56:59], v[164:167], v[220:223], v[56:59]
	v_mfma_f32_16x16x32_bf16 v[52:55], v[156:159], v[228:231], v[52:55]
	v_mfma_f32_16x16x32_bf16 v[48:51], v[164:167], v[228:231], v[48:51]
	v_mfma_f32_16x16x32_bf16 v[28:31], v[156:159], v[236:239], v[28:31]
	v_mfma_f32_16x16x32_bf16 v[24:27], v[164:167], v[236:239], v[24:27]
	v_mfma_f32_16x16x32_bf16 v[20:23], v[156:159], v[244:247], v[20:23]
	v_mfma_f32_16x16x32_bf16 v[12:15], v[164:167], v[244:247], v[12:15]
	v_mfma_f32_16x16x32_bf16 v[60:63], v[160:163], v[224:227], v[60:63]
	v_mfma_f32_16x16x32_bf16 v[56:59], v[168:171], v[224:227], v[56:59]
	v_mfma_f32_16x16x32_bf16 v[52:55], v[160:163], v[232:235], v[52:55]
	v_mfma_f32_16x16x32_bf16 v[48:51], v[168:171], v[232:235], v[48:51]
	v_mfma_f32_16x16x32_bf16 v[28:31], v[160:163], v[240:243], v[28:31]
	v_mfma_f32_16x16x32_bf16 v[24:27], v[168:171], v[240:243], v[24:27]
	v_mfma_f32_16x16x32_bf16 v[20:23], v[160:163], v[248:251], v[20:23]
	v_mfma_f32_16x16x32_bf16 v[12:15], v[168:171], v[248:251], v[12:15]
	s_setprio 0
	s_setprio 1
	v_mfma_f32_16x16x32_bf16 v[44:47], v[172:175], v[220:223], v[44:47]
	v_mfma_f32_16x16x32_bf16 v[40:43], v[212:215], v[220:223], v[40:43]
	v_mfma_f32_16x16x32_bf16 v[36:39], v[172:175], v[228:231], v[36:39]
	v_mfma_f32_16x16x32_bf16 v[32:35], v[212:215], v[228:231], v[32:35]
	v_mfma_f32_16x16x32_bf16 v[16:19], v[172:175], v[236:239], v[16:19]
	v_mfma_f32_16x16x32_bf16 v[8:11], v[212:215], v[236:239], v[8:11]
	v_mfma_f32_16x16x32_bf16 v[4:7], v[172:175], v[244:247], v[4:7]
	v_mfma_f32_16x16x32_bf16 v[0:3], v[212:215], v[244:247], v[0:3]
	v_mfma_f32_16x16x32_bf16 v[44:47], v[176:179], v[224:227], v[44:47]
	v_mfma_f32_16x16x32_bf16 v[40:43], v[216:219], v[224:227], v[40:43]
	v_mfma_f32_16x16x32_bf16 v[36:39], v[176:179], v[232:235], v[36:39]
	v_mfma_f32_16x16x32_bf16 v[32:35], v[216:219], v[232:235], v[32:35]
	v_mfma_f32_16x16x32_bf16 v[16:19], v[176:179], v[240:243], v[16:19]
	v_mfma_f32_16x16x32_bf16 v[8:11], v[216:219], v[240:243], v[8:11]
	v_mfma_f32_16x16x32_bf16 v[4:7], v[176:179], v[248:251], v[4:7]
	v_mfma_f32_16x16x32_bf16 v[0:3], v[216:219], v[248:251], v[0:3]
	s_setprio 0
	s_barrier
	s_add_i32 s48, 0, 0x18000
	s_add_i32 s49, 0, 0x1c000
	v_add_u32_e32 v168, s48, v182
	v_add_u32_e32 v204, s49, v182
	ds_read_b128 v[156:159], v168
	ds_read_b128 v[160:163], v168 offset:1024
	ds_read_b128 v[164:167], v168 offset:2048
	ds_read_b128 v[168:171], v168 offset:3072
	ds_read_b128 v[172:175], v204
	ds_read_b128 v[176:179], v204 offset:1024
	ds_read_b128 v[212:215], v204 offset:2048
	ds_read_b128 v[216:219], v204 offset:3072
	s_add_u32 s42, s42, 0x4000
	s_addc_u32 s43, s43, 0
	s_mov_b32 m0, s58
	v_lshl_add_u64 v[204:205], s[42:43], 0, v[128:129]
	ds_read_b128 v[220:223], v199 offset:32768
	ds_read_b128 v[224:227], v199 offset:33792
	ds_read_b128 v[228:231], v199 offset:34816
	ds_read_b128 v[232:235], v199 offset:35840
	ds_read_b128 v[236:239], v199 offset:36864
	ds_read_b128 v[240:243], v199 offset:37888
	ds_read_b128 v[244:247], v199 offset:38912
	ds_read_b128 v[248:251], v199 offset:39936
	global_load_lds_dwordx4 v[204:205], off
	v_lshl_add_u64 v[204:205], s[42:43], 0, v[130:131]
	s_mov_b32 m0, s59
	s_nop 0
	global_load_lds_dwordx4 v[204:205], off
	s_waitcnt vmcnt(8)
	s_waitcnt lgkmcnt(0)
	s_barrier
	s_setprio 1
	s_waitcnt lgkmcnt(0)
	v_mfma_f32_16x16x32_bf16 v[124:127], v[156:159], v[220:223], v[124:127]
	v_mfma_f32_16x16x32_bf16 v[120:123], v[164:167], v[220:223], v[120:123]
	v_mfma_f32_16x16x32_bf16 v[116:119], v[156:159], v[228:231], v[116:119]
	v_mfma_f32_16x16x32_bf16 v[112:115], v[164:167], v[228:231], v[112:115]
	v_mfma_f32_16x16x32_bf16 v[92:95], v[156:159], v[236:239], v[92:95]
	v_mfma_f32_16x16x32_bf16 v[88:91], v[164:167], v[236:239], v[88:91]
	v_mfma_f32_16x16x32_bf16 v[84:87], v[156:159], v[244:247], v[84:87]
	v_mfma_f32_16x16x32_bf16 v[80:83], v[164:167], v[244:247], v[80:83]
	v_mfma_f32_16x16x32_bf16 v[124:127], v[160:163], v[224:227], v[124:127]
	v_mfma_f32_16x16x32_bf16 v[120:123], v[168:171], v[224:227], v[120:123]
	v_mfma_f32_16x16x32_bf16 v[116:119], v[160:163], v[232:235], v[116:119]
	v_mfma_f32_16x16x32_bf16 v[112:115], v[168:171], v[232:235], v[112:115]
	v_mfma_f32_16x16x32_bf16 v[92:95], v[160:163], v[240:243], v[92:95]
	v_mfma_f32_16x16x32_bf16 v[88:91], v[168:171], v[240:243], v[88:91]
	v_mfma_f32_16x16x32_bf16 v[84:87], v[160:163], v[248:251], v[84:87]
	v_mfma_f32_16x16x32_bf16 v[80:83], v[168:171], v[248:251], v[80:83]
	s_setprio 0
	s_setprio 1
	v_mfma_f32_16x16x32_bf16 v[108:111], v[172:175], v[220:223], v[108:111]
	v_mfma_f32_16x16x32_bf16 v[104:107], v[212:215], v[220:223], v[104:107]
	v_mfma_f32_16x16x32_bf16 v[100:103], v[172:175], v[228:231], v[100:103]
	v_mfma_f32_16x16x32_bf16 v[96:99], v[212:215], v[228:231], v[96:99]
	v_mfma_f32_16x16x32_bf16 v[76:79], v[172:175], v[236:239], v[76:79]
	v_mfma_f32_16x16x32_bf16 v[72:75], v[212:215], v[236:239], v[72:75]
	v_mfma_f32_16x16x32_bf16 v[68:71], v[172:175], v[244:247], v[68:71]
	v_mfma_f32_16x16x32_bf16 v[64:67], v[212:215], v[244:247], v[64:67]
	v_mfma_f32_16x16x32_bf16 v[108:111], v[176:179], v[224:227], v[108:111]
	v_mfma_f32_16x16x32_bf16 v[104:107], v[216:219], v[224:227], v[104:107]
	v_mfma_f32_16x16x32_bf16 v[100:103], v[176:179], v[232:235], v[100:103]
	v_mfma_f32_16x16x32_bf16 v[96:99], v[216:219], v[232:235], v[96:99]
	v_mfma_f32_16x16x32_bf16 v[76:79], v[176:179], v[240:243], v[76:79]
	v_mfma_f32_16x16x32_bf16 v[72:75], v[216:219], v[240:243], v[72:75]
	v_mfma_f32_16x16x32_bf16 v[68:71], v[176:179], v[248:251], v[68:71]
	v_mfma_f32_16x16x32_bf16 v[64:67], v[216:219], v[248:251], v[64:67]
	s_setprio 0
	s_barrier
	s_add_u32 s42, s40, 0x8000
	s_addc_u32 s43, s41, 0
	s_add_i32 s48, s48, s55
	v_lshl_add_u64 v[204:205], s[42:43], 0, v[128:129]
	s_mov_b32 m0, s48
	ds_read_b128 v[220:223], v199 offset:49152
	ds_read_b128 v[224:227], v199 offset:50176
	ds_read_b128 v[228:231], v199 offset:51200
	ds_read_b128 v[232:235], v199 offset:52224
	ds_read_b128 v[236:239], v199 offset:53248
	ds_read_b128 v[240:243], v199 offset:54272
	ds_read_b128 v[244:247], v199 offset:55296
	ds_read_b128 v[248:251], v199 offset:56320
	global_load_lds_dwordx4 v[204:205], off
	s_add_i32 m0, s48, 0x2000
	s_add_u32 s40, s40, 0xc000
	v_lshl_add_u64 v[204:205], s[42:43], 0, v[130:131]
	s_addc_u32 s41, s41, 0
	s_add_i32 s42, s49, s55
	global_load_lds_dwordx4 v[204:205], off
	v_lshl_add_u64 v[204:205], s[40:41], 0, v[128:129]
	s_mov_b32 m0, s42
	s_nop 0
	global_load_lds_dwordx4 v[204:205], off
	v_lshl_add_u64 v[204:205], s[40:41], 0, v[130:131]
	s_add_i32 m0, s42, 0x2000
	s_nop 0
	global_load_lds_dwordx4 v[204:205], off
	v_lshl_add_u64 v[204:205], s[38:39], 0, v[128:129]
	s_mov_b32 m0, s65
	s_nop 0
	global_load_lds_dwordx4 v[204:205], off
	v_lshl_add_u64 v[204:205], s[38:39], 0, v[130:131]
	s_mov_b32 m0, s66
	s_nop 0
	global_load_lds_dwordx4 v[204:205], off
	s_waitcnt vmcnt(8)
	s_waitcnt lgkmcnt(0)
	s_barrier
	s_setprio 1
	s_waitcnt lgkmcnt(0)
	v_mfma_f32_16x16x32_bf16 v[60:63], v[156:159], v[220:223], v[60:63]
	v_mfma_f32_16x16x32_bf16 v[56:59], v[164:167], v[220:223], v[56:59]
	v_mfma_f32_16x16x32_bf16 v[52:55], v[156:159], v[228:231], v[52:55]
	v_mfma_f32_16x16x32_bf16 v[48:51], v[164:167], v[228:231], v[48:51]
	v_mfma_f32_16x16x32_bf16 v[28:31], v[156:159], v[236:239], v[28:31]
	v_mfma_f32_16x16x32_bf16 v[24:27], v[164:167], v[236:239], v[24:27]
	v_mfma_f32_16x16x32_bf16 v[20:23], v[156:159], v[244:247], v[20:23]
	v_mfma_f32_16x16x32_bf16 v[12:15], v[164:167], v[244:247], v[12:15]
	v_mfma_f32_16x16x32_bf16 v[60:63], v[160:163], v[224:227], v[60:63]
	v_mfma_f32_16x16x32_bf16 v[56:59], v[168:171], v[224:227], v[56:59]
	v_mfma_f32_16x16x32_bf16 v[52:55], v[160:163], v[232:235], v[52:55]
	v_mfma_f32_16x16x32_bf16 v[48:51], v[168:171], v[232:235], v[48:51]
	v_mfma_f32_16x16x32_bf16 v[28:31], v[160:163], v[240:243], v[28:31]
	v_mfma_f32_16x16x32_bf16 v[24:27], v[168:171], v[240:243], v[24:27]
	v_mfma_f32_16x16x32_bf16 v[20:23], v[160:163], v[248:251], v[20:23]
	v_mfma_f32_16x16x32_bf16 v[12:15], v[168:171], v[248:251], v[12:15]
	s_setprio 0
	s_setprio 1
	v_mfma_f32_16x16x32_bf16 v[44:47], v[172:175], v[220:223], v[44:47]
	v_mfma_f32_16x16x32_bf16 v[40:43], v[212:215], v[220:223], v[40:43]
	v_mfma_f32_16x16x32_bf16 v[36:39], v[172:175], v[228:231], v[36:39]
	v_mfma_f32_16x16x32_bf16 v[32:35], v[212:215], v[228:231], v[32:35]
	v_mfma_f32_16x16x32_bf16 v[16:19], v[172:175], v[236:239], v[16:19]
	v_mfma_f32_16x16x32_bf16 v[8:11], v[212:215], v[236:239], v[8:11]
	v_mfma_f32_16x16x32_bf16 v[4:7], v[172:175], v[244:247], v[4:7]
	v_mfma_f32_16x16x32_bf16 v[0:3], v[212:215], v[244:247], v[0:3]
	v_mfma_f32_16x16x32_bf16 v[44:47], v[176:179], v[224:227], v[44:47]
	v_mfma_f32_16x16x32_bf16 v[40:43], v[216:219], v[224:227], v[40:43]
	v_mfma_f32_16x16x32_bf16 v[36:39], v[176:179], v[232:235], v[36:39]
	v_mfma_f32_16x16x32_bf16 v[32:35], v[216:219], v[232:235], v[32:35]
	v_mfma_f32_16x16x32_bf16 v[16:19], v[176:179], v[240:243], v[16:19]
	v_mfma_f32_16x16x32_bf16 v[8:11], v[216:219], v[240:243], v[8:11]
	v_mfma_f32_16x16x32_bf16 v[4:7], v[176:179], v[248:251], v[4:7]
	v_mfma_f32_16x16x32_bf16 v[0:3], v[216:219], v[248:251], v[0:3]
	s_setprio 0
	s_add_i32 s47, s47, 2
	s_add_u32 s45, s45, 0x10000
	s_addc_u32 s46, s46, 0
	s_add_u32 s36, s36, 0x10000
	s_addc_u32 s37, s37, 0
	s_cmp_gt_u32 s47, 41
	s_cbranch_scc0 .Lrot9
	s_barrier
	s_and_b64 vcc, exec, s[2:3]
	s_cbranch_vccz .LBB0_1648
	s_barrier

.LBB0_1728:
	s_ashr_i32 s19, s18, 31
	s_lshl_b64 s[22:23], s[18:19], 19
	s_add_u32 s22, s37, s22
	s_addc_u32 s23, s38, s23
	s_and_b64 s[24:25], s[4:5], exec
	s_cselect_b32 s1, s23, s27
	s_cselect_b32 s19, s22, s26
	s_ashr_i32 s21, s20, 31
	s_lshl_b64 s[24:25], s[20:21], 19
	s_add_u32 s24, s39, s24
	s_addc_u32 s25, s40, s25
	s_and_b64 s[28:29], s[4:5], exec
	s_cselect_b32 s21, s25, s7
	s_cselect_b32 s30, s24, s6
	s_add_u32 s31, s6, 0x10000
	s_addc_u32 s34, s7, 0
	s_add_u32 s6, s26, 0x40080
	v_mov_b32_e32 v0, 0
	s_addc_u32 s7, s27, 0
	s_mov_b32 s35, -2
	v_mov_b32_e32 v1, v0
	v_mov_b32_e32 v2, v0
	v_mov_b32_e32 v3, v0
	v_mov_b32_e32 v4, v0
	v_mov_b32_e32 v5, v0
	v_mov_b32_e32 v6, v0
	v_mov_b32_e32 v7, v0
	v_mov_b32_e32 v8, v0
	v_mov_b32_e32 v9, v0
	v_mov_b32_e32 v10, v0
	v_mov_b32_e32 v11, v0
	v_mov_b32_e32 v12, v0
	v_mov_b32_e32 v13, v0
	v_mov_b32_e32 v14, v0
	v_mov_b32_e32 v15, v0
	v_mov_b32_e32 v16, v0
	v_mov_b32_e32 v17, v0
	v_mov_b32_e32 v18, v0
	v_mov_b32_e32 v19, v0
	v_mov_b32_e32 v20, v0
	v_mov_b32_e32 v21, v0
	v_mov_b32_e32 v22, v0
	v_mov_b32_e32 v23, v0
	v_mov_b32_e32 v24, v0
	v_mov_b32_e32 v25, v0
	v_mov_b32_e32 v26, v0
	v_mov_b32_e32 v27, v0
	v_mov_b32_e32 v28, v0
	v_mov_b32_e32 v29, v0
	v_mov_b32_e32 v30, v0
	v_mov_b32_e32 v31, v0
	v_mov_b32_e32 v64, v0
	v_mov_b32_e32 v65, v0
	v_mov_b32_e32 v66, v0
	v_mov_b32_e32 v67, v0
	v_mov_b32_e32 v68, v0
	v_mov_b32_e32 v69, v0
	v_mov_b32_e32 v70, v0
	v_mov_b32_e32 v71, v0
	v_mov_b32_e32 v72, v0
	v_mov_b32_e32 v73, v0
	v_mov_b32_e32 v74, v0
	v_mov_b32_e32 v75, v0
	v_mov_b32_e32 v76, v0
	v_mov_b32_e32 v77, v0
	v_mov_b32_e32 v78, v0
	v_mov_b32_e32 v79, v0
	v_mov_b32_e32 v80, v0
	v_mov_b32_e32 v81, v0
	v_mov_b32_e32 v82, v0
	v_mov_b32_e32 v83, v0
	v_mov_b32_e32 v84, v0
	v_mov_b32_e32 v85, v0
	v_mov_b32_e32 v86, v0
	v_mov_b32_e32 v87, v0
	v_mov_b32_e32 v88, v0
	v_mov_b32_e32 v89, v0
	v_mov_b32_e32 v90, v0
	v_mov_b32_e32 v91, v0
	v_mov_b32_e32 v92, v0
	v_mov_b32_e32 v93, v0
	v_mov_b32_e32 v94, v0
	v_mov_b32_e32 v95, v0
	v_mov_b32_e32 v32, v0
	v_mov_b32_e32 v33, v0
	v_mov_b32_e32 v34, v0
	v_mov_b32_e32 v35, v0
	v_mov_b32_e32 v36, v0
	v_mov_b32_e32 v37, v0
	v_mov_b32_e32 v38, v0
	v_mov_b32_e32 v39, v0
	v_mov_b32_e32 v40, v0
	v_mov_b32_e32 v41, v0
	v_mov_b32_e32 v42, v0
	v_mov_b32_e32 v43, v0
	v_mov_b32_e32 v44, v0
	v_mov_b32_e32 v45, v0
	v_mov_b32_e32 v46, v0
	v_mov_b32_e32 v47, v0
	v_mov_b32_e32 v48, v0
	v_mov_b32_e32 v49, v0
	v_mov_b32_e32 v50, v0
	v_mov_b32_e32 v51, v0
	v_mov_b32_e32 v52, v0
	v_mov_b32_e32 v53, v0
	v_mov_b32_e32 v54, v0
	v_mov_b32_e32 v55, v0
	v_mov_b32_e32 v56, v0
	v_mov_b32_e32 v57, v0
	v_mov_b32_e32 v58, v0
	v_mov_b32_e32 v59, v0
	v_mov_b32_e32 v60, v0
	v_mov_b32_e32 v61, v0
	v_mov_b32_e32 v62, v0
	v_mov_b32_e32 v63, v0
	v_mov_b32_e32 v96, v0
	v_mov_b32_e32 v97, v0
	v_mov_b32_e32 v98, v0
	v_mov_b32_e32 v99, v0
	v_mov_b32_e32 v100, v0
	v_mov_b32_e32 v101, v0
	v_mov_b32_e32 v102, v0
	v_mov_b32_e32 v103, v0
	v_mov_b32_e32 v104, v0
	v_mov_b32_e32 v105, v0
	v_mov_b32_e32 v106, v0
	v_mov_b32_e32 v107, v0
	v_mov_b32_e32 v108, v0
	v_mov_b32_e32 v109, v0
	v_mov_b32_e32 v110, v0
	v_mov_b32_e32 v111, v0
	v_mov_b32_e32 v112, v0
	v_mov_b32_e32 v113, v0
	v_mov_b32_e32 v114, v0
	v_mov_b32_e32 v115, v0
	v_mov_b32_e32 v116, v0
	v_mov_b32_e32 v117, v0
	v_mov_b32_e32 v118, v0
	v_mov_b32_e32 v119, v0
	v_mov_b32_e32 v120, v0
	v_mov_b32_e32 v121, v0
	v_mov_b32_e32 v122, v0
	v_mov_b32_e32 v123, v0
	v_mov_b32_e32 v124, v0
	v_mov_b32_e32 v125, v0
	v_mov_b32_e32 v126, v0
	v_mov_b32_e32 v127, v0
	s_branch .LBB0_1729

.LBB0_1729:
	ds_read_b128 v[128:131], v210
	ds_read_b128 v[132:135], v210 offset:1024
	ds_read_b128 v[136:139], v210 offset:2048
	ds_read_b128 v[140:143], v210 offset:3072
	ds_read_b128 v[144:147], v211
	ds_read_b128 v[148:151], v211 offset:1024
	ds_read_b128 v[152:155], v211 offset:2048
	ds_read_b128 v[156:159], v211 offset:3072
	s_add_u32 s26, s6, 0xfffc0080
	s_addc_u32 s27, s7, -1
	s_cmp_eq_u32 s35, 12
	s_cselect_b32 s29, s1, s27
	s_cselect_b32 s28, s19, s26
	s_cselect_b32 s27, s21, s34
	s_cselect_b32 s26, s30, s31
	v_lshl_add_u64 v[198:199], s[6:7], 0, v[188:189]
	s_add_i32 m0, s42, 0xc000
	ds_read_b128 v[160:163], v212
	ds_read_b128 v[164:167], v212 offset:1024
	ds_read_b128 v[194:197], v212 offset:2048
	ds_read_b128 v[214:217], v212 offset:3072
	ds_read_b128 v[218:221], v212 offset:4096
	ds_read_b128 v[222:225], v212 offset:5120
	ds_read_b128 v[226:229], v212 offset:6144
	ds_read_b128 v[230:233], v212 offset:7168
	global_load_lds_dwordx4 v[198:199], off
	v_lshl_add_u64 v[198:199], s[6:7], 0, v[186:187]
	s_add_i32 m0, s42, 0xe000
	s_nop 0
	global_load_lds_dwordx4 v[198:199], off
	s_waitcnt vmcnt(8)
	s_waitcnt lgkmcnt(0)
	s_barrier
	s_setprio 1
	s_waitcnt lgkmcnt(0)
	v_mfma_f32_16x16x32_bf16 v[124:127], v[128:131], v[160:163], v[124:127]
	v_mfma_f32_16x16x32_bf16 v[120:123], v[136:139], v[160:163], v[120:123]
	v_mfma_f32_16x16x32_bf16 v[116:119], v[128:131], v[194:197], v[116:119]
	v_mfma_f32_16x16x32_bf16 v[112:115], v[136:139], v[194:197], v[112:115]
	v_mfma_f32_16x16x32_bf16 v[108:111], v[128:131], v[218:221], v[108:111]
	v_mfma_f32_16x16x32_bf16 v[104:107], v[136:139], v[218:221], v[104:107]
	v_mfma_f32_16x16x32_bf16 v[100:103], v[128:131], v[226:229], v[100:103]
	v_mfma_f32_16x16x32_bf16 v[96:99], v[136:139], v[226:229], v[96:99]
	v_mfma_f32_16x16x32_bf16 v[124:127], v[132:135], v[164:167], v[124:127]
	v_mfma_f32_16x16x32_bf16 v[120:123], v[140:143], v[164:167], v[120:123]
	v_mfma_f32_16x16x32_bf16 v[116:119], v[132:135], v[214:217], v[116:119]
	v_mfma_f32_16x16x32_bf16 v[112:115], v[140:143], v[214:217], v[112:115]
	v_mfma_f32_16x16x32_bf16 v[108:111], v[132:135], v[222:225], v[108:111]
	v_mfma_f32_16x16x32_bf16 v[104:107], v[140:143], v[222:225], v[104:107]
	v_mfma_f32_16x16x32_bf16 v[100:103], v[132:135], v[230:233], v[100:103]
	v_mfma_f32_16x16x32_bf16 v[96:99], v[140:143], v[230:233], v[96:99]
	s_setprio 0
	s_setprio 1
	v_mfma_f32_16x16x32_bf16 v[60:63], v[144:147], v[160:163], v[60:63]
	v_mfma_f32_16x16x32_bf16 v[56:59], v[152:155], v[160:163], v[56:59]
	v_mfma_f32_16x16x32_bf16 v[52:55], v[144:147], v[194:197], v[52:55]
	v_mfma_f32_16x16x32_bf16 v[48:51], v[152:155], v[194:197], v[48:51]
	v_mfma_f32_16x16x32_bf16 v[44:47], v[144:147], v[218:221], v[44:47]
	v_mfma_f32_16x16x32_bf16 v[40:43], v[152:155], v[218:221], v[40:43]
	v_mfma_f32_16x16x32_bf16 v[36:39], v[144:147], v[226:229], v[36:39]
	v_mfma_f32_16x16x32_bf16 v[32:35], v[152:155], v[226:229], v[32:35]
	v_mfma_f32_16x16x32_bf16 v[60:63], v[148:151], v[164:167], v[60:63]
	v_mfma_f32_16x16x32_bf16 v[56:59], v[156:159], v[164:167], v[56:59]
	v_mfma_f32_16x16x32_bf16 v[52:55], v[148:151], v[214:217], v[52:55]
	v_mfma_f32_16x16x32_bf16 v[48:51], v[156:159], v[214:217], v[48:51]
	v_mfma_f32_16x16x32_bf16 v[44:47], v[148:151], v[222:225], v[44:47]
	v_mfma_f32_16x16x32_bf16 v[40:43], v[156:159], v[222:225], v[40:43]
	v_mfma_f32_16x16x32_bf16 v[36:39], v[148:151], v[230:233], v[36:39]
	v_mfma_f32_16x16x32_bf16 v[32:35], v[156:159], v[230:233], v[32:35]
	s_setprio 0
	s_barrier
	s_add_i32 s61, s56, s41
	v_lshl_add_u64 v[198:199], s[26:27], 0, v[170:171]
	s_mov_b32 m0, s61
	ds_read_b128 v[160:163], v212 offset:16384
	ds_read_b128 v[164:167], v212 offset:17408
	ds_read_b128 v[194:197], v212 offset:18432
	ds_read_b128 v[214:217], v212 offset:19456
	ds_read_b128 v[218:221], v212 offset:20480
	ds_read_b128 v[222:225], v212 offset:21504
	ds_read_b128 v[226:229], v212 offset:22528
	ds_read_b128 v[230:233], v212 offset:23552
	global_load_lds_dwordx4 v[198:199], off
	s_add_i32 m0, s61, 0x2000
	s_add_u32 s62, s26, 0x4000
	v_lshl_add_u64 v[198:199], s[26:27], 0, v[174:175]
	s_addc_u32 s63, s27, 0
	s_add_i32 s61, s57, s41
	global_load_lds_dwordx4 v[198:199], off
	v_lshl_add_u64 v[198:199], s[62:63], 0, v[170:171]
	s_mov_b32 m0, s61
	v_lshl_add_u64 v[204:205], s[28:29], 0, v[172:173]
	global_load_lds_dwordx4 v[198:199], off
	v_lshl_add_u64 v[198:199], s[62:63], 0, v[174:175]
	s_add_i32 m0, s61, 0x2000
	s_nop 0
	global_load_lds_dwordx4 v[198:199], off
	v_lshl_add_u64 v[198:199], s[28:29], 0, v[168:169]
	s_mov_b32 m0, s42
	s_nop 0
	global_load_lds_dwordx4 v[198:199], off
	s_mov_b32 m0, s43
	s_nop 0
	global_load_lds_dwordx4 v[204:205], off
	s_waitcnt vmcnt(8)
	s_waitcnt lgkmcnt(0)
	s_barrier
	s_setprio 1
	s_waitcnt lgkmcnt(0)
	v_mfma_f32_16x16x32_bf16 v[92:95], v[128:131], v[160:163], v[92:95]
	v_mfma_f32_16x16x32_bf16 v[88:91], v[136:139], v[160:163], v[88:91]
	v_mfma_f32_16x16x32_bf16 v[84:87], v[128:131], v[194:197], v[84:87]
	v_mfma_f32_16x16x32_bf16 v[80:83], v[136:139], v[194:197], v[80:83]
	v_mfma_f32_16x16x32_bf16 v[76:79], v[128:131], v[218:221], v[76:79]
	v_mfma_f32_16x16x32_bf16 v[72:75], v[136:139], v[218:221], v[72:75]
	v_mfma_f32_16x16x32_bf16 v[68:71], v[128:131], v[226:229], v[68:71]
	v_mfma_f32_16x16x32_bf16 v[64:67], v[136:139], v[226:229], v[64:67]
	v_mfma_f32_16x16x32_bf16 v[92:95], v[132:135], v[164:167], v[92:95]
	v_mfma_f32_16x16x32_bf16 v[88:91], v[140:143], v[164:167], v[88:91]
	v_mfma_f32_16x16x32_bf16 v[84:87], v[132:135], v[214:217], v[84:87]
	v_mfma_f32_16x16x32_bf16 v[80:83], v[140:143], v[214:217], v[80:83]
	v_mfma_f32_16x16x32_bf16 v[76:79], v[132:135], v[222:225], v[76:79]
	v_mfma_f32_16x16x32_bf16 v[72:75], v[140:143], v[222:225], v[72:75]
	v_mfma_f32_16x16x32_bf16 v[68:71], v[132:135], v[230:233], v[68:71]
	v_mfma_f32_16x16x32_bf16 v[64:67], v[140:143], v[230:233], v[64:67]
	s_setprio 0
	s_setprio 1
	v_mfma_f32_16x16x32_bf16 v[28:31], v[144:147], v[160:163], v[28:31]
	v_mfma_f32_16x16x32_bf16 v[24:27], v[152:155], v[160:163], v[24:27]
	v_mfma_f32_16x16x32_bf16 v[20:23], v[144:147], v[194:197], v[20:23]
	v_mfma_f32_16x16x32_bf16 v[16:19], v[152:155], v[194:197], v[16:19]
	v_mfma_f32_16x16x32_bf16 v[12:15], v[144:147], v[218:221], v[12:15]
	v_mfma_f32_16x16x32_bf16 v[8:11], v[152:155], v[218:221], v[8:11]
	v_mfma_f32_16x16x32_bf16 v[4:7], v[144:147], v[226:229], v[4:7]
	v_mfma_f32_16x16x32_bf16 v[0:3], v[152:155], v[226:229], v[0:3]
	v_mfma_f32_16x16x32_bf16 v[28:31], v[148:151], v[164:167], v[28:31]
	v_mfma_f32_16x16x32_bf16 v[24:27], v[156:159], v[164:167], v[24:27]
	v_mfma_f32_16x16x32_bf16 v[20:23], v[148:151], v[214:217], v[20:23]
	v_mfma_f32_16x16x32_bf16 v[16:19], v[156:159], v[214:217], v[16:19]
	v_mfma_f32_16x16x32_bf16 v[12:15], v[148:151], v[222:225], v[12:15]
	v_mfma_f32_16x16x32_bf16 v[8:11], v[156:159], v[222:225], v[8:11]
	v_mfma_f32_16x16x32_bf16 v[4:7], v[148:151], v[230:233], v[4:7]
	v_mfma_f32_16x16x32_bf16 v[0:3], v[156:159], v[230:233], v[0:3]
	s_setprio 0
	s_barrier
	s_add_i32 s61, 0, 0x18000
	s_add_i32 s62, 0, 0x1c000
	v_add_u32_e32 v140, s61, v200
	v_add_u32_e32 v156, s62, v200
	ds_read_b128 v[128:131], v140
	ds_read_b128 v[132:135], v140 offset:1024
	ds_read_b128 v[136:139], v140 offset:2048
	ds_read_b128 v[140:143], v140 offset:3072
	ds_read_b128 v[144:147], v156
	ds_read_b128 v[148:151], v156 offset:1024
	ds_read_b128 v[152:155], v156 offset:2048
	ds_read_b128 v[156:159], v156 offset:3072
	s_add_u32 s28, s28, 0x40000
	s_addc_u32 s29, s29, 0
	s_mov_b32 m0, s44
	v_lshl_add_u64 v[206:207], s[28:29], 0, v[168:169]
	ds_read_b128 v[160:163], v212 offset:32768
	ds_read_b128 v[164:167], v212 offset:33792
	ds_read_b128 v[194:197], v212 offset:34816
	ds_read_b128 v[214:217], v212 offset:35840
	ds_read_b128 v[218:221], v212 offset:36864
	ds_read_b128 v[222:225], v212 offset:37888
	ds_read_b128 v[226:229], v212 offset:38912
	ds_read_b128 v[230:233], v212 offset:39936
	global_load_lds_dwordx4 v[206:207], off
	v_lshl_add_u64 v[206:207], s[28:29], 0, v[172:173]
	s_mov_b32 m0, s45
	s_nop 0
	global_load_lds_dwordx4 v[206:207], off
	s_waitcnt vmcnt(8)
	s_waitcnt lgkmcnt(0)
	s_barrier
	s_setprio 1
	s_waitcnt lgkmcnt(0)
	v_mfma_f32_16x16x32_bf16 v[124:127], v[128:131], v[160:163], v[124:127]
	v_mfma_f32_16x16x32_bf16 v[120:123], v[136:139], v[160:163], v[120:123]
	v_mfma_f32_16x16x32_bf16 v[116:119], v[128:131], v[194:197], v[116:119]
	v_mfma_f32_16x16x32_bf16 v[112:115], v[136:139], v[194:197], v[112:115]
	v_mfma_f32_16x16x32_bf16 v[108:111], v[128:131], v[218:221], v[108:111]
	v_mfma_f32_16x16x32_bf16 v[104:107], v[136:139], v[218:221], v[104:107]
	v_mfma_f32_16x16x32_bf16 v[100:103], v[128:131], v[226:229], v[100:103]
	v_mfma_f32_16x16x32_bf16 v[96:99], v[136:139], v[226:229], v[96:99]
	v_mfma_f32_16x16x32_bf16 v[124:127], v[132:135], v[164:167], v[124:127]
	v_mfma_f32_16x16x32_bf16 v[120:123], v[140:143], v[164:167], v[120:123]
	v_mfma_f32_16x16x32_bf16 v[116:119], v[132:135], v[214:217], v[116:119]
	v_mfma_f32_16x16x32_bf16 v[112:115], v[140:143], v[214:217], v[112:115]
	v_mfma_f32_16x16x32_bf16 v[108:111], v[132:135], v[222:225], v[108:111]
	v_mfma_f32_16x16x32_bf16 v[104:107], v[140:143], v[222:225], v[104:107]
	v_mfma_f32_16x16x32_bf16 v[100:103], v[132:135], v[230:233], v[100:103]
	v_mfma_f32_16x16x32_bf16 v[96:99], v[140:143], v[230:233], v[96:99]
	s_setprio 0
	s_setprio 1
	v_mfma_f32_16x16x32_bf16 v[60:63], v[144:147], v[160:163], v[60:63]
	v_mfma_f32_16x16x32_bf16 v[56:59], v[152:155], v[160:163], v[56:59]
	v_mfma_f32_16x16x32_bf16 v[52:55], v[144:147], v[194:197], v[52:55]
	v_mfma_f32_16x16x32_bf16 v[48:51], v[152:155], v[194:197], v[48:51]
	v_mfma_f32_16x16x32_bf16 v[44:47], v[144:147], v[218:221], v[44:47]
	v_mfma_f32_16x16x32_bf16 v[40:43], v[152:155], v[218:221], v[40:43]
	v_mfma_f32_16x16x32_bf16 v[36:39], v[144:147], v[226:229], v[36:39]
	v_mfma_f32_16x16x32_bf16 v[32:35], v[152:155], v[226:229], v[32:35]
	v_mfma_f32_16x16x32_bf16 v[60:63], v[148:151], v[164:167], v[60:63]
	v_mfma_f32_16x16x32_bf16 v[56:59], v[156:159], v[164:167], v[56:59]
	v_mfma_f32_16x16x32_bf16 v[52:55], v[148:151], v[214:217], v[52:55]
	v_mfma_f32_16x16x32_bf16 v[48:51], v[156:159], v[214:217], v[48:51]
	v_mfma_f32_16x16x32_bf16 v[44:47], v[148:151], v[222:225], v[44:47]
	v_mfma_f32_16x16x32_bf16 v[40:43], v[156:159], v[222:225], v[40:43]
	v_mfma_f32_16x16x32_bf16 v[36:39], v[148:151], v[230:233], v[36:39]
	v_mfma_f32_16x16x32_bf16 v[32:35], v[156:159], v[230:233], v[32:35]
	s_setprio 0
	s_barrier
	s_add_u32 s28, s26, 0x8000
	s_addc_u32 s29, s27, 0
	s_add_i32 s61, s61, s41
	v_lshl_add_u64 v[206:207], s[28:29], 0, v[170:171]
	s_mov_b32 m0, s61
	ds_read_b128 v[160:163], v212 offset:49152
	ds_read_b128 v[164:167], v212 offset:50176
	ds_read_b128 v[194:197], v212 offset:51200
	ds_read_b128 v[214:217], v212 offset:52224
	ds_read_b128 v[218:221], v212 offset:53248
	ds_read_b128 v[222:225], v212 offset:54272
	ds_read_b128 v[226:229], v212 offset:55296
	ds_read_b128 v[230:233], v212 offset:56320
	global_load_lds_dwordx4 v[206:207], off
	s_add_i32 m0, s61, 0x2000
	s_add_u32 s26, s26, 0xc000
	v_lshl_add_u64 v[206:207], s[28:29], 0, v[174:175]
	s_addc_u32 s27, s27, 0
	s_add_i32 s28, s62, s41
	global_load_lds_dwordx4 v[206:207], off
	v_lshl_add_u64 v[206:207], s[26:27], 0, v[170:171]
	s_mov_b32 m0, s28
	v_lshl_add_u64 v[198:199], v[198:199], 0, s[12:13]
	global_load_lds_dwordx4 v[206:207], off
	v_lshl_add_u64 v[206:207], s[26:27], 0, v[174:175]
	s_add_i32 m0, s28, 0x2000
	s_nop 0
	global_load_lds_dwordx4 v[206:207], off
	s_mov_b32 m0, s50
	s_nop 0
	global_load_lds_dwordx4 v[198:199], off
	v_lshl_add_u64 v[198:199], v[204:205], 0, s[12:13]
	s_mov_b32 m0, s51
	s_nop 0
	global_load_lds_dwordx4 v[198:199], off
	s_waitcnt vmcnt(8)
	s_waitcnt lgkmcnt(0)
	s_barrier
	s_setprio 1
	s_waitcnt lgkmcnt(0)
	v_mfma_f32_16x16x32_bf16 v[92:95], v[128:131], v[160:163], v[92:95]
	v_mfma_f32_16x16x32_bf16 v[88:91], v[136:139], v[160:163], v[88:91]
	v_mfma_f32_16x16x32_bf16 v[84:87], v[128:131], v[194:197], v[84:87]
	v_mfma_f32_16x16x32_bf16 v[80:83], v[136:139], v[194:197], v[80:83]
	v_mfma_f32_16x16x32_bf16 v[76:79], v[128:131], v[218:221], v[76:79]
	v_mfma_f32_16x16x32_bf16 v[72:75], v[136:139], v[218:221], v[72:75]
	v_mfma_f32_16x16x32_bf16 v[68:71], v[128:131], v[226:229], v[68:71]
	v_mfma_f32_16x16x32_bf16 v[64:67], v[136:139], v[226:229], v[64:67]
	v_mfma_f32_16x16x32_bf16 v[92:95], v[132:135], v[164:167], v[92:95]
	v_mfma_f32_16x16x32_bf16 v[88:91], v[140:143], v[164:167], v[88:91]
	v_mfma_f32_16x16x32_bf16 v[84:87], v[132:135], v[214:217], v[84:87]
	v_mfma_f32_16x16x32_bf16 v[80:83], v[140:143], v[214:217], v[80:83]
	v_mfma_f32_16x16x32_bf16 v[76:79], v[132:135], v[222:225], v[76:79]
	v_mfma_f32_16x16x32_bf16 v[72:75], v[140:143], v[222:225], v[72:75]
	v_mfma_f32_16x16x32_bf16 v[68:71], v[132:135], v[230:233], v[68:71]
	v_mfma_f32_16x16x32_bf16 v[64:67], v[140:143], v[230:233], v[64:67]
	s_setprio 0
	s_setprio 1
	v_mfma_f32_16x16x32_bf16 v[28:31], v[144:147], v[160:163], v[28:31]
	v_mfma_f32_16x16x32_bf16 v[24:27], v[152:155], v[160:163], v[24:27]
	v_mfma_f32_16x16x32_bf16 v[20:23], v[144:147], v[194:197], v[20:23]
	v_mfma_f32_16x16x32_bf16 v[16:19], v[152:155], v[194:197], v[16:19]
	v_mfma_f32_16x16x32_bf16 v[12:15], v[144:147], v[218:221], v[12:15]
	v_mfma_f32_16x16x32_bf16 v[8:11], v[152:155], v[218:221], v[8:11]
	v_mfma_f32_16x16x32_bf16 v[4:7], v[144:147], v[226:229], v[4:7]
	v_mfma_f32_16x16x32_bf16 v[0:3], v[152:155], v[226:229], v[0:3]
	v_mfma_f32_16x16x32_bf16 v[28:31], v[148:151], v[164:167], v[28:31]
	v_mfma_f32_16x16x32_bf16 v[24:27], v[156:159], v[164:167], v[24:27]
	v_mfma_f32_16x16x32_bf16 v[20:23], v[148:151], v[214:217], v[20:23]
	v_mfma_f32_16x16x32_bf16 v[16:19], v[156:159], v[214:217], v[16:19]
	v_mfma_f32_16x16x32_bf16 v[12:15], v[148:151], v[222:225], v[12:15]
	v_mfma_f32_16x16x32_bf16 v[8:11], v[156:159], v[222:225], v[8:11]
	v_mfma_f32_16x16x32_bf16 v[4:7], v[148:151], v[230:233], v[4:7]
	v_mfma_f32_16x16x32_bf16 v[0:3], v[156:159], v[230:233], v[0:3]
	s_setprio 0
	s_add_i32 s35, s35, 2
	s_add_u32 s31, s31, 0x10000
	s_addc_u32 s34, s34, 0
	s_add_u32 s6, s6, 0x100
	s_addc_u32 s7, s7, 0
	s_cmp_gt_u32 s35, 13
	s_cbranch_scc0 .Lrot10
	s_barrier
	s_and_b64 vcc, exec, s[14:15]
	s_cbranch_vccz .LBB0_1740
	s_barrier
	v_lshl_add_u32 v214, s0, 8, v179
	s_cmp_gt_i32 s2, 4
	s_mov_b64 s[0:1], -1
	s_cbranch_scc1 .LBB0_1741

.LBB0_2258:
	ds_read_b128 v[128:131], v170
	ds_read_b128 v[148:151], v170 offset:1024
	ds_read_b128 v[152:155], v170 offset:2048
	ds_read_b128 v[174:177], v170 offset:3072
	ds_read_b128 v[178:181], v171
	ds_read_b128 v[182:185], v171 offset:1024
	ds_read_b128 v[186:189], v171 offset:2048
	ds_read_b128 v[190:193], v171 offset:3072
	s_add_u32 s30, s28, 0xfffe0080
	s_addc_u32 s31, s29, -1
	s_cmp_eq_u32 s56, 4
	s_cselect_b32 s35, s17, s31
	s_cselect_b32 s34, s52, s30
	s_cselect_b32 s31, s19, s55
	s_cselect_b32 s30, s53, s54
	v_lshl_add_u64 v[204:205], s[28:29], 0, v[142:143]
	s_add_i32 m0, s25, 0xc000
	ds_read_b128 v[194:197], v172
	ds_read_b128 v[198:201], v172 offset:1024
	ds_read_b128 v[210:213], v172 offset:2048
	ds_read_b128 v[214:217], v172 offset:3072
	ds_read_b128 v[218:221], v172 offset:4096
	ds_read_b128 v[222:225], v172 offset:5120
	ds_read_b128 v[226:229], v172 offset:6144
	ds_read_b128 v[230:233], v172 offset:7168
	global_load_lds_dwordx4 v[204:205], off
	v_lshl_add_u64 v[204:205], s[28:29], 0, v[140:141]
	s_add_i32 m0, s25, 0xe000
	s_nop 0
	global_load_lds_dwordx4 v[204:205], off
	s_waitcnt vmcnt(8)
	s_waitcnt lgkmcnt(0)
	s_barrier
	s_setprio 1
	s_waitcnt lgkmcnt(0)
	v_mfma_f32_16x16x32_bf16 v[124:127], v[128:131], v[194:197], v[124:127]
	v_mfma_f32_16x16x32_bf16 v[120:123], v[152:155], v[194:197], v[120:123]
	v_mfma_f32_16x16x32_bf16 v[116:119], v[128:131], v[210:213], v[116:119]
	v_mfma_f32_16x16x32_bf16 v[112:115], v[152:155], v[210:213], v[112:115]
	v_mfma_f32_16x16x32_bf16 v[92:95], v[128:131], v[218:221], v[92:95]
	v_mfma_f32_16x16x32_bf16 v[88:91], v[152:155], v[218:221], v[88:91]
	v_mfma_f32_16x16x32_bf16 v[84:87], v[128:131], v[226:229], v[84:87]
	v_mfma_f32_16x16x32_bf16 v[72:75], v[152:155], v[226:229], v[72:75]
	v_mfma_f32_16x16x32_bf16 v[124:127], v[148:151], v[198:201], v[124:127]
	v_mfma_f32_16x16x32_bf16 v[120:123], v[174:177], v[198:201], v[120:123]
	v_mfma_f32_16x16x32_bf16 v[116:119], v[148:151], v[214:217], v[116:119]
	v_mfma_f32_16x16x32_bf16 v[112:115], v[174:177], v[214:217], v[112:115]
	v_mfma_f32_16x16x32_bf16 v[92:95], v[148:151], v[222:225], v[92:95]
	v_mfma_f32_16x16x32_bf16 v[88:91], v[174:177], v[222:225], v[88:91]
	v_mfma_f32_16x16x32_bf16 v[84:87], v[148:151], v[230:233], v[84:87]
	v_mfma_f32_16x16x32_bf16 v[72:75], v[174:177], v[230:233], v[72:75]
	s_setprio 0
	s_setprio 1
	v_mfma_f32_16x16x32_bf16 v[108:111], v[178:181], v[194:197], v[108:111]
	v_mfma_f32_16x16x32_bf16 v[104:107], v[186:189], v[194:197], v[104:107]
	v_mfma_f32_16x16x32_bf16 v[100:103], v[178:181], v[210:213], v[100:103]
	v_mfma_f32_16x16x32_bf16 v[96:99], v[186:189], v[210:213], v[96:99]
	v_mfma_f32_16x16x32_bf16 v[80:83], v[178:181], v[218:221], v[80:83]
	v_mfma_f32_16x16x32_bf16 v[76:79], v[186:189], v[218:221], v[76:79]
	v_mfma_f32_16x16x32_bf16 v[68:71], v[178:181], v[226:229], v[68:71]
	v_mfma_f32_16x16x32_bf16 v[64:67], v[186:189], v[226:229], v[64:67]
	v_mfma_f32_16x16x32_bf16 v[108:111], v[182:185], v[198:201], v[108:111]
	v_mfma_f32_16x16x32_bf16 v[104:107], v[190:193], v[198:201], v[104:107]
	v_mfma_f32_16x16x32_bf16 v[100:103], v[182:185], v[214:217], v[100:103]
	v_mfma_f32_16x16x32_bf16 v[96:99], v[190:193], v[214:217], v[96:99]
	v_mfma_f32_16x16x32_bf16 v[80:83], v[182:185], v[222:225], v[80:83]
	v_mfma_f32_16x16x32_bf16 v[76:79], v[190:193], v[222:225], v[76:79]
	v_mfma_f32_16x16x32_bf16 v[68:71], v[182:185], v[230:233], v[68:71]
	v_mfma_f32_16x16x32_bf16 v[64:67], v[190:193], v[230:233], v[64:67]
	s_setprio 0
	s_barrier
	s_add_i32 s57, s49, s42
	v_lshl_add_u64 v[204:205], s[30:31], 0, v[134:135]
	s_mov_b32 m0, s57
	ds_read_b128 v[194:197], v172 offset:16384
	ds_read_b128 v[198:201], v172 offset:17408
	ds_read_b128 v[210:213], v172 offset:18432
	ds_read_b128 v[214:217], v172 offset:19456
	ds_read_b128 v[218:221], v172 offset:20480
	ds_read_b128 v[222:225], v172 offset:21504
	ds_read_b128 v[226:229], v172 offset:22528
	ds_read_b128 v[230:233], v172 offset:23552
	global_load_lds_dwordx4 v[204:205], off
	s_add_i32 m0, s57, 0x2000
	s_add_u32 s58, s30, 0x4000
	v_lshl_add_u64 v[204:205], s[30:31], 0, v[138:139]
	s_addc_u32 s59, s31, 0
	s_add_i32 s57, s50, s42
	global_load_lds_dwordx4 v[204:205], off
	v_lshl_add_u64 v[204:205], s[58:59], 0, v[134:135]
	s_mov_b32 m0, s57
	v_lshl_add_u64 v[206:207], s[34:35], 0, v[136:137]
	global_load_lds_dwordx4 v[204:205], off
	v_lshl_add_u64 v[204:205], s[58:59], 0, v[138:139]
	s_add_i32 m0, s57, 0x2000
	s_nop 0
	global_load_lds_dwordx4 v[204:205], off
	v_lshl_add_u64 v[204:205], s[34:35], 0, v[132:133]
	s_mov_b32 m0, s25
	s_nop 0
	global_load_lds_dwordx4 v[204:205], off
	s_mov_b32 m0, s27
	s_nop 0
	global_load_lds_dwordx4 v[206:207], off
	s_waitcnt vmcnt(8)
	s_waitcnt lgkmcnt(0)
	s_barrier
	s_setprio 1
	s_waitcnt lgkmcnt(0)
	v_mfma_f32_16x16x32_bf16 v[60:63], v[128:131], v[194:197], v[60:63]
	v_mfma_f32_16x16x32_bf16 v[56:59], v[152:155], v[194:197], v[56:59]
	v_mfma_f32_16x16x32_bf16 v[48:51], v[128:131], v[210:213], v[48:51]
	v_mfma_f32_16x16x32_bf16 v[40:43], v[152:155], v[210:213], v[40:43]
	v_mfma_f32_16x16x32_bf16 v[32:35], v[128:131], v[218:221], v[32:35]
	v_mfma_f32_16x16x32_bf16 v[24:27], v[152:155], v[218:221], v[24:27]
	v_mfma_f32_16x16x32_bf16 v[16:19], v[128:131], v[226:229], v[16:19]
	v_mfma_f32_16x16x32_bf16 v[8:11], v[152:155], v[226:229], v[8:11]
	v_mfma_f32_16x16x32_bf16 v[60:63], v[148:151], v[198:201], v[60:63]
	v_mfma_f32_16x16x32_bf16 v[56:59], v[174:177], v[198:201], v[56:59]
	v_mfma_f32_16x16x32_bf16 v[48:51], v[148:151], v[214:217], v[48:51]
	v_mfma_f32_16x16x32_bf16 v[40:43], v[174:177], v[214:217], v[40:43]
	v_mfma_f32_16x16x32_bf16 v[32:35], v[148:151], v[222:225], v[32:35]
	v_mfma_f32_16x16x32_bf16 v[24:27], v[174:177], v[222:225], v[24:27]
	v_mfma_f32_16x16x32_bf16 v[16:19], v[148:151], v[230:233], v[16:19]
	v_mfma_f32_16x16x32_bf16 v[8:11], v[174:177], v[230:233], v[8:11]
	s_setprio 0
	s_setprio 1
	v_mfma_f32_16x16x32_bf16 v[52:55], v[178:181], v[194:197], v[52:55]
	v_mfma_f32_16x16x32_bf16 v[44:47], v[186:189], v[194:197], v[44:47]
	v_mfma_f32_16x16x32_bf16 v[36:39], v[178:181], v[210:213], v[36:39]
	v_mfma_f32_16x16x32_bf16 v[28:31], v[186:189], v[210:213], v[28:31]
	v_mfma_f32_16x16x32_bf16 v[20:23], v[178:181], v[218:221], v[20:23]
	v_mfma_f32_16x16x32_bf16 v[12:15], v[186:189], v[218:221], v[12:15]
	v_mfma_f32_16x16x32_bf16 v[4:7], v[178:181], v[226:229], v[4:7]
	v_mfma_f32_16x16x32_bf16 v[0:3], v[186:189], v[226:229], v[0:3]
	v_mfma_f32_16x16x32_bf16 v[52:55], v[182:185], v[198:201], v[52:55]
	v_mfma_f32_16x16x32_bf16 v[44:47], v[190:193], v[198:201], v[44:47]
	v_mfma_f32_16x16x32_bf16 v[36:39], v[182:185], v[214:217], v[36:39]
	v_mfma_f32_16x16x32_bf16 v[28:31], v[190:193], v[214:217], v[28:31]
	v_mfma_f32_16x16x32_bf16 v[20:23], v[182:185], v[222:225], v[20:23]
	v_mfma_f32_16x16x32_bf16 v[12:15], v[190:193], v[222:225], v[12:15]
	v_mfma_f32_16x16x32_bf16 v[4:7], v[182:185], v[230:233], v[4:7]
	v_mfma_f32_16x16x32_bf16 v[0:3], v[190:193], v[230:233], v[0:3]
	s_setprio 0
	s_barrier
	s_add_i32 s57, 0, 0x18000
	v_add_u32_e32 v173, s57, v168
	s_add_i32 s58, 0, 0x1c000
	ds_read_b128 v[128:131], v173
	ds_read_b128 v[148:151], v173 offset:1024
	ds_read_b128 v[152:155], v173 offset:2048
	ds_read_b128 v[174:177], v173 offset:3072
	v_add_u32_e32 v173, s58, v168
	ds_read_b128 v[178:181], v173
	ds_read_b128 v[182:185], v173 offset:1024
	ds_read_b128 v[186:189], v173 offset:2048
	ds_read_b128 v[190:193], v173 offset:3072
	s_add_u32 s34, s34, 0x20000
	s_addc_u32 s35, s35, 0
	s_mov_b32 m0, s43
	v_lshl_add_u64 v[234:235], s[34:35], 0, v[132:133]
	ds_read_b128 v[194:197], v172 offset:32768
	ds_read_b128 v[198:201], v172 offset:33792
	ds_read_b128 v[210:213], v172 offset:34816
	ds_read_b128 v[214:217], v172 offset:35840
	ds_read_b128 v[218:221], v172 offset:36864
	ds_read_b128 v[222:225], v172 offset:37888
	ds_read_b128 v[226:229], v172 offset:38912
	ds_read_b128 v[230:233], v172 offset:39936
	global_load_lds_dwordx4 v[234:235], off
	v_lshl_add_u64 v[234:235], s[34:35], 0, v[136:137]
	s_mov_b32 m0, s44
	s_nop 0
	global_load_lds_dwordx4 v[234:235], off
	s_waitcnt vmcnt(8)
	s_waitcnt lgkmcnt(0)
	s_barrier
	s_setprio 1
	s_waitcnt lgkmcnt(0)
	v_mfma_f32_16x16x32_bf16 v[124:127], v[128:131], v[194:197], v[124:127]
	v_mfma_f32_16x16x32_bf16 v[120:123], v[152:155], v[194:197], v[120:123]
	v_mfma_f32_16x16x32_bf16 v[116:119], v[128:131], v[210:213], v[116:119]
	v_mfma_f32_16x16x32_bf16 v[112:115], v[152:155], v[210:213], v[112:115]
	v_mfma_f32_16x16x32_bf16 v[92:95], v[128:131], v[218:221], v[92:95]
	v_mfma_f32_16x16x32_bf16 v[88:91], v[152:155], v[218:221], v[88:91]
	v_mfma_f32_16x16x32_bf16 v[84:87], v[128:131], v[226:229], v[84:87]
	v_mfma_f32_16x16x32_bf16 v[72:75], v[152:155], v[226:229], v[72:75]
	v_mfma_f32_16x16x32_bf16 v[124:127], v[148:151], v[198:201], v[124:127]
	v_mfma_f32_16x16x32_bf16 v[120:123], v[174:177], v[198:201], v[120:123]
	v_mfma_f32_16x16x32_bf16 v[116:119], v[148:151], v[214:217], v[116:119]
	v_mfma_f32_16x16x32_bf16 v[112:115], v[174:177], v[214:217], v[112:115]
	v_mfma_f32_16x16x32_bf16 v[92:95], v[148:151], v[222:225], v[92:95]
	v_mfma_f32_16x16x32_bf16 v[88:91], v[174:177], v[222:225], v[88:91]
	v_mfma_f32_16x16x32_bf16 v[84:87], v[148:151], v[230:233], v[84:87]
	v_mfma_f32_16x16x32_bf16 v[72:75], v[174:177], v[230:233], v[72:75]
	s_setprio 0
	s_setprio 1
	v_mfma_f32_16x16x32_bf16 v[108:111], v[178:181], v[194:197], v[108:111]
	v_mfma_f32_16x16x32_bf16 v[104:107], v[186:189], v[194:197], v[104:107]
	v_mfma_f32_16x16x32_bf16 v[100:103], v[178:181], v[210:213], v[100:103]
	v_mfma_f32_16x16x32_bf16 v[96:99], v[186:189], v[210:213], v[96:99]
	v_mfma_f32_16x16x32_bf16 v[80:83], v[178:181], v[218:221], v[80:83]
	v_mfma_f32_16x16x32_bf16 v[76:79], v[186:189], v[218:221], v[76:79]
	v_mfma_f32_16x16x32_bf16 v[68:71], v[178:181], v[226:229], v[68:71]
	v_mfma_f32_16x16x32_bf16 v[64:67], v[186:189], v[226:229], v[64:67]
	v_mfma_f32_16x16x32_bf16 v[108:111], v[182:185], v[198:201], v[108:111]
	v_mfma_f32_16x16x32_bf16 v[104:107], v[190:193], v[198:201], v[104:107]
	v_mfma_f32_16x16x32_bf16 v[100:103], v[182:185], v[214:217], v[100:103]
	v_mfma_f32_16x16x32_bf16 v[96:99], v[190:193], v[214:217], v[96:99]
	v_mfma_f32_16x16x32_bf16 v[80:83], v[182:185], v[222:225], v[80:83]
	v_mfma_f32_16x16x32_bf16 v[76:79], v[190:193], v[222:225], v[76:79]
	v_mfma_f32_16x16x32_bf16 v[68:71], v[182:185], v[230:233], v[68:71]
	v_mfma_f32_16x16x32_bf16 v[64:67], v[190:193], v[230:233], v[64:67]
	s_setprio 0
	s_barrier
	s_add_u32 s34, s30, 0x8000
	s_addc_u32 s35, s31, 0
	s_add_i32 s57, s57, s42
	v_lshl_add_u64 v[234:235], s[34:35], 0, v[134:135]
	s_mov_b32 m0, s57
	ds_read_b128 v[194:197], v172 offset:49152
	ds_read_b128 v[198:201], v172 offset:50176
	ds_read_b128 v[210:213], v172 offset:51200
	ds_read_b128 v[214:217], v172 offset:52224
	ds_read_b128 v[218:221], v172 offset:53248
	ds_read_b128 v[222:225], v172 offset:54272
	ds_read_b128 v[226:229], v172 offset:55296
	ds_read_b128 v[230:233], v172 offset:56320
	global_load_lds_dwordx4 v[234:235], off
	s_add_i32 m0, s57, 0x2000
	s_add_u32 s30, s30, 0xc000
	v_lshl_add_u64 v[234:235], s[34:35], 0, v[138:139]
	s_addc_u32 s31, s31, 0
	s_add_i32 s34, s58, s42
	global_load_lds_dwordx4 v[234:235], off
	v_lshl_add_u64 v[234:235], s[30:31], 0, v[134:135]
	s_mov_b32 m0, s34
	v_lshl_add_u64 v[204:205], v[204:205], 0, s[12:13]
	global_load_lds_dwordx4 v[234:235], off
	v_lshl_add_u64 v[234:235], s[30:31], 0, v[138:139]
	s_add_i32 m0, s34, 0x2000
	s_nop 0
	global_load_lds_dwordx4 v[234:235], off
	s_mov_b32 m0, s46
	s_nop 0
	global_load_lds_dwordx4 v[204:205], off
	v_lshl_add_u64 v[204:205], v[206:207], 0, s[12:13]
	s_mov_b32 m0, s47
	s_nop 0
	global_load_lds_dwordx4 v[204:205], off
	s_waitcnt vmcnt(8)
	s_waitcnt lgkmcnt(0)
	s_barrier
	s_setprio 1
	s_waitcnt lgkmcnt(0)
	v_mfma_f32_16x16x32_bf16 v[60:63], v[128:131], v[194:197], v[60:63]
	v_mfma_f32_16x16x32_bf16 v[56:59], v[152:155], v[194:197], v[56:59]
	v_mfma_f32_16x16x32_bf16 v[48:51], v[128:131], v[210:213], v[48:51]
	v_mfma_f32_16x16x32_bf16 v[40:43], v[152:155], v[210:213], v[40:43]
	v_mfma_f32_16x16x32_bf16 v[32:35], v[128:131], v[218:221], v[32:35]
	v_mfma_f32_16x16x32_bf16 v[24:27], v[152:155], v[218:221], v[24:27]
	v_mfma_f32_16x16x32_bf16 v[16:19], v[128:131], v[226:229], v[16:19]
	v_mfma_f32_16x16x32_bf16 v[8:11], v[152:155], v[226:229], v[8:11]
	v_mfma_f32_16x16x32_bf16 v[60:63], v[148:151], v[198:201], v[60:63]
	v_mfma_f32_16x16x32_bf16 v[56:59], v[174:177], v[198:201], v[56:59]
	v_mfma_f32_16x16x32_bf16 v[48:51], v[148:151], v[214:217], v[48:51]
	v_mfma_f32_16x16x32_bf16 v[40:43], v[174:177], v[214:217], v[40:43]
	v_mfma_f32_16x16x32_bf16 v[32:35], v[148:151], v[222:225], v[32:35]
	v_mfma_f32_16x16x32_bf16 v[24:27], v[174:177], v[222:225], v[24:27]
	v_mfma_f32_16x16x32_bf16 v[16:19], v[148:151], v[230:233], v[16:19]
	v_mfma_f32_16x16x32_bf16 v[8:11], v[174:177], v[230:233], v[8:11]
	s_setprio 0
	s_setprio 1
	v_mfma_f32_16x16x32_bf16 v[52:55], v[178:181], v[194:197], v[52:55]
	v_mfma_f32_16x16x32_bf16 v[44:47], v[186:189], v[194:197], v[44:47]
	v_mfma_f32_16x16x32_bf16 v[36:39], v[178:181], v[210:213], v[36:39]
	v_mfma_f32_16x16x32_bf16 v[28:31], v[186:189], v[210:213], v[28:31]
	v_mfma_f32_16x16x32_bf16 v[20:23], v[178:181], v[218:221], v[20:23]
	v_mfma_f32_16x16x32_bf16 v[12:15], v[186:189], v[218:221], v[12:15]
	v_mfma_f32_16x16x32_bf16 v[4:7], v[178:181], v[226:229], v[4:7]
	v_mfma_f32_16x16x32_bf16 v[0:3], v[186:189], v[226:229], v[0:3]
	v_mfma_f32_16x16x32_bf16 v[52:55], v[182:185], v[198:201], v[52:55]
	v_mfma_f32_16x16x32_bf16 v[44:47], v[190:193], v[198:201], v[44:47]
	v_mfma_f32_16x16x32_bf16 v[36:39], v[182:185], v[214:217], v[36:39]
	v_mfma_f32_16x16x32_bf16 v[28:31], v[190:193], v[214:217], v[28:31]
	v_mfma_f32_16x16x32_bf16 v[20:23], v[182:185], v[222:225], v[20:23]
	v_mfma_f32_16x16x32_bf16 v[12:15], v[190:193], v[222:225], v[12:15]
	v_mfma_f32_16x16x32_bf16 v[4:7], v[182:185], v[230:233], v[4:7]
	v_mfma_f32_16x16x32_bf16 v[0:3], v[190:193], v[230:233], v[0:3]
	s_setprio 0
	s_add_i32 s56, s56, 2
	s_add_u32 s54, s54, 0x10000
	s_addc_u32 s55, s55, 0
	s_add_u32 s28, s28, 0x100
	s_addc_u32 s29, s29, 0
	s_cmp_gt_u32 s56, 5
	s_cbranch_scc0 .Lrot11
	s_barrier
	s_and_b64 vcc, exec, s[14:15]
	s_cbranch_vccz .LBB0_2261
	s_barrier

.LBB0_2282:
	ds_read_b128 v[144:147], v155
	ds_read_b128 v[148:151], v155 offset:1024
	ds_read_b128 v[158:161], v155 offset:2048
	ds_read_b128 v[162:165], v155 offset:3072
	ds_read_b128 v[166:169], v156
	ds_read_b128 v[170:173], v156 offset:1024
	ds_read_b128 v[174:177], v156 offset:2048
	ds_read_b128 v[178:181], v156 offset:3072
	s_add_u32 s28, s26, 0xfffe0080
	s_addc_u32 s29, s27, -1
	s_cmp_eq_u32 s54, 4
	s_cselect_b32 s31, s15, s29
	s_cselect_b32 s30, s50, s28
	s_cselect_b32 s29, s17, s53
	s_cselect_b32 s28, s51, s52
	v_lshl_add_u64 v[204:205], s[26:27], 0, v[130:131]
	s_add_i32 m0, s23, 0xc000
	ds_read_b128 v[182:185], v157
	ds_read_b128 v[186:189], v157 offset:1024
	ds_read_b128 v[190:193], v157 offset:2048
	ds_read_b128 v[194:197], v157 offset:3072
	ds_read_b128 v[198:201], v157 offset:4096
	ds_read_b128 v[210:213], v157 offset:5120
	ds_read_b128 v[214:217], v157 offset:6144
	ds_read_b128 v[218:221], v157 offset:7168
	global_load_lds_dwordx4 v[204:205], off
	v_lshl_add_u64 v[204:205], s[26:27], 0, v[128:129]
	s_add_i32 m0, s23, 0xe000
	s_nop 0
	global_load_lds_dwordx4 v[204:205], off
	s_waitcnt vmcnt(8)
	s_waitcnt lgkmcnt(0)
	s_barrier
	s_setprio 1
	s_waitcnt lgkmcnt(0)
	v_mfma_f32_16x16x32_bf16 v[124:127], v[144:147], v[182:185], v[124:127]
	v_mfma_f32_16x16x32_bf16 v[120:123], v[158:161], v[182:185], v[120:123]
	v_mfma_f32_16x16x32_bf16 v[112:115], v[144:147], v[190:193], v[112:115]
	v_mfma_f32_16x16x32_bf16 v[104:107], v[158:161], v[190:193], v[104:107]
	v_mfma_f32_16x16x32_bf16 v[92:95], v[144:147], v[198:201], v[92:95]
	v_mfma_f32_16x16x32_bf16 v[88:91], v[158:161], v[198:201], v[88:91]
	v_mfma_f32_16x16x32_bf16 v[80:83], v[144:147], v[214:217], v[80:83]
	v_mfma_f32_16x16x32_bf16 v[72:75], v[158:161], v[214:217], v[72:75]
	v_mfma_f32_16x16x32_bf16 v[124:127], v[148:151], v[186:189], v[124:127]
	v_mfma_f32_16x16x32_bf16 v[120:123], v[162:165], v[186:189], v[120:123]
	v_mfma_f32_16x16x32_bf16 v[112:115], v[148:151], v[194:197], v[112:115]
	v_mfma_f32_16x16x32_bf16 v[104:107], v[162:165], v[194:197], v[104:107]
	v_mfma_f32_16x16x32_bf16 v[92:95], v[148:151], v[210:213], v[92:95]
	v_mfma_f32_16x16x32_bf16 v[88:91], v[162:165], v[210:213], v[88:91]
	v_mfma_f32_16x16x32_bf16 v[80:83], v[148:151], v[218:221], v[80:83]
	v_mfma_f32_16x16x32_bf16 v[72:75], v[162:165], v[218:221], v[72:75]
	s_setprio 0
	s_setprio 1
	v_mfma_f32_16x16x32_bf16 v[116:119], v[166:169], v[182:185], v[116:119]
	v_mfma_f32_16x16x32_bf16 v[108:111], v[174:177], v[182:185], v[108:111]
	v_mfma_f32_16x16x32_bf16 v[100:103], v[166:169], v[190:193], v[100:103]
	v_mfma_f32_16x16x32_bf16 v[96:99], v[174:177], v[190:193], v[96:99]
	v_mfma_f32_16x16x32_bf16 v[84:87], v[166:169], v[198:201], v[84:87]
	v_mfma_f32_16x16x32_bf16 v[76:79], v[174:177], v[198:201], v[76:79]
	v_mfma_f32_16x16x32_bf16 v[68:71], v[166:169], v[214:217], v[68:71]
	v_mfma_f32_16x16x32_bf16 v[64:67], v[174:177], v[214:217], v[64:67]
	v_mfma_f32_16x16x32_bf16 v[116:119], v[170:173], v[186:189], v[116:119]
	v_mfma_f32_16x16x32_bf16 v[108:111], v[178:181], v[186:189], v[108:111]
	v_mfma_f32_16x16x32_bf16 v[100:103], v[170:173], v[194:197], v[100:103]
	v_mfma_f32_16x16x32_bf16 v[96:99], v[178:181], v[194:197], v[96:99]
	v_mfma_f32_16x16x32_bf16 v[84:87], v[170:173], v[210:213], v[84:87]
	v_mfma_f32_16x16x32_bf16 v[76:79], v[178:181], v[210:213], v[76:79]
	v_mfma_f32_16x16x32_bf16 v[68:71], v[170:173], v[218:221], v[68:71]
	v_mfma_f32_16x16x32_bf16 v[64:67], v[178:181], v[218:221], v[64:67]
	s_setprio 0
	s_barrier
	s_add_i32 s55, s47, s40
	v_lshl_add_u64 v[204:205], s[28:29], 0, v[134:135]
	s_mov_b32 m0, s55
	ds_read_b128 v[182:185], v157 offset:16384
	ds_read_b128 v[186:189], v157 offset:17408
	ds_read_b128 v[190:193], v157 offset:18432
	ds_read_b128 v[194:197], v157 offset:19456
	ds_read_b128 v[198:201], v157 offset:20480
	ds_read_b128 v[210:213], v157 offset:21504
	ds_read_b128 v[214:217], v157 offset:22528
	ds_read_b128 v[218:221], v157 offset:23552
	global_load_lds_dwordx4 v[204:205], off
	s_add_i32 m0, s55, 0x2000
	s_add_u32 s56, s28, 0x4000
	v_lshl_add_u64 v[204:205], s[28:29], 0, v[138:139]
	s_addc_u32 s57, s29, 0
	s_add_i32 s55, s48, s40
	global_load_lds_dwordx4 v[204:205], off
	v_lshl_add_u64 v[204:205], s[56:57], 0, v[134:135]
	s_mov_b32 m0, s55
	v_lshl_add_u64 v[206:207], s[30:31], 0, v[136:137]
	global_load_lds_dwordx4 v[204:205], off
	v_lshl_add_u64 v[204:205], s[56:57], 0, v[138:139]
	s_add_i32 m0, s55, 0x2000
	s_nop 0
	global_load_lds_dwordx4 v[204:205], off
	v_lshl_add_u64 v[204:205], s[30:31], 0, v[132:133]
	s_mov_b32 m0, s23
	s_nop 0
	global_load_lds_dwordx4 v[204:205], off
	s_mov_b32 m0, s25
	s_nop 0
	global_load_lds_dwordx4 v[206:207], off
	s_waitcnt vmcnt(8)
	s_waitcnt lgkmcnt(0)
	s_barrier
	s_setprio 1
	s_waitcnt lgkmcnt(0)
	v_mfma_f32_16x16x32_bf16 v[60:63], v[144:147], v[182:185], v[60:63]
	v_mfma_f32_16x16x32_bf16 v[56:59], v[158:161], v[182:185], v[56:59]
	v_mfma_f32_16x16x32_bf16 v[48:51], v[144:147], v[190:193], v[48:51]
	v_mfma_f32_16x16x32_bf16 v[40:43], v[158:161], v[190:193], v[40:43]
	v_mfma_f32_16x16x32_bf16 v[28:31], v[144:147], v[198:201], v[28:31]
	v_mfma_f32_16x16x32_bf16 v[24:27], v[158:161], v[198:201], v[24:27]
	v_mfma_f32_16x16x32_bf16 v[16:19], v[144:147], v[214:217], v[16:19]
	v_mfma_f32_16x16x32_bf16 v[8:11], v[158:161], v[214:217], v[8:11]
	v_mfma_f32_16x16x32_bf16 v[60:63], v[148:151], v[186:189], v[60:63]
	v_mfma_f32_16x16x32_bf16 v[56:59], v[162:165], v[186:189], v[56:59]
	v_mfma_f32_16x16x32_bf16 v[48:51], v[148:151], v[194:197], v[48:51]
	v_mfma_f32_16x16x32_bf16 v[40:43], v[162:165], v[194:197], v[40:43]
	v_mfma_f32_16x16x32_bf16 v[28:31], v[148:151], v[210:213], v[28:31]
	v_mfma_f32_16x16x32_bf16 v[24:27], v[162:165], v[210:213], v[24:27]
	v_mfma_f32_16x16x32_bf16 v[16:19], v[148:151], v[218:221], v[16:19]
	v_mfma_f32_16x16x32_bf16 v[8:11], v[162:165], v[218:221], v[8:11]
	s_setprio 0
	s_setprio 1
	v_mfma_f32_16x16x32_bf16 v[52:55], v[166:169], v[182:185], v[52:55]
	v_mfma_f32_16x16x32_bf16 v[44:47], v[174:177], v[182:185], v[44:47]
	v_mfma_f32_16x16x32_bf16 v[36:39], v[166:169], v[190:193], v[36:39]
	v_mfma_f32_16x16x32_bf16 v[32:35], v[174:177], v[190:193], v[32:35]
	v_mfma_f32_16x16x32_bf16 v[20:23], v[166:169], v[198:201], v[20:23]
	v_mfma_f32_16x16x32_bf16 v[12:15], v[174:177], v[198:201], v[12:15]
	v_mfma_f32_16x16x32_bf16 v[4:7], v[166:169], v[214:217], v[4:7]
	v_mfma_f32_16x16x32_bf16 v[0:3], v[174:177], v[214:217], v[0:3]
	v_mfma_f32_16x16x32_bf16 v[52:55], v[170:173], v[186:189], v[52:55]
	v_mfma_f32_16x16x32_bf16 v[44:47], v[178:181], v[186:189], v[44:47]
	v_mfma_f32_16x16x32_bf16 v[36:39], v[170:173], v[194:197], v[36:39]
	v_mfma_f32_16x16x32_bf16 v[32:35], v[178:181], v[194:197], v[32:35]
	v_mfma_f32_16x16x32_bf16 v[20:23], v[170:173], v[210:213], v[20:23]
	v_mfma_f32_16x16x32_bf16 v[12:15], v[178:181], v[210:213], v[12:15]
	v_mfma_f32_16x16x32_bf16 v[4:7], v[170:173], v[218:221], v[4:7]
	v_mfma_f32_16x16x32_bf16 v[0:3], v[178:181], v[218:221], v[0:3]
	s_setprio 0
	s_barrier
	s_add_i32 s55, 0, 0x18000
	s_add_i32 s56, 0, 0x1c000
	v_add_u32_e32 v162, s55, v153
	v_add_u32_e32 v178, s56, v153
	ds_read_b128 v[144:147], v162
	ds_read_b128 v[148:151], v162 offset:1024
	ds_read_b128 v[158:161], v162 offset:2048
	ds_read_b128 v[162:165], v162 offset:3072
	ds_read_b128 v[166:169], v178
	ds_read_b128 v[170:173], v178 offset:1024
	ds_read_b128 v[174:177], v178 offset:2048
	ds_read_b128 v[178:181], v178 offset:3072
	s_add_u32 s30, s30, 0x20000
	s_addc_u32 s31, s31, 0
	s_mov_b32 m0, s41
	v_lshl_add_u64 v[222:223], s[30:31], 0, v[132:133]
	ds_read_b128 v[182:185], v157 offset:32768
	ds_read_b128 v[186:189], v157 offset:33792
	ds_read_b128 v[190:193], v157 offset:34816
	ds_read_b128 v[194:197], v157 offset:35840
	ds_read_b128 v[198:201], v157 offset:36864
	ds_read_b128 v[210:213], v157 offset:37888
	ds_read_b128 v[214:217], v157 offset:38912
	ds_read_b128 v[218:221], v157 offset:39936
	global_load_lds_dwordx4 v[222:223], off
	v_lshl_add_u64 v[222:223], s[30:31], 0, v[136:137]
	s_mov_b32 m0, s42
	s_nop 0
	global_load_lds_dwordx4 v[222:223], off
	s_waitcnt vmcnt(8)
	s_waitcnt lgkmcnt(0)
	s_barrier
	s_setprio 1
	s_waitcnt lgkmcnt(0)
	v_mfma_f32_16x16x32_bf16 v[124:127], v[144:147], v[182:185], v[124:127]
	v_mfma_f32_16x16x32_bf16 v[120:123], v[158:161], v[182:185], v[120:123]
	v_mfma_f32_16x16x32_bf16 v[112:115], v[144:147], v[190:193], v[112:115]
	v_mfma_f32_16x16x32_bf16 v[104:107], v[158:161], v[190:193], v[104:107]
	v_mfma_f32_16x16x32_bf16 v[92:95], v[144:147], v[198:201], v[92:95]
	v_mfma_f32_16x16x32_bf16 v[88:91], v[158:161], v[198:201], v[88:91]
	v_mfma_f32_16x16x32_bf16 v[80:83], v[144:147], v[214:217], v[80:83]
	v_mfma_f32_16x16x32_bf16 v[72:75], v[158:161], v[214:217], v[72:75]
	v_mfma_f32_16x16x32_bf16 v[124:127], v[148:151], v[186:189], v[124:127]
	v_mfma_f32_16x16x32_bf16 v[120:123], v[162:165], v[186:189], v[120:123]
	v_mfma_f32_16x16x32_bf16 v[112:115], v[148:151], v[194:197], v[112:115]
	v_mfma_f32_16x16x32_bf16 v[104:107], v[162:165], v[194:197], v[104:107]
	v_mfma_f32_16x16x32_bf16 v[92:95], v[148:151], v[210:213], v[92:95]
	v_mfma_f32_16x16x32_bf16 v[88:91], v[162:165], v[210:213], v[88:91]
	v_mfma_f32_16x16x32_bf16 v[80:83], v[148:151], v[218:221], v[80:83]
	v_mfma_f32_16x16x32_bf16 v[72:75], v[162:165], v[218:221], v[72:75]
	s_setprio 0
	s_setprio 1
	v_mfma_f32_16x16x32_bf16 v[116:119], v[166:169], v[182:185], v[116:119]
	v_mfma_f32_16x16x32_bf16 v[108:111], v[174:177], v[182:185], v[108:111]
	v_mfma_f32_16x16x32_bf16 v[100:103], v[166:169], v[190:193], v[100:103]
	v_mfma_f32_16x16x32_bf16 v[96:99], v[174:177], v[190:193], v[96:99]
	v_mfma_f32_16x16x32_bf16 v[84:87], v[166:169], v[198:201], v[84:87]
	v_mfma_f32_16x16x32_bf16 v[76:79], v[174:177], v[198:201], v[76:79]
	v_mfma_f32_16x16x32_bf16 v[68:71], v[166:169], v[214:217], v[68:71]
	v_mfma_f32_16x16x32_bf16 v[64:67], v[174:177], v[214:217], v[64:67]
	v_mfma_f32_16x16x32_bf16 v[116:119], v[170:173], v[186:189], v[116:119]
	v_mfma_f32_16x16x32_bf16 v[108:111], v[178:181], v[186:189], v[108:111]
	v_mfma_f32_16x16x32_bf16 v[100:103], v[170:173], v[194:197], v[100:103]
	v_mfma_f32_16x16x32_bf16 v[96:99], v[178:181], v[194:197], v[96:99]
	v_mfma_f32_16x16x32_bf16 v[84:87], v[170:173], v[210:213], v[84:87]
	v_mfma_f32_16x16x32_bf16 v[76:79], v[178:181], v[210:213], v[76:79]
	v_mfma_f32_16x16x32_bf16 v[68:71], v[170:173], v[218:221], v[68:71]
	v_mfma_f32_16x16x32_bf16 v[64:67], v[178:181], v[218:221], v[64:67]
	s_setprio 0
	s_barrier
	s_add_u32 s30, s28, 0x8000
	s_addc_u32 s31, s29, 0
	s_add_i32 s55, s55, s40
	v_lshl_add_u64 v[222:223], s[30:31], 0, v[134:135]
	s_mov_b32 m0, s55
	ds_read_b128 v[182:185], v157 offset:49152
	ds_read_b128 v[186:189], v157 offset:50176
	ds_read_b128 v[190:193], v157 offset:51200
	ds_read_b128 v[194:197], v157 offset:52224
	ds_read_b128 v[198:201], v157 offset:53248
	ds_read_b128 v[210:213], v157 offset:54272
	ds_read_b128 v[214:217], v157 offset:55296
	ds_read_b128 v[218:221], v157 offset:56320
	global_load_lds_dwordx4 v[222:223], off
	s_add_i32 m0, s55, 0x2000
	s_add_u32 s28, s28, 0xc000
	v_lshl_add_u64 v[222:223], s[30:31], 0, v[138:139]
	s_addc_u32 s29, s29, 0
	s_add_i32 s30, s56, s40
	global_load_lds_dwordx4 v[222:223], off
	v_lshl_add_u64 v[222:223], s[28:29], 0, v[134:135]
	s_mov_b32 m0, s30
	v_lshl_add_u64 v[204:205], v[204:205], 0, s[8:9]
	global_load_lds_dwordx4 v[222:223], off
	v_lshl_add_u64 v[222:223], s[28:29], 0, v[138:139]
	s_add_i32 m0, s30, 0x2000
	s_nop 0
	global_load_lds_dwordx4 v[222:223], off
	s_mov_b32 m0, s44
	s_nop 0
	global_load_lds_dwordx4 v[204:205], off
	v_lshl_add_u64 v[204:205], v[206:207], 0, s[8:9]
	s_mov_b32 m0, s45
	s_nop 0
	global_load_lds_dwordx4 v[204:205], off
	s_waitcnt vmcnt(8)
	s_waitcnt lgkmcnt(0)
	s_barrier
	s_setprio 1
	s_waitcnt lgkmcnt(0)
	v_mfma_f32_16x16x32_bf16 v[60:63], v[144:147], v[182:185], v[60:63]
	v_mfma_f32_16x16x32_bf16 v[56:59], v[158:161], v[182:185], v[56:59]
	v_mfma_f32_16x16x32_bf16 v[48:51], v[144:147], v[190:193], v[48:51]
	v_mfma_f32_16x16x32_bf16 v[40:43], v[158:161], v[190:193], v[40:43]
	v_mfma_f32_16x16x32_bf16 v[28:31], v[144:147], v[198:201], v[28:31]
	v_mfma_f32_16x16x32_bf16 v[24:27], v[158:161], v[198:201], v[24:27]
	v_mfma_f32_16x16x32_bf16 v[16:19], v[144:147], v[214:217], v[16:19]
	v_mfma_f32_16x16x32_bf16 v[8:11], v[158:161], v[214:217], v[8:11]
	v_mfma_f32_16x16x32_bf16 v[60:63], v[148:151], v[186:189], v[60:63]
	v_mfma_f32_16x16x32_bf16 v[56:59], v[162:165], v[186:189], v[56:59]
	v_mfma_f32_16x16x32_bf16 v[48:51], v[148:151], v[194:197], v[48:51]
	v_mfma_f32_16x16x32_bf16 v[40:43], v[162:165], v[194:197], v[40:43]
	v_mfma_f32_16x16x32_bf16 v[28:31], v[148:151], v[210:213], v[28:31]
	v_mfma_f32_16x16x32_bf16 v[24:27], v[162:165], v[210:213], v[24:27]
	v_mfma_f32_16x16x32_bf16 v[16:19], v[148:151], v[218:221], v[16:19]
	v_mfma_f32_16x16x32_bf16 v[8:11], v[162:165], v[218:221], v[8:11]
	s_setprio 0
	s_setprio 1
	v_mfma_f32_16x16x32_bf16 v[52:55], v[166:169], v[182:185], v[52:55]
	v_mfma_f32_16x16x32_bf16 v[44:47], v[174:177], v[182:185], v[44:47]
	v_mfma_f32_16x16x32_bf16 v[36:39], v[166:169], v[190:193], v[36:39]
	v_mfma_f32_16x16x32_bf16 v[32:35], v[174:177], v[190:193], v[32:35]
	v_mfma_f32_16x16x32_bf16 v[20:23], v[166:169], v[198:201], v[20:23]
	v_mfma_f32_16x16x32_bf16 v[12:15], v[174:177], v[198:201], v[12:15]
	v_mfma_f32_16x16x32_bf16 v[4:7], v[166:169], v[214:217], v[4:7]
	v_mfma_f32_16x16x32_bf16 v[0:3], v[174:177], v[214:217], v[0:3]
	v_mfma_f32_16x16x32_bf16 v[52:55], v[170:173], v[186:189], v[52:55]
	v_mfma_f32_16x16x32_bf16 v[44:47], v[178:181], v[186:189], v[44:47]
	v_mfma_f32_16x16x32_bf16 v[36:39], v[170:173], v[194:197], v[36:39]
	v_mfma_f32_16x16x32_bf16 v[32:35], v[178:181], v[194:197], v[32:35]
	v_mfma_f32_16x16x32_bf16 v[20:23], v[170:173], v[210:213], v[20:23]
	v_mfma_f32_16x16x32_bf16 v[12:15], v[178:181], v[210:213], v[12:15]
	v_mfma_f32_16x16x32_bf16 v[4:7], v[170:173], v[218:221], v[4:7]
	v_mfma_f32_16x16x32_bf16 v[0:3], v[178:181], v[218:221], v[0:3]
	s_setprio 0
	s_add_i32 s54, s54, 2
	s_add_u32 s52, s52, 0x10000
	s_addc_u32 s53, s53, 0
	s_add_u32 s26, s26, 0x100
	s_addc_u32 s27, s27, 0
	s_cmp_gt_u32 s54, 5
	s_cbranch_scc0 .Lrot12
	s_barrier
	s_and_b64 vcc, exec, s[10:11]
	s_cbranch_vccz .LBB0_2285
	s_barrier

.LBB0_2358:
	v_add_u32_e32 v168, s77, v182
	v_add_u32_e32 v204, s78, v182
	ds_read_b128 v[156:159], v168
	ds_read_b128 v[160:163], v168 offset:1024
	ds_read_b128 v[164:167], v168 offset:2048
	ds_read_b128 v[168:171], v168 offset:3072
	ds_read_b128 v[172:175], v204
	ds_read_b128 v[176:179], v204 offset:1024
	ds_read_b128 v[212:215], v204 offset:2048
	ds_read_b128 v[216:219], v204 offset:3072
	s_add_u32 s48, s46, 0xfffc0080
	s_addc_u32 s49, s47, -1
	s_cmp_eq_u32 s54, 12
	s_cselect_b32 s51, s35, s49
	s_cselect_b32 s50, s43, s48
	s_cselect_b32 s49, s37, s53
	s_cselect_b32 s48, s45, s52
	v_lshl_add_u64 v[204:205], s[46:47], 0, v[154:155]
	s_add_i32 m0, s65, 0xc000
	ds_read_b128 v[220:223], v199
	ds_read_b128 v[224:227], v199 offset:1024
	ds_read_b128 v[228:231], v199 offset:2048
	ds_read_b128 v[232:235], v199 offset:3072
	ds_read_b128 v[236:239], v199 offset:4096
	ds_read_b128 v[240:243], v199 offset:5120
	ds_read_b128 v[244:247], v199 offset:6144
	ds_read_b128 v[248:251], v199 offset:7168
	global_load_lds_dwordx4 v[204:205], off
	v_lshl_add_u64 v[204:205], s[46:47], 0, v[152:153]
	s_add_i32 m0, s65, 0xe000
	s_nop 0
	global_load_lds_dwordx4 v[204:205], off
	s_waitcnt vmcnt(8)
	s_waitcnt lgkmcnt(0)
	s_barrier
	s_setprio 1
	s_waitcnt lgkmcnt(0)
	v_mfma_f32_16x16x32_bf16 v[124:127], v[156:159], v[220:223], v[124:127]
	v_mfma_f32_16x16x32_bf16 v[120:123], v[164:167], v[220:223], v[120:123]
	v_mfma_f32_16x16x32_bf16 v[116:119], v[156:159], v[228:231], v[116:119]
	v_mfma_f32_16x16x32_bf16 v[112:115], v[164:167], v[228:231], v[112:115]
	v_mfma_f32_16x16x32_bf16 v[92:95], v[156:159], v[236:239], v[92:95]
	v_mfma_f32_16x16x32_bf16 v[88:91], v[164:167], v[236:239], v[88:91]
	v_mfma_f32_16x16x32_bf16 v[84:87], v[156:159], v[244:247], v[84:87]
	v_mfma_f32_16x16x32_bf16 v[80:83], v[164:167], v[244:247], v[80:83]
	v_mfma_f32_16x16x32_bf16 v[124:127], v[160:163], v[224:227], v[124:127]
	v_mfma_f32_16x16x32_bf16 v[120:123], v[168:171], v[224:227], v[120:123]
	v_mfma_f32_16x16x32_bf16 v[116:119], v[160:163], v[232:235], v[116:119]
	v_mfma_f32_16x16x32_bf16 v[112:115], v[168:171], v[232:235], v[112:115]
	v_mfma_f32_16x16x32_bf16 v[92:95], v[160:163], v[240:243], v[92:95]
	v_mfma_f32_16x16x32_bf16 v[88:91], v[168:171], v[240:243], v[88:91]
	v_mfma_f32_16x16x32_bf16 v[84:87], v[160:163], v[248:251], v[84:87]
	v_mfma_f32_16x16x32_bf16 v[80:83], v[168:171], v[248:251], v[80:83]
	s_setprio 0
	s_setprio 1
	v_mfma_f32_16x16x32_bf16 v[108:111], v[172:175], v[220:223], v[108:111]
	v_mfma_f32_16x16x32_bf16 v[104:107], v[212:215], v[220:223], v[104:107]
	v_mfma_f32_16x16x32_bf16 v[100:103], v[172:175], v[228:231], v[100:103]
	v_mfma_f32_16x16x32_bf16 v[96:99], v[212:215], v[228:231], v[96:99]
	v_mfma_f32_16x16x32_bf16 v[76:79], v[172:175], v[236:239], v[76:79]
	v_mfma_f32_16x16x32_bf16 v[72:75], v[212:215], v[236:239], v[72:75]
	v_mfma_f32_16x16x32_bf16 v[68:71], v[172:175], v[244:247], v[68:71]
	v_mfma_f32_16x16x32_bf16 v[64:67], v[212:215], v[244:247], v[64:67]
	v_mfma_f32_16x16x32_bf16 v[108:111], v[176:179], v[224:227], v[108:111]
	v_mfma_f32_16x16x32_bf16 v[104:107], v[216:219], v[224:227], v[104:107]
	v_mfma_f32_16x16x32_bf16 v[100:103], v[176:179], v[232:235], v[100:103]
	v_mfma_f32_16x16x32_bf16 v[96:99], v[216:219], v[232:235], v[96:99]
	v_mfma_f32_16x16x32_bf16 v[76:79], v[176:179], v[240:243], v[76:79]
	v_mfma_f32_16x16x32_bf16 v[72:75], v[216:219], v[240:243], v[72:75]
	v_mfma_f32_16x16x32_bf16 v[68:71], v[176:179], v[248:251], v[68:71]
	v_mfma_f32_16x16x32_bf16 v[64:67], v[216:219], v[248:251], v[64:67]
	s_setprio 0
	s_barrier
	s_add_i32 s55, s77, s64
	v_lshl_add_u64 v[204:205], s[48:49], 0, v[130:131]
	s_mov_b32 m0, s55
	ds_read_b128 v[220:223], v199 offset:16384
	ds_read_b128 v[224:227], v199 offset:17408
	ds_read_b128 v[228:231], v199 offset:18432
	ds_read_b128 v[232:235], v199 offset:19456
	ds_read_b128 v[236:239], v199 offset:20480
	ds_read_b128 v[240:243], v199 offset:21504
	ds_read_b128 v[244:247], v199 offset:22528
	ds_read_b128 v[248:251], v199 offset:23552
	global_load_lds_dwordx4 v[204:205], off
	s_add_i32 m0, s55, 0x2000
	s_add_u32 s56, s48, 0x4000
	v_lshl_add_u64 v[204:205], s[48:49], 0, v[134:135]
	s_addc_u32 s57, s49, 0
	s_add_i32 s55, s78, s64
	global_load_lds_dwordx4 v[204:205], off
	v_lshl_add_u64 v[204:205], s[56:57], 0, v[130:131]
	s_mov_b32 m0, s55
	v_lshl_add_u64 v[206:207], s[50:51], 0, v[132:133]
	global_load_lds_dwordx4 v[204:205], off
	v_lshl_add_u64 v[204:205], s[56:57], 0, v[134:135]
	s_add_i32 m0, s55, 0x2000
	s_nop 0
	global_load_lds_dwordx4 v[204:205], off
	v_lshl_add_u64 v[204:205], s[50:51], 0, v[128:129]
	s_mov_b32 m0, s65
	s_nop 0
	global_load_lds_dwordx4 v[204:205], off
	s_mov_b32 m0, s66
	s_nop 0
	global_load_lds_dwordx4 v[206:207], off
	s_waitcnt vmcnt(8)
	s_waitcnt lgkmcnt(0)
	s_barrier
	s_setprio 1
	s_waitcnt lgkmcnt(0)
	v_mfma_f32_16x16x32_bf16 v[60:63], v[156:159], v[220:223], v[60:63]
	v_mfma_f32_16x16x32_bf16 v[56:59], v[164:167], v[220:223], v[56:59]
	v_mfma_f32_16x16x32_bf16 v[52:55], v[156:159], v[228:231], v[52:55]
	v_mfma_f32_16x16x32_bf16 v[48:51], v[164:167], v[228:231], v[48:51]
	v_mfma_f32_16x16x32_bf16 v[28:31], v[156:159], v[236:239], v[28:31]
	v_mfma_f32_16x16x32_bf16 v[24:27], v[164:167], v[236:239], v[24:27]
	v_mfma_f32_16x16x32_bf16 v[20:23], v[156:159], v[244:247], v[20:23]
	v_mfma_f32_16x16x32_bf16 v[12:15], v[164:167], v[244:247], v[12:15]
	v_mfma_f32_16x16x32_bf16 v[60:63], v[160:163], v[224:227], v[60:63]
	v_mfma_f32_16x16x32_bf16 v[56:59], v[168:171], v[224:227], v[56:59]
	v_mfma_f32_16x16x32_bf16 v[52:55], v[160:163], v[232:235], v[52:55]
	v_mfma_f32_16x16x32_bf16 v[48:51], v[168:171], v[232:235], v[48:51]
	v_mfma_f32_16x16x32_bf16 v[28:31], v[160:163], v[240:243], v[28:31]
	v_mfma_f32_16x16x32_bf16 v[24:27], v[168:171], v[240:243], v[24:27]
	v_mfma_f32_16x16x32_bf16 v[20:23], v[160:163], v[248:251], v[20:23]
	v_mfma_f32_16x16x32_bf16 v[12:15], v[168:171], v[248:251], v[12:15]
	s_setprio 0
	s_setprio 1
	v_mfma_f32_16x16x32_bf16 v[44:47], v[172:175], v[220:223], v[44:47]
	v_mfma_f32_16x16x32_bf16 v[40:43], v[212:215], v[220:223], v[40:43]
	v_mfma_f32_16x16x32_bf16 v[36:39], v[172:175], v[228:231], v[36:39]
	v_mfma_f32_16x16x32_bf16 v[32:35], v[212:215], v[228:231], v[32:35]
	v_mfma_f32_16x16x32_bf16 v[16:19], v[172:175], v[236:239], v[16:19]
	v_mfma_f32_16x16x32_bf16 v[8:11], v[212:215], v[236:239], v[8:11]
	v_mfma_f32_16x16x32_bf16 v[4:7], v[172:175], v[244:247], v[4:7]
	v_mfma_f32_16x16x32_bf16 v[0:3], v[212:215], v[244:247], v[0:3]
	v_mfma_f32_16x16x32_bf16 v[44:47], v[176:179], v[224:227], v[44:47]
	v_mfma_f32_16x16x32_bf16 v[40:43], v[216:219], v[224:227], v[40:43]
	v_mfma_f32_16x16x32_bf16 v[36:39], v[176:179], v[232:235], v[36:39]
	v_mfma_f32_16x16x32_bf16 v[32:35], v[216:219], v[232:235], v[32:35]
	v_mfma_f32_16x16x32_bf16 v[16:19], v[176:179], v[240:243], v[16:19]
	v_mfma_f32_16x16x32_bf16 v[8:11], v[216:219], v[240:243], v[8:11]
	v_mfma_f32_16x16x32_bf16 v[4:7], v[176:179], v[248:251], v[4:7]
	v_mfma_f32_16x16x32_bf16 v[0:3], v[216:219], v[248:251], v[0:3]
	s_setprio 0
	s_barrier
	s_add_i32 s55, 0, 0x18000
	s_add_i32 s56, 0, 0x1c000
	v_add_u32_e32 v168, s55, v182
	v_add_u32_e32 v216, s56, v182
	ds_read_b128 v[156:159], v168
	ds_read_b128 v[160:163], v168 offset:1024
	ds_read_b128 v[164:167], v168 offset:2048
	ds_read_b128 v[168:171], v168 offset:3072
	ds_read_b128 v[172:175], v216
	ds_read_b128 v[176:179], v216 offset:1024
	ds_read_b128 v[212:215], v216 offset:2048
	ds_read_b128 v[216:219], v216 offset:3072
	s_add_u32 s50, s50, 0x40000
	s_addc_u32 s51, s51, 0
	s_mov_b32 m0, s67
	v_lshl_add_u64 v[252:253], s[50:51], 0, v[128:129]
	ds_read_b128 v[220:223], v199 offset:32768
	ds_read_b128 v[224:227], v199 offset:33792
	ds_read_b128 v[228:231], v199 offset:34816
	ds_read_b128 v[232:235], v199 offset:35840
	ds_read_b128 v[236:239], v199 offset:36864
	ds_read_b128 v[240:243], v199 offset:37888
	ds_read_b128 v[244:247], v199 offset:38912
	ds_read_b128 v[248:251], v199 offset:39936
	global_load_lds_dwordx4 v[252:253], off
	v_lshl_add_u64 v[252:253], s[50:51], 0, v[132:133]
	s_mov_b32 m0, s68
	s_nop 0
	global_load_lds_dwordx4 v[252:253], off
	s_waitcnt vmcnt(8)
	s_waitcnt lgkmcnt(0)
	s_barrier
	s_setprio 1
	s_waitcnt lgkmcnt(0)
	v_mfma_f32_16x16x32_bf16 v[124:127], v[156:159], v[220:223], v[124:127]
	v_mfma_f32_16x16x32_bf16 v[120:123], v[164:167], v[220:223], v[120:123]
	v_mfma_f32_16x16x32_bf16 v[116:119], v[156:159], v[228:231], v[116:119]
	v_mfma_f32_16x16x32_bf16 v[112:115], v[164:167], v[228:231], v[112:115]
	v_mfma_f32_16x16x32_bf16 v[92:95], v[156:159], v[236:239], v[92:95]
	v_mfma_f32_16x16x32_bf16 v[88:91], v[164:167], v[236:239], v[88:91]
	v_mfma_f32_16x16x32_bf16 v[84:87], v[156:159], v[244:247], v[84:87]
	v_mfma_f32_16x16x32_bf16 v[80:83], v[164:167], v[244:247], v[80:83]
	v_mfma_f32_16x16x32_bf16 v[124:127], v[160:163], v[224:227], v[124:127]
	v_mfma_f32_16x16x32_bf16 v[120:123], v[168:171], v[224:227], v[120:123]
	v_mfma_f32_16x16x32_bf16 v[116:119], v[160:163], v[232:235], v[116:119]
	v_mfma_f32_16x16x32_bf16 v[112:115], v[168:171], v[232:235], v[112:115]
	v_mfma_f32_16x16x32_bf16 v[92:95], v[160:163], v[240:243], v[92:95]
	v_mfma_f32_16x16x32_bf16 v[88:91], v[168:171], v[240:243], v[88:91]
	v_mfma_f32_16x16x32_bf16 v[84:87], v[160:163], v[248:251], v[84:87]
	v_mfma_f32_16x16x32_bf16 v[80:83], v[168:171], v[248:251], v[80:83]
	s_setprio 0
	s_setprio 1
	v_mfma_f32_16x16x32_bf16 v[108:111], v[172:175], v[220:223], v[108:111]
	v_mfma_f32_16x16x32_bf16 v[104:107], v[212:215], v[220:223], v[104:107]
	v_mfma_f32_16x16x32_bf16 v[100:103], v[172:175], v[228:231], v[100:103]
	v_mfma_f32_16x16x32_bf16 v[96:99], v[212:215], v[228:231], v[96:99]
	v_mfma_f32_16x16x32_bf16 v[76:79], v[172:175], v[236:239], v[76:79]
	v_mfma_f32_16x16x32_bf16 v[72:75], v[212:215], v[236:239], v[72:75]
	v_mfma_f32_16x16x32_bf16 v[68:71], v[172:175], v[244:247], v[68:71]
	v_mfma_f32_16x16x32_bf16 v[64:67], v[212:215], v[244:247], v[64:67]
	v_mfma_f32_16x16x32_bf16 v[108:111], v[176:179], v[224:227], v[108:111]
	v_mfma_f32_16x16x32_bf16 v[104:107], v[216:219], v[224:227], v[104:107]
	v_mfma_f32_16x16x32_bf16 v[100:103], v[176:179], v[232:235], v[100:103]
	v_mfma_f32_16x16x32_bf16 v[96:99], v[216:219], v[232:235], v[96:99]
	v_mfma_f32_16x16x32_bf16 v[76:79], v[176:179], v[240:243], v[76:79]
	v_mfma_f32_16x16x32_bf16 v[72:75], v[216:219], v[240:243], v[72:75]
	v_mfma_f32_16x16x32_bf16 v[68:71], v[176:179], v[248:251], v[68:71]
	v_mfma_f32_16x16x32_bf16 v[64:67], v[216:219], v[248:251], v[64:67]
	s_setprio 0
	s_barrier
	s_add_u32 s50, s48, 0x8000
	s_addc_u32 s51, s49, 0
	s_add_i32 s55, s55, s64
	v_lshl_add_u64 v[252:253], s[50:51], 0, v[130:131]
	s_mov_b32 m0, s55
	ds_read_b128 v[220:223], v199 offset:49152
	ds_read_b128 v[224:227], v199 offset:50176
	ds_read_b128 v[228:231], v199 offset:51200
	ds_read_b128 v[232:235], v199 offset:52224
	ds_read_b128 v[236:239], v199 offset:53248
	ds_read_b128 v[240:243], v199 offset:54272
	ds_read_b128 v[244:247], v199 offset:55296
	ds_read_b128 v[248:251], v199 offset:56320
	global_load_lds_dwordx4 v[252:253], off
	s_add_i32 m0, s55, 0x2000
	s_add_u32 s48, s48, 0xc000
	v_lshl_add_u64 v[252:253], s[50:51], 0, v[134:135]
	s_addc_u32 s49, s49, 0
	s_add_i32 s50, s56, s64
	global_load_lds_dwordx4 v[252:253], off
	v_lshl_add_u64 v[252:253], s[48:49], 0, v[130:131]
	s_mov_b32 m0, s50
	v_lshl_add_u64 v[204:205], v[204:205], 0, s[14:15]
	global_load_lds_dwordx4 v[252:253], off
	v_lshl_add_u64 v[252:253], s[48:49], 0, v[134:135]
	s_add_i32 m0, s50, 0x2000
	s_nop 0
	global_load_lds_dwordx4 v[252:253], off
	s_mov_b32 m0, s74
	s_nop 0
	global_load_lds_dwordx4 v[204:205], off
	v_lshl_add_u64 v[204:205], v[206:207], 0, s[14:15]
	s_mov_b32 m0, s75
	s_nop 0
	global_load_lds_dwordx4 v[204:205], off
	s_waitcnt vmcnt(8)
	s_waitcnt lgkmcnt(0)
	s_barrier
	s_setprio 1
	s_waitcnt lgkmcnt(0)
	v_mfma_f32_16x16x32_bf16 v[60:63], v[156:159], v[220:223], v[60:63]
	v_mfma_f32_16x16x32_bf16 v[56:59], v[164:167], v[220:223], v[56:59]
	v_mfma_f32_16x16x32_bf16 v[52:55], v[156:159], v[228:231], v[52:55]
	v_mfma_f32_16x16x32_bf16 v[48:51], v[164:167], v[228:231], v[48:51]
	v_mfma_f32_16x16x32_bf16 v[28:31], v[156:159], v[236:239], v[28:31]
	v_mfma_f32_16x16x32_bf16 v[24:27], v[164:167], v[236:239], v[24:27]
	v_mfma_f32_16x16x32_bf16 v[20:23], v[156:159], v[244:247], v[20:23]
	v_mfma_f32_16x16x32_bf16 v[12:15], v[164:167], v[244:247], v[12:15]
	v_mfma_f32_16x16x32_bf16 v[60:63], v[160:163], v[224:227], v[60:63]
	v_mfma_f32_16x16x32_bf16 v[56:59], v[168:171], v[224:227], v[56:59]
	v_mfma_f32_16x16x32_bf16 v[52:55], v[160:163], v[232:235], v[52:55]
	v_mfma_f32_16x16x32_bf16 v[48:51], v[168:171], v[232:235], v[48:51]
	v_mfma_f32_16x16x32_bf16 v[28:31], v[160:163], v[240:243], v[28:31]
	v_mfma_f32_16x16x32_bf16 v[24:27], v[168:171], v[240:243], v[24:27]
	v_mfma_f32_16x16x32_bf16 v[20:23], v[160:163], v[248:251], v[20:23]
	v_mfma_f32_16x16x32_bf16 v[12:15], v[168:171], v[248:251], v[12:15]
	s_setprio 0
	s_setprio 1
	v_mfma_f32_16x16x32_bf16 v[44:47], v[172:175], v[220:223], v[44:47]
	v_mfma_f32_16x16x32_bf16 v[40:43], v[212:215], v[220:223], v[40:43]
	v_mfma_f32_16x16x32_bf16 v[36:39], v[172:175], v[228:231], v[36:39]
	v_mfma_f32_16x16x32_bf16 v[32:35], v[212:215], v[228:231], v[32:35]
	v_mfma_f32_16x16x32_bf16 v[16:19], v[172:175], v[236:239], v[16:19]
	v_mfma_f32_16x16x32_bf16 v[8:11], v[212:215], v[236:239], v[8:11]
	v_mfma_f32_16x16x32_bf16 v[4:7], v[172:175], v[244:247], v[4:7]
	v_mfma_f32_16x16x32_bf16 v[0:3], v[212:215], v[244:247], v[0:3]
	v_mfma_f32_16x16x32_bf16 v[44:47], v[176:179], v[224:227], v[44:47]
	v_mfma_f32_16x16x32_bf16 v[40:43], v[216:219], v[224:227], v[40:43]
	v_mfma_f32_16x16x32_bf16 v[36:39], v[176:179], v[232:235], v[36:39]
	v_mfma_f32_16x16x32_bf16 v[32:35], v[216:219], v[232:235], v[32:35]
	v_mfma_f32_16x16x32_bf16 v[16:19], v[176:179], v[240:243], v[16:19]
	v_mfma_f32_16x16x32_bf16 v[8:11], v[216:219], v[240:243], v[8:11]
	v_mfma_f32_16x16x32_bf16 v[4:7], v[176:179], v[248:251], v[4:7]
	v_mfma_f32_16x16x32_bf16 v[0:3], v[216:219], v[248:251], v[0:3]
	s_setprio 0
	s_add_i32 s54, s54, 2
	s_add_u32 s52, s52, 0x10000
	s_addc_u32 s53, s53, 0
	s_add_u32 s46, s46, 0x100
	s_addc_u32 s47, s47, 0
	s_cmp_gt_u32 s54, 13
	s_cbranch_scc0 .Lrot13
	s_barrier
	s_and_b64 vcc, exec, s[16:17]
	s_cbranch_vccz .LBB0_2361
	s_barrier

.Lrot14:
	s_barrier
.LBB0_2440:
	ds_read_b128 v[168:171], v165
	ds_read_b128 v[172:175], v165 offset:1024
	ds_read_b128 v[176:179], v165 offset:2048
	ds_read_b128 v[180:183], v165 offset:3072
	ds_read_b128 v[184:187], v166
	ds_read_b128 v[188:191], v166 offset:1024
	ds_read_b128 v[192:195], v166 offset:2048
	ds_read_b128 v[196:199], v166 offset:3072
	s_add_u32 s22, s20, 0xfffc0080
	s_addc_u32 s23, s21, -1
	s_cmp_eq_u32 s49, 12
	s_cselect_b32 s25, s9, s23
	s_cselect_b32 s24, s45, s22
	s_cselect_b32 s23, s11, s48
	s_cselect_b32 s22, s46, s47
	v_lshl_add_u64 v[162:163], s[20:21], 0, v[156:157]
	s_add_i32 m0, s17, 0xc000
	ds_read_b128 v[210:213], v167
	ds_read_b128 v[214:217], v167 offset:1024
	ds_read_b128 v[218:221], v167 offset:2048
	ds_read_b128 v[222:225], v167 offset:3072
	ds_read_b128 v[226:229], v167 offset:4096
	ds_read_b128 v[230:233], v167 offset:5120
	ds_read_b128 v[234:237], v167 offset:6144
	ds_read_b128 v[238:241], v167 offset:7168
	global_load_lds_dwordx4 v[162:163], off
	v_lshl_add_u64 v[162:163], s[20:21], 0, v[154:155]
	s_add_i32 m0, s17, 0xe000
	s_nop 0
	global_load_lds_dwordx4 v[162:163], off
	s_waitcnt vmcnt(8)
	s_waitcnt lgkmcnt(0)
	s_barrier
	s_setprio 1
	s_waitcnt lgkmcnt(0)
	v_mfma_f32_16x16x32_bf16 v[124:127], v[168:171], v[210:213], v[124:127]
	v_mfma_f32_16x16x32_bf16 v[116:119], v[176:179], v[210:213], v[116:119]
	v_mfma_f32_16x16x32_bf16 v[108:111], v[168:171], v[218:221], v[108:111]
	v_mfma_f32_16x16x32_bf16 v[100:103], v[176:179], v[218:221], v[100:103]
	v_mfma_f32_16x16x32_bf16 v[92:95], v[168:171], v[226:229], v[92:95]
	v_mfma_f32_16x16x32_bf16 v[84:87], v[176:179], v[226:229], v[84:87]
	v_mfma_f32_16x16x32_bf16 v[76:79], v[168:171], v[234:237], v[76:79]
	v_mfma_f32_16x16x32_bf16 v[68:71], v[176:179], v[234:237], v[68:71]
	v_mfma_f32_16x16x32_bf16 v[124:127], v[172:175], v[214:217], v[124:127]
	v_mfma_f32_16x16x32_bf16 v[116:119], v[180:183], v[214:217], v[116:119]
	v_mfma_f32_16x16x32_bf16 v[108:111], v[172:175], v[222:225], v[108:111]
	v_mfma_f32_16x16x32_bf16 v[100:103], v[180:183], v[222:225], v[100:103]
	v_mfma_f32_16x16x32_bf16 v[92:95], v[172:175], v[230:233], v[92:95]
	v_mfma_f32_16x16x32_bf16 v[84:87], v[180:183], v[230:233], v[84:87]
	v_mfma_f32_16x16x32_bf16 v[76:79], v[172:175], v[238:241], v[76:79]
	v_mfma_f32_16x16x32_bf16 v[68:71], v[180:183], v[238:241], v[68:71]
	s_setprio 0
	s_setprio 1
	v_mfma_f32_16x16x32_bf16 v[120:123], v[184:187], v[210:213], v[120:123]
	v_mfma_f32_16x16x32_bf16 v[112:115], v[192:195], v[210:213], v[112:115]
	v_mfma_f32_16x16x32_bf16 v[104:107], v[184:187], v[218:221], v[104:107]
	v_mfma_f32_16x16x32_bf16 v[96:99], v[192:195], v[218:221], v[96:99]
	v_mfma_f32_16x16x32_bf16 v[88:91], v[184:187], v[226:229], v[88:91]
	v_mfma_f32_16x16x32_bf16 v[80:83], v[192:195], v[226:229], v[80:83]
	v_mfma_f32_16x16x32_bf16 v[72:75], v[184:187], v[234:237], v[72:75]
	v_mfma_f32_16x16x32_bf16 v[64:67], v[192:195], v[234:237], v[64:67]
	v_mfma_f32_16x16x32_bf16 v[120:123], v[188:191], v[214:217], v[120:123]
	v_mfma_f32_16x16x32_bf16 v[112:115], v[196:199], v[214:217], v[112:115]
	v_mfma_f32_16x16x32_bf16 v[104:107], v[188:191], v[222:225], v[104:107]
	v_mfma_f32_16x16x32_bf16 v[96:99], v[196:199], v[222:225], v[96:99]
	v_mfma_f32_16x16x32_bf16 v[88:91], v[188:191], v[230:233], v[88:91]
	v_mfma_f32_16x16x32_bf16 v[80:83], v[196:199], v[230:233], v[80:83]
	v_mfma_f32_16x16x32_bf16 v[72:75], v[188:191], v[238:241], v[72:75]
	v_mfma_f32_16x16x32_bf16 v[64:67], v[196:199], v[238:241], v[64:67]
	s_setprio 0
	s_barrier
	s_add_i32 s50, s43, s33
	v_lshl_add_u64 v[162:163], s[22:23], 0, v[132:133]
	s_mov_b32 m0, s50
	s_cmp_lg_u32 s54, 0
	s_cbranch_scc1 .Lts1_skip1
	ds_read_b128 v[210:213], v167 offset:16384
	ds_read_b128 v[214:217], v167 offset:17408
	ds_read_b128 v[218:221], v167 offset:18432
	ds_read_b128 v[222:225], v167 offset:19456
	ds_read_b128 v[226:229], v167 offset:20480
	ds_read_b128 v[230:233], v167 offset:21504
	ds_read_b128 v[234:237], v167 offset:22528
	ds_read_b128 v[238:241], v167 offset:23552

.LBB0_2518:
	s_add_u32 s62, s30, 0x10000
	s_addc_u32 s63, s31, 0
	s_add_u32 s30, s34, 0xc000
	v_mov_b32_e32 v0, 0
	s_addc_u32 s31, s35, 0
	s_mov_b32 s64, -2
	v_mov_b32_e32 v1, v0
	v_mov_b32_e32 v2, v0
	v_mov_b32_e32 v3, v0
	v_mov_b32_e32 v4, v0
	v_mov_b32_e32 v5, v0
	v_mov_b32_e32 v6, v0
	v_mov_b32_e32 v7, v0
	v_mov_b32_e32 v8, v0
	v_mov_b32_e32 v9, v0
	v_mov_b32_e32 v10, v0
	v_mov_b32_e32 v11, v0
	v_mov_b32_e32 v16, v0
	v_mov_b32_e32 v17, v0
	v_mov_b32_e32 v18, v0
	v_mov_b32_e32 v19, v0
	v_mov_b32_e32 v32, v0
	v_mov_b32_e32 v33, v0
	v_mov_b32_e32 v34, v0
	v_mov_b32_e32 v35, v0
	v_mov_b32_e32 v36, v0
	v_mov_b32_e32 v37, v0
	v_mov_b32_e32 v38, v0
	v_mov_b32_e32 v39, v0
	v_mov_b32_e32 v40, v0
	v_mov_b32_e32 v41, v0
	v_mov_b32_e32 v42, v0
	v_mov_b32_e32 v43, v0
	v_mov_b32_e32 v44, v0
	v_mov_b32_e32 v45, v0
	v_mov_b32_e32 v46, v0
	v_mov_b32_e32 v47, v0
	v_mov_b32_e32 v12, v0
	v_mov_b32_e32 v13, v0
	v_mov_b32_e32 v14, v0
	v_mov_b32_e32 v15, v0
	v_mov_b32_e32 v20, v0
	v_mov_b32_e32 v21, v0
	v_mov_b32_e32 v22, v0
	v_mov_b32_e32 v23, v0
	v_mov_b32_e32 v24, v0
	v_mov_b32_e32 v25, v0
	v_mov_b32_e32 v26, v0
	v_mov_b32_e32 v27, v0
	v_mov_b32_e32 v28, v0
	v_mov_b32_e32 v29, v0
	v_mov_b32_e32 v30, v0
	v_mov_b32_e32 v31, v0
	v_mov_b32_e32 v48, v0
	v_mov_b32_e32 v49, v0
	v_mov_b32_e32 v50, v0
	v_mov_b32_e32 v51, v0
	v_mov_b32_e32 v52, v0
	v_mov_b32_e32 v53, v0
	v_mov_b32_e32 v54, v0
	v_mov_b32_e32 v55, v0
	v_mov_b32_e32 v56, v0
	v_mov_b32_e32 v57, v0
	v_mov_b32_e32 v58, v0
	v_mov_b32_e32 v59, v0
	v_mov_b32_e32 v60, v0
	v_mov_b32_e32 v61, v0
	v_mov_b32_e32 v62, v0
	v_mov_b32_e32 v63, v0
	v_mov_b32_e32 v64, v0
	v_mov_b32_e32 v65, v0
	v_mov_b32_e32 v66, v0
	v_mov_b32_e32 v67, v0
	v_mov_b32_e32 v68, v0
	v_mov_b32_e32 v69, v0
	v_mov_b32_e32 v70, v0
	v_mov_b32_e32 v71, v0
	v_mov_b32_e32 v72, v0
	v_mov_b32_e32 v73, v0
	v_mov_b32_e32 v74, v0
	v_mov_b32_e32 v75, v0
	v_mov_b32_e32 v76, v0
	v_mov_b32_e32 v77, v0
	v_mov_b32_e32 v78, v0
	v_mov_b32_e32 v79, v0
	v_mov_b32_e32 v96, v0
	v_mov_b32_e32 v97, v0
	v_mov_b32_e32 v98, v0
	v_mov_b32_e32 v99, v0
	v_mov_b32_e32 v100, v0
	v_mov_b32_e32 v101, v0
	v_mov_b32_e32 v102, v0
	v_mov_b32_e32 v103, v0
	v_mov_b32_e32 v104, v0
	v_mov_b32_e32 v105, v0
	v_mov_b32_e32 v106, v0
	v_mov_b32_e32 v107, v0
	v_mov_b32_e32 v108, v0
	v_mov_b32_e32 v109, v0
	v_mov_b32_e32 v110, v0
	v_mov_b32_e32 v111, v0
	v_mov_b32_e32 v80, v0
	v_mov_b32_e32 v81, v0
	v_mov_b32_e32 v82, v0
	v_mov_b32_e32 v83, v0
	v_mov_b32_e32 v84, v0
	v_mov_b32_e32 v85, v0
	v_mov_b32_e32 v86, v0
	v_mov_b32_e32 v87, v0
	v_mov_b32_e32 v88, v0
	v_mov_b32_e32 v89, v0
	v_mov_b32_e32 v90, v0
	v_mov_b32_e32 v91, v0
	v_mov_b32_e32 v92, v0
	v_mov_b32_e32 v93, v0
	v_mov_b32_e32 v94, v0
	v_mov_b32_e32 v95, v0
	v_mov_b32_e32 v112, v0
	v_mov_b32_e32 v113, v0
	v_mov_b32_e32 v114, v0
	v_mov_b32_e32 v115, v0
	v_mov_b32_e32 v116, v0
	v_mov_b32_e32 v117, v0
	v_mov_b32_e32 v118, v0
	v_mov_b32_e32 v119, v0
	v_mov_b32_e32 v120, v0
	v_mov_b32_e32 v121, v0
	v_mov_b32_e32 v122, v0
	v_mov_b32_e32 v123, v0
	v_mov_b32_e32 v124, v0
	v_mov_b32_e32 v125, v0
	v_mov_b32_e32 v126, v0
	v_mov_b32_e32 v127, v0
	s_branch .LBB0_2519

.LBB0_2519:
	ds_read_b128 v[144:147], v178
	ds_read_b128 v[148:151], v178 offset:1024
	ds_read_b128 v[152:155], v178 offset:2048
	ds_read_b128 v[156:159], v178 offset:3072
	ds_read_b128 v[160:163], v179
	ds_read_b128 v[164:167], v179 offset:1024
	ds_read_b128 v[182:185], v179 offset:2048
	ds_read_b128 v[186:189], v179 offset:3072
	s_add_u32 s34, s30, 0x4000
	s_addc_u32 s35, s31, 0
	s_cmp_eq_u32 s64, 40
	s_cselect_b32 s38, s4, s34
	s_cselect_b32 s39, s5, s35
	s_cselect_b32 s36, s28, s62
	s_cselect_b32 s37, s29, s63
	s_add_u32 s34, s38, 0x8000
	s_addc_u32 s35, s39, 0
	v_lshl_add_u64 v[222:223], s[30:31], 0, v[138:139]
	s_add_i32 m0, s42, 0xc000
	ds_read_b128 v[190:193], v180
	ds_read_b128 v[194:197], v180 offset:1024
	ds_read_b128 v[198:201], v180 offset:2048
	ds_read_b128 v[202:205], v180 offset:3072
	ds_read_b128 v[206:209], v180 offset:4096
	ds_read_b128 v[210:213], v180 offset:5120
	ds_read_b128 v[214:217], v180 offset:6144
	ds_read_b128 v[218:221], v180 offset:7168
	global_load_lds_dwordx4 v[222:223], off
	v_lshl_add_u64 v[222:223], s[30:31], 0, v[136:137]
	s_add_i32 m0, s42, 0xe000
	s_nop 0
	global_load_lds_dwordx4 v[222:223], off
	s_waitcnt vmcnt(8)
	s_waitcnt lgkmcnt(0)
	s_barrier
	s_setprio 1
	s_waitcnt lgkmcnt(0)
	v_mfma_f32_16x16x32_bf16 v[124:127], v[144:147], v[190:193], v[124:127]
	v_mfma_f32_16x16x32_bf16 v[120:123], v[152:155], v[190:193], v[120:123]
	v_mfma_f32_16x16x32_bf16 v[116:119], v[144:147], v[198:201], v[116:119]
	v_mfma_f32_16x16x32_bf16 v[112:115], v[152:155], v[198:201], v[112:115]
	v_mfma_f32_16x16x32_bf16 v[92:95], v[144:147], v[206:209], v[92:95]
	v_mfma_f32_16x16x32_bf16 v[88:91], v[152:155], v[206:209], v[88:91]
	v_mfma_f32_16x16x32_bf16 v[84:87], v[144:147], v[214:217], v[84:87]
	v_mfma_f32_16x16x32_bf16 v[80:83], v[152:155], v[214:217], v[80:83]
	v_mfma_f32_16x16x32_bf16 v[124:127], v[148:151], v[194:197], v[124:127]
	v_mfma_f32_16x16x32_bf16 v[120:123], v[156:159], v[194:197], v[120:123]
	v_mfma_f32_16x16x32_bf16 v[116:119], v[148:151], v[202:205], v[116:119]
	v_mfma_f32_16x16x32_bf16 v[112:115], v[156:159], v[202:205], v[112:115]
	v_mfma_f32_16x16x32_bf16 v[92:95], v[148:151], v[210:213], v[92:95]
	v_mfma_f32_16x16x32_bf16 v[88:91], v[156:159], v[210:213], v[88:91]
	v_mfma_f32_16x16x32_bf16 v[84:87], v[148:151], v[218:221], v[84:87]
	v_mfma_f32_16x16x32_bf16 v[80:83], v[156:159], v[218:221], v[80:83]
	s_setprio 0
	s_setprio 1
	v_mfma_f32_16x16x32_bf16 v[108:111], v[160:163], v[190:193], v[108:111]
	v_mfma_f32_16x16x32_bf16 v[104:107], v[182:185], v[190:193], v[104:107]
	v_mfma_f32_16x16x32_bf16 v[100:103], v[160:163], v[198:201], v[100:103]
	v_mfma_f32_16x16x32_bf16 v[96:99], v[182:185], v[198:201], v[96:99]
	v_mfma_f32_16x16x32_bf16 v[76:79], v[160:163], v[206:209], v[76:79]
	v_mfma_f32_16x16x32_bf16 v[72:75], v[182:185], v[206:209], v[72:75]
	v_mfma_f32_16x16x32_bf16 v[68:71], v[160:163], v[214:217], v[68:71]
	v_mfma_f32_16x16x32_bf16 v[64:67], v[182:185], v[214:217], v[64:67]
	v_mfma_f32_16x16x32_bf16 v[108:111], v[164:167], v[194:197], v[108:111]
	v_mfma_f32_16x16x32_bf16 v[104:107], v[186:189], v[194:197], v[104:107]
	v_mfma_f32_16x16x32_bf16 v[100:103], v[164:167], v[202:205], v[100:103]
	v_mfma_f32_16x16x32_bf16 v[96:99], v[186:189], v[202:205], v[96:99]
	v_mfma_f32_16x16x32_bf16 v[76:79], v[164:167], v[210:213], v[76:79]
	v_mfma_f32_16x16x32_bf16 v[72:75], v[186:189], v[210:213], v[72:75]
	v_mfma_f32_16x16x32_bf16 v[68:71], v[164:167], v[218:221], v[68:71]
	v_mfma_f32_16x16x32_bf16 v[64:67], v[186:189], v[218:221], v[64:67]
	s_setprio 0
	s_barrier
	s_add_i32 s65, s55, s41
	v_lshl_add_u64 v[222:223], s[36:37], 0, v[128:129]
	s_mov_b32 m0, s65
	ds_read_b128 v[190:193], v180 offset:16384
	ds_read_b128 v[194:197], v180 offset:17408
	ds_read_b128 v[198:201], v180 offset:18432
	ds_read_b128 v[202:205], v180 offset:19456
	ds_read_b128 v[206:209], v180 offset:20480
	ds_read_b128 v[210:213], v180 offset:21504
	ds_read_b128 v[214:217], v180 offset:22528
	ds_read_b128 v[218:221], v180 offset:23552
	global_load_lds_dwordx4 v[222:223], off
	s_add_i32 m0, s65, 0x2000
	s_add_u32 s66, s36, 0x4000
	v_lshl_add_u64 v[222:223], s[36:37], 0, v[130:131]
	s_addc_u32 s67, s37, 0
	s_add_i32 s65, s56, s41
	global_load_lds_dwordx4 v[222:223], off
	v_lshl_add_u64 v[222:223], s[66:67], 0, v[128:129]
	s_mov_b32 m0, s65
	s_nop 0
	global_load_lds_dwordx4 v[222:223], off
	v_lshl_add_u64 v[222:223], s[66:67], 0, v[130:131]
	s_add_i32 m0, s65, 0x2000
	s_nop 0
	global_load_lds_dwordx4 v[222:223], off
	v_lshl_add_u64 v[222:223], s[38:39], 0, v[128:129]
	s_mov_b32 m0, s42
	s_nop 0
	global_load_lds_dwordx4 v[222:223], off
	v_lshl_add_u64 v[222:223], s[38:39], 0, v[130:131]
	s_mov_b32 m0, s43
	s_nop 0
	global_load_lds_dwordx4 v[222:223], off
	s_waitcnt vmcnt(8)
	s_waitcnt lgkmcnt(0)
	s_barrier
	s_setprio 1
	s_waitcnt lgkmcnt(0)
	v_mfma_f32_16x16x32_bf16 v[60:63], v[144:147], v[190:193], v[60:63]
	v_mfma_f32_16x16x32_bf16 v[56:59], v[152:155], v[190:193], v[56:59]
	v_mfma_f32_16x16x32_bf16 v[52:55], v[144:147], v[198:201], v[52:55]
	v_mfma_f32_16x16x32_bf16 v[48:51], v[152:155], v[198:201], v[48:51]
	v_mfma_f32_16x16x32_bf16 v[28:31], v[144:147], v[206:209], v[28:31]
	v_mfma_f32_16x16x32_bf16 v[24:27], v[152:155], v[206:209], v[24:27]
	v_mfma_f32_16x16x32_bf16 v[20:23], v[144:147], v[214:217], v[20:23]
	v_mfma_f32_16x16x32_bf16 v[12:15], v[152:155], v[214:217], v[12:15]
	v_mfma_f32_16x16x32_bf16 v[60:63], v[148:151], v[194:197], v[60:63]
	v_mfma_f32_16x16x32_bf16 v[56:59], v[156:159], v[194:197], v[56:59]
	v_mfma_f32_16x16x32_bf16 v[52:55], v[148:151], v[202:205], v[52:55]
	v_mfma_f32_16x16x32_bf16 v[48:51], v[156:159], v[202:205], v[48:51]
	v_mfma_f32_16x16x32_bf16 v[28:31], v[148:151], v[210:213], v[28:31]
	v_mfma_f32_16x16x32_bf16 v[24:27], v[156:159], v[210:213], v[24:27]
	v_mfma_f32_16x16x32_bf16 v[20:23], v[148:151], v[218:221], v[20:23]
	v_mfma_f32_16x16x32_bf16 v[12:15], v[156:159], v[218:221], v[12:15]
	s_setprio 0
	s_setprio 1
	v_mfma_f32_16x16x32_bf16 v[44:47], v[160:163], v[190:193], v[44:47]
	v_mfma_f32_16x16x32_bf16 v[40:43], v[182:185], v[190:193], v[40:43]
	v_mfma_f32_16x16x32_bf16 v[36:39], v[160:163], v[198:201], v[36:39]
	v_mfma_f32_16x16x32_bf16 v[32:35], v[182:185], v[198:201], v[32:35]
	v_mfma_f32_16x16x32_bf16 v[16:19], v[160:163], v[206:209], v[16:19]
	v_mfma_f32_16x16x32_bf16 v[8:11], v[182:185], v[206:209], v[8:11]
	v_mfma_f32_16x16x32_bf16 v[4:7], v[160:163], v[214:217], v[4:7]
	v_mfma_f32_16x16x32_bf16 v[0:3], v[182:185], v[214:217], v[0:3]
	v_mfma_f32_16x16x32_bf16 v[44:47], v[164:167], v[194:197], v[44:47]
	v_mfma_f32_16x16x32_bf16 v[40:43], v[186:189], v[194:197], v[40:43]
	v_mfma_f32_16x16x32_bf16 v[36:39], v[164:167], v[202:205], v[36:39]
	v_mfma_f32_16x16x32_bf16 v[32:35], v[186:189], v[202:205], v[32:35]
	v_mfma_f32_16x16x32_bf16 v[16:19], v[164:167], v[210:213], v[16:19]
	v_mfma_f32_16x16x32_bf16 v[8:11], v[186:189], v[210:213], v[8:11]
	v_mfma_f32_16x16x32_bf16 v[4:7], v[164:167], v[218:221], v[4:7]
	v_mfma_f32_16x16x32_bf16 v[0:3], v[186:189], v[218:221], v[0:3]
	s_setprio 0
	s_barrier
	s_add_i32 s65, 0, 0x18000
	s_add_i32 s66, 0, 0x1c000
	v_add_u32_e32 v156, s65, v170
	v_add_u32_e32 v186, s66, v170
	ds_read_b128 v[144:147], v156
	ds_read_b128 v[148:151], v156 offset:1024
	ds_read_b128 v[152:155], v156 offset:2048
	ds_read_b128 v[156:159], v156 offset:3072
	ds_read_b128 v[160:163], v186
	ds_read_b128 v[164:167], v186 offset:1024
	ds_read_b128 v[182:185], v186 offset:2048
	ds_read_b128 v[186:189], v186 offset:3072
	s_add_u32 s38, s38, 0x4000
	s_addc_u32 s39, s39, 0
	s_mov_b32 m0, s44
	v_lshl_add_u64 v[222:223], s[38:39], 0, v[128:129]
	ds_read_b128 v[190:193], v180 offset:32768
	ds_read_b128 v[194:197], v180 offset:33792
	ds_read_b128 v[198:201], v180 offset:34816
	ds_read_b128 v[202:205], v180 offset:35840
	ds_read_b128 v[206:209], v180 offset:36864
	ds_read_b128 v[210:213], v180 offset:37888
	ds_read_b128 v[214:217], v180 offset:38912
	ds_read_b128 v[218:221], v180 offset:39936
	global_load_lds_dwordx4 v[222:223], off
	v_lshl_add_u64 v[222:223], s[38:39], 0, v[130:131]
	s_mov_b32 m0, s45
	s_nop 0
	global_load_lds_dwordx4 v[222:223], off
	s_waitcnt vmcnt(8)
	s_waitcnt lgkmcnt(0)
	s_barrier
	s_setprio 1
	s_waitcnt lgkmcnt(0)
	v_mfma_f32_16x16x32_bf16 v[124:127], v[144:147], v[190:193], v[124:127]
	v_mfma_f32_16x16x32_bf16 v[120:123], v[152:155], v[190:193], v[120:123]
	v_mfma_f32_16x16x32_bf16 v[116:119], v[144:147], v[198:201], v[116:119]
	v_mfma_f32_16x16x32_bf16 v[112:115], v[152:155], v[198:201], v[112:115]
	v_mfma_f32_16x16x32_bf16 v[92:95], v[144:147], v[206:209], v[92:95]
	v_mfma_f32_16x16x32_bf16 v[88:91], v[152:155], v[206:209], v[88:91]
	v_mfma_f32_16x16x32_bf16 v[84:87], v[144:147], v[214:217], v[84:87]
	v_mfma_f32_16x16x32_bf16 v[80:83], v[152:155], v[214:217], v[80:83]
	v_mfma_f32_16x16x32_bf16 v[124:127], v[148:151], v[194:197], v[124:127]
	v_mfma_f32_16x16x32_bf16 v[120:123], v[156:159], v[194:197], v[120:123]
	v_mfma_f32_16x16x32_bf16 v[116:119], v[148:151], v[202:205], v[116:119]
	v_mfma_f32_16x16x32_bf16 v[112:115], v[156:159], v[202:205], v[112:115]
	v_mfma_f32_16x16x32_bf16 v[92:95], v[148:151], v[210:213], v[92:95]
	v_mfma_f32_16x16x32_bf16 v[88:91], v[156:159], v[210:213], v[88:91]
	v_mfma_f32_16x16x32_bf16 v[84:87], v[148:151], v[218:221], v[84:87]
	v_mfma_f32_16x16x32_bf16 v[80:83], v[156:159], v[218:221], v[80:83]
	s_setprio 0
	s_setprio 1
	v_mfma_f32_16x16x32_bf16 v[108:111], v[160:163], v[190:193], v[108:111]
	v_mfma_f32_16x16x32_bf16 v[104:107], v[182:185], v[190:193], v[104:107]
	v_mfma_f32_16x16x32_bf16 v[100:103], v[160:163], v[198:201], v[100:103]
	v_mfma_f32_16x16x32_bf16 v[96:99], v[182:185], v[198:201], v[96:99]
	v_mfma_f32_16x16x32_bf16 v[76:79], v[160:163], v[206:209], v[76:79]
	v_mfma_f32_16x16x32_bf16 v[72:75], v[182:185], v[206:209], v[72:75]
	v_mfma_f32_16x16x32_bf16 v[68:71], v[160:163], v[214:217], v[68:71]
	v_mfma_f32_16x16x32_bf16 v[64:67], v[182:185], v[214:217], v[64:67]
	v_mfma_f32_16x16x32_bf16 v[108:111], v[164:167], v[194:197], v[108:111]
	v_mfma_f32_16x16x32_bf16 v[104:107], v[186:189], v[194:197], v[104:107]
	v_mfma_f32_16x16x32_bf16 v[100:103], v[164:167], v[202:205], v[100:103]
	v_mfma_f32_16x16x32_bf16 v[96:99], v[186:189], v[202:205], v[96:99]
	v_mfma_f32_16x16x32_bf16 v[76:79], v[164:167], v[210:213], v[76:79]
	v_mfma_f32_16x16x32_bf16 v[72:75], v[186:189], v[210:213], v[72:75]
	v_mfma_f32_16x16x32_bf16 v[68:71], v[164:167], v[218:221], v[68:71]
	v_mfma_f32_16x16x32_bf16 v[64:67], v[186:189], v[218:221], v[64:67]
	s_setprio 0
	s_barrier
	s_add_u32 s38, s36, 0x8000
	s_addc_u32 s39, s37, 0
	s_add_i32 s65, s65, s41
	v_lshl_add_u64 v[222:223], s[38:39], 0, v[128:129]
	s_mov_b32 m0, s65
	ds_read_b128 v[190:193], v180 offset:49152
	ds_read_b128 v[194:197], v180 offset:50176
	ds_read_b128 v[198:201], v180 offset:51200
	ds_read_b128 v[202:205], v180 offset:52224
	ds_read_b128 v[206:209], v180 offset:53248
	ds_read_b128 v[210:213], v180 offset:54272
	ds_read_b128 v[214:217], v180 offset:55296
	ds_read_b128 v[218:221], v180 offset:56320
	global_load_lds_dwordx4 v[222:223], off
	s_add_i32 m0, s65, 0x2000
	s_add_u32 s36, s36, 0xc000
	v_lshl_add_u64 v[222:223], s[38:39], 0, v[130:131]
	s_addc_u32 s37, s37, 0
	s_add_i32 s38, s66, s41
	global_load_lds_dwordx4 v[222:223], off
	v_lshl_add_u64 v[222:223], s[36:37], 0, v[128:129]
	s_mov_b32 m0, s38
	s_nop 0
	global_load_lds_dwordx4 v[222:223], off
	v_lshl_add_u64 v[222:223], s[36:37], 0, v[130:131]
	s_add_i32 m0, s38, 0x2000
	s_nop 0
	global_load_lds_dwordx4 v[222:223], off
	v_lshl_add_u64 v[222:223], s[34:35], 0, v[128:129]
	s_mov_b32 m0, s51
	s_nop 0
	global_load_lds_dwordx4 v[222:223], off
	v_lshl_add_u64 v[222:223], s[34:35], 0, v[130:131]
	s_mov_b32 m0, s52
	s_nop 0
	global_load_lds_dwordx4 v[222:223], off
	s_waitcnt vmcnt(8)
	s_waitcnt lgkmcnt(0)
	s_barrier
	s_setprio 1
	s_waitcnt lgkmcnt(0)
	v_mfma_f32_16x16x32_bf16 v[60:63], v[144:147], v[190:193], v[60:63]
	v_mfma_f32_16x16x32_bf16 v[56:59], v[152:155], v[190:193], v[56:59]
	v_mfma_f32_16x16x32_bf16 v[52:55], v[144:147], v[198:201], v[52:55]
	v_mfma_f32_16x16x32_bf16 v[48:51], v[152:155], v[198:201], v[48:51]
	v_mfma_f32_16x16x32_bf16 v[28:31], v[144:147], v[206:209], v[28:31]
	v_mfma_f32_16x16x32_bf16 v[24:27], v[152:155], v[206:209], v[24:27]
	v_mfma_f32_16x16x32_bf16 v[20:23], v[144:147], v[214:217], v[20:23]
	v_mfma_f32_16x16x32_bf16 v[12:15], v[152:155], v[214:217], v[12:15]
	v_mfma_f32_16x16x32_bf16 v[60:63], v[148:151], v[194:197], v[60:63]
	v_mfma_f32_16x16x32_bf16 v[56:59], v[156:159], v[194:197], v[56:59]
	v_mfma_f32_16x16x32_bf16 v[52:55], v[148:151], v[202:205], v[52:55]
	v_mfma_f32_16x16x32_bf16 v[48:51], v[156:159], v[202:205], v[48:51]
	v_mfma_f32_16x16x32_bf16 v[28:31], v[148:151], v[210:213], v[28:31]
	v_mfma_f32_16x16x32_bf16 v[24:27], v[156:159], v[210:213], v[24:27]
	v_mfma_f32_16x16x32_bf16 v[20:23], v[148:151], v[218:221], v[20:23]
	v_mfma_f32_16x16x32_bf16 v[12:15], v[156:159], v[218:221], v[12:15]
	s_setprio 0
	s_setprio 1
	v_mfma_f32_16x16x32_bf16 v[44:47], v[160:163], v[190:193], v[44:47]
	v_mfma_f32_16x16x32_bf16 v[40:43], v[182:185], v[190:193], v[40:43]
	v_mfma_f32_16x16x32_bf16 v[36:39], v[160:163], v[198:201], v[36:39]
	v_mfma_f32_16x16x32_bf16 v[32:35], v[182:185], v[198:201], v[32:35]
	v_mfma_f32_16x16x32_bf16 v[16:19], v[160:163], v[206:209], v[16:19]
	v_mfma_f32_16x16x32_bf16 v[8:11], v[182:185], v[206:209], v[8:11]
	v_mfma_f32_16x16x32_bf16 v[4:7], v[160:163], v[214:217], v[4:7]
	v_mfma_f32_16x16x32_bf16 v[0:3], v[182:185], v[214:217], v[0:3]
	v_mfma_f32_16x16x32_bf16 v[44:47], v[164:167], v[194:197], v[44:47]
	v_mfma_f32_16x16x32_bf16 v[40:43], v[186:189], v[194:197], v[40:43]
	v_mfma_f32_16x16x32_bf16 v[36:39], v[164:167], v[202:205], v[36:39]
	v_mfma_f32_16x16x32_bf16 v[32:35], v[186:189], v[202:205], v[32:35]
	v_mfma_f32_16x16x32_bf16 v[16:19], v[164:167], v[210:213], v[16:19]
	v_mfma_f32_16x16x32_bf16 v[8:11], v[186:189], v[210:213], v[8:11]
	v_mfma_f32_16x16x32_bf16 v[4:7], v[164:167], v[218:221], v[4:7]
	v_mfma_f32_16x16x32_bf16 v[0:3], v[186:189], v[218:221], v[0:3]
	s_setprio 0
	s_add_i32 s64, s64, 2
	s_add_u32 s62, s62, 0x10000
	s_addc_u32 s63, s63, 0
	s_add_u32 s30, s30, 0x10000
	s_addc_u32 s31, s31, 0
	s_cmp_gt_u32 s64, 41
	s_cbranch_scc0 .Lrot15
	s_barrier
	s_and_b64 vcc, exec, s[14:15]
	s_cbranch_vccz .LBB0_2522
	s_barrier
